# v16 + every individually-neutral bit-identical edit stacked: 3 gate loads hoisted, MLA loads before tile barrier, attention packed-fp32 split, GEMM ds_read-first, setprio 0 behind the post-MFMA barrie
# speedup vs baseline: 1.0073x; 1.0047x over previous
.LBB0_849:
	ds_read_b128 v[146:149], v155
	ds_read_b128 v[160:163], v155 offset:1024
	ds_read_b128 v[164:167], v155 offset:2048
	ds_read_b128 v[168:171], v155 offset:3072
	ds_read_b128 v[172:175], v156
	ds_read_b128 v[176:179], v156 offset:1024
	ds_read_b128 v[180:183], v156 offset:2048
	ds_read_b128 v[184:187], v156 offset:3072
	ds_read_b128 v[188:191], v157
	ds_read_b128 v[192:195], v157 offset:1024
	ds_read_b128 v[196:199], v157 offset:2048
	ds_read_b128 v[200:203], v157 offset:3072
	ds_read_b128 v[204:207], v157 offset:4096
	ds_read_b128 v[208:211], v157 offset:5120
	ds_read_b128 v[212:215], v157 offset:6144
	ds_read_b128 v[216:219], v157 offset:7168
	s_add_u32 s74, s72, 0xfff80080
	s_addc_u32 s75, s73, -1
	s_cmp_eq_u32 s85, 28
	s_cselect_b32 s77, s63, s75
	s_cselect_b32 s76, s69, s74
	s_cselect_b32 s75, s57, s84
	s_cselect_b32 s74, s71, s83
	v_lshl_add_u64 v[220:221], s[72:73], 0, v[138:139]
	s_add_i32 m0, s3, 0xc000
	s_nop 0
	global_load_lds_dwordx4 v[220:221], off
	v_lshl_add_u64 v[220:221], s[72:73], 0, v[140:141]
	s_add_i32 m0, s3, 0xe000
	s_nop 0
	global_load_lds_dwordx4 v[220:221], off
	s_waitcnt vmcnt(8)
	s_waitcnt lgkmcnt(0)
	s_barrier
	s_setprio 1
	s_waitcnt lgkmcnt(0)
	v_mfma_f32_16x16x32_bf16 v[124:127], v[146:149], v[188:191], v[124:127]
	v_mfma_f32_16x16x32_bf16 v[120:123], v[164:167], v[188:191], v[120:123]
	v_mfma_f32_16x16x32_bf16 v[108:111], v[146:149], v[196:199], v[108:111]
	v_mfma_f32_16x16x32_bf16 v[104:107], v[164:167], v[196:199], v[104:107]
	v_mfma_f32_16x16x32_bf16 v[92:95], v[146:149], v[204:207], v[92:95]
	v_mfma_f32_16x16x32_bf16 v[88:91], v[164:167], v[204:207], v[88:91]
	v_mfma_f32_16x16x32_bf16 v[76:79], v[146:149], v[212:215], v[76:79]
	v_mfma_f32_16x16x32_bf16 v[72:75], v[164:167], v[212:215], v[72:75]
	v_mfma_f32_16x16x32_bf16 v[124:127], v[160:163], v[192:195], v[124:127]
	v_mfma_f32_16x16x32_bf16 v[120:123], v[168:171], v[192:195], v[120:123]
	v_mfma_f32_16x16x32_bf16 v[108:111], v[160:163], v[200:203], v[108:111]
	v_mfma_f32_16x16x32_bf16 v[104:107], v[168:171], v[200:203], v[104:107]
	v_mfma_f32_16x16x32_bf16 v[92:95], v[160:163], v[208:211], v[92:95]
	v_mfma_f32_16x16x32_bf16 v[88:91], v[168:171], v[208:211], v[88:91]
	v_mfma_f32_16x16x32_bf16 v[76:79], v[160:163], v[216:219], v[76:79]
	v_mfma_f32_16x16x32_bf16 v[72:75], v[168:171], v[216:219], v[72:75]
	v_mfma_f32_16x16x32_bf16 v[116:119], v[172:175], v[188:191], v[116:119]
	v_mfma_f32_16x16x32_bf16 v[112:115], v[180:183], v[188:191], v[112:115]
	v_mfma_f32_16x16x32_bf16 v[100:103], v[172:175], v[196:199], v[100:103]
	v_mfma_f32_16x16x32_bf16 v[96:99], v[180:183], v[196:199], v[96:99]
	v_mfma_f32_16x16x32_bf16 v[84:87], v[172:175], v[204:207], v[84:87]
	v_mfma_f32_16x16x32_bf16 v[80:83], v[180:183], v[204:207], v[80:83]
	v_mfma_f32_16x16x32_bf16 v[68:71], v[172:175], v[212:215], v[68:71]
	v_mfma_f32_16x16x32_bf16 v[64:67], v[180:183], v[212:215], v[64:67]
	v_mfma_f32_16x16x32_bf16 v[116:119], v[176:179], v[192:195], v[116:119]
	v_mfma_f32_16x16x32_bf16 v[112:115], v[184:187], v[192:195], v[112:115]
	v_mfma_f32_16x16x32_bf16 v[100:103], v[176:179], v[200:203], v[100:103]
	v_mfma_f32_16x16x32_bf16 v[96:99], v[184:187], v[200:203], v[96:99]
	v_mfma_f32_16x16x32_bf16 v[84:87], v[176:179], v[208:211], v[84:87]
	v_mfma_f32_16x16x32_bf16 v[80:83], v[184:187], v[208:211], v[80:83]
	v_mfma_f32_16x16x32_bf16 v[68:71], v[176:179], v[216:219], v[68:71]
	v_mfma_f32_16x16x32_bf16 v[64:67], v[184:187], v[216:219], v[64:67]
	s_barrier
	s_setprio 0
	ds_read_b128 v[188:191], v157 offset:16384
	ds_read_b128 v[192:195], v157 offset:17408
	ds_read_b128 v[196:199], v157 offset:18432
	ds_read_b128 v[200:203], v157 offset:19456
	ds_read_b128 v[204:207], v157 offset:20480
	ds_read_b128 v[208:211], v157 offset:21504
	ds_read_b128 v[212:215], v157 offset:22528
	ds_read_b128 v[216:219], v157 offset:23552
	s_add_i32 s86, s79, s94
	v_lshl_add_u64 v[220:221], s[74:75], 0, v[130:131]
	s_mov_b32 m0, s86
	s_nop 0
	global_load_lds_dwordx4 v[220:221], off
	s_add_i32 m0, s86, 0x2000
	s_add_u32 s86, s74, 0x80000
	v_lshl_add_u64 v[222:223], s[74:75], 0, v[134:135]
	s_addc_u32 s87, s75, 0
	s_add_i32 s88, s81, s94
	global_load_lds_dwordx4 v[222:223], off
	v_lshl_add_u64 v[224:225], s[86:87], 0, v[130:131]
	s_mov_b32 m0, s88
	v_lshl_add_u64 v[226:227], s[76:77], 0, v[132:133]
	global_load_lds_dwordx4 v[224:225], off
	v_lshl_add_u64 v[224:225], s[86:87], 0, v[134:135]
	s_add_i32 m0, s88, 0x2000
	s_nop 0
	global_load_lds_dwordx4 v[224:225], off
	v_lshl_add_u64 v[224:225], s[76:77], 0, v[128:129]
	s_mov_b32 m0, s3
	s_nop 0
	global_load_lds_dwordx4 v[224:225], off
	s_mov_b32 m0, s6
	s_nop 0
	global_load_lds_dwordx4 v[226:227], off
	s_waitcnt vmcnt(8)
	s_waitcnt lgkmcnt(0)
	s_barrier
	s_setprio 1
	s_waitcnt lgkmcnt(0)
	v_mfma_f32_16x16x32_bf16 v[60:63], v[146:149], v[188:191], v[60:63]
	v_mfma_f32_16x16x32_bf16 v[56:59], v[164:167], v[188:191], v[56:59]
	v_mfma_f32_16x16x32_bf16 v[44:47], v[146:149], v[196:199], v[44:47]
	v_mfma_f32_16x16x32_bf16 v[40:43], v[164:167], v[196:199], v[40:43]
	v_mfma_f32_16x16x32_bf16 v[28:31], v[146:149], v[204:207], v[28:31]
	v_mfma_f32_16x16x32_bf16 v[24:27], v[164:167], v[204:207], v[24:27]
	v_mfma_f32_16x16x32_bf16 v[12:15], v[146:149], v[212:215], v[12:15]
	v_mfma_f32_16x16x32_bf16 v[8:11], v[164:167], v[212:215], v[8:11]
	v_mfma_f32_16x16x32_bf16 v[60:63], v[160:163], v[192:195], v[60:63]
	v_mfma_f32_16x16x32_bf16 v[56:59], v[168:171], v[192:195], v[56:59]
	v_mfma_f32_16x16x32_bf16 v[44:47], v[160:163], v[200:203], v[44:47]
	v_mfma_f32_16x16x32_bf16 v[40:43], v[168:171], v[200:203], v[40:43]
	v_mfma_f32_16x16x32_bf16 v[28:31], v[160:163], v[208:211], v[28:31]
	v_mfma_f32_16x16x32_bf16 v[24:27], v[168:171], v[208:211], v[24:27]
	v_mfma_f32_16x16x32_bf16 v[12:15], v[160:163], v[216:219], v[12:15]
	v_mfma_f32_16x16x32_bf16 v[8:11], v[168:171], v[216:219], v[8:11]
	v_mfma_f32_16x16x32_bf16 v[52:55], v[172:175], v[188:191], v[52:55]
	v_mfma_f32_16x16x32_bf16 v[48:51], v[180:183], v[188:191], v[48:51]
	v_mfma_f32_16x16x32_bf16 v[36:39], v[172:175], v[196:199], v[36:39]
	v_mfma_f32_16x16x32_bf16 v[32:35], v[180:183], v[196:199], v[32:35]
	v_mfma_f32_16x16x32_bf16 v[20:23], v[172:175], v[204:207], v[20:23]
	v_mfma_f32_16x16x32_bf16 v[16:19], v[180:183], v[204:207], v[16:19]
	v_mfma_f32_16x16x32_bf16 v[4:7], v[172:175], v[212:215], v[4:7]
	v_mfma_f32_16x16x32_bf16 v[0:3], v[180:183], v[212:215], v[0:3]
	v_mfma_f32_16x16x32_bf16 v[52:55], v[176:179], v[192:195], v[52:55]
	v_mfma_f32_16x16x32_bf16 v[48:51], v[184:187], v[192:195], v[48:51]
	v_mfma_f32_16x16x32_bf16 v[36:39], v[176:179], v[200:203], v[36:39]
	v_mfma_f32_16x16x32_bf16 v[32:35], v[184:187], v[200:203], v[32:35]
	v_mfma_f32_16x16x32_bf16 v[20:23], v[176:179], v[208:211], v[20:23]
	v_mfma_f32_16x16x32_bf16 v[16:19], v[184:187], v[208:211], v[16:19]
	v_mfma_f32_16x16x32_bf16 v[4:7], v[176:179], v[216:219], v[4:7]
	v_mfma_f32_16x16x32_bf16 v[0:3], v[184:187], v[216:219], v[0:3]
	s_barrier
	s_setprio 0
	s_add_i32 s86, 0, 0x18000
	v_add_u32_e32 v159, s86, v151
	ds_read_b128 v[146:149], v159
	ds_read_b128 v[160:163], v159 offset:1024
	ds_read_b128 v[164:167], v159 offset:2048
	ds_read_b128 v[168:171], v159 offset:3072
	s_add_i32 s87, 0, 0x1c000
	v_add_u32_e32 v159, s87, v151
	ds_read_b128 v[172:175], v159
	ds_read_b128 v[176:179], v159 offset:1024
	ds_read_b128 v[180:183], v159 offset:2048
	ds_read_b128 v[184:187], v159 offset:3072
	ds_read_b128 v[188:191], v157 offset:32768
	ds_read_b128 v[192:195], v157 offset:33792
	ds_read_b128 v[196:199], v157 offset:34816
	ds_read_b128 v[200:203], v157 offset:35840
	ds_read_b128 v[204:207], v157 offset:36864
	ds_read_b128 v[208:211], v157 offset:37888
	ds_read_b128 v[212:215], v157 offset:38912
	ds_read_b128 v[216:219], v157 offset:39936
	s_add_u32 s76, s76, 0x80000
	s_addc_u32 s77, s77, 0
	s_mov_b32 m0, s7
	v_lshl_add_u64 v[228:229], s[76:77], 0, v[128:129]
	global_load_lds_dwordx4 v[228:229], off
	v_lshl_add_u64 v[228:229], s[76:77], 0, v[132:133]
	s_mov_b32 m0, s29
	s_nop 0
	global_load_lds_dwordx4 v[228:229], off
	s_waitcnt vmcnt(8)
	s_waitcnt lgkmcnt(0)
	s_barrier
	s_setprio 1
	s_waitcnt lgkmcnt(0)
	v_mfma_f32_16x16x32_bf16 v[124:127], v[146:149], v[188:191], v[124:127]
	v_mfma_f32_16x16x32_bf16 v[120:123], v[164:167], v[188:191], v[120:123]
	v_mfma_f32_16x16x32_bf16 v[108:111], v[146:149], v[196:199], v[108:111]
	v_mfma_f32_16x16x32_bf16 v[104:107], v[164:167], v[196:199], v[104:107]
	v_mfma_f32_16x16x32_bf16 v[92:95], v[146:149], v[204:207], v[92:95]
	v_mfma_f32_16x16x32_bf16 v[88:91], v[164:167], v[204:207], v[88:91]
	v_mfma_f32_16x16x32_bf16 v[76:79], v[146:149], v[212:215], v[76:79]
	v_mfma_f32_16x16x32_bf16 v[72:75], v[164:167], v[212:215], v[72:75]
	v_mfma_f32_16x16x32_bf16 v[124:127], v[160:163], v[192:195], v[124:127]
	v_mfma_f32_16x16x32_bf16 v[120:123], v[168:171], v[192:195], v[120:123]
	v_mfma_f32_16x16x32_bf16 v[108:111], v[160:163], v[200:203], v[108:111]
	v_mfma_f32_16x16x32_bf16 v[104:107], v[168:171], v[200:203], v[104:107]
	v_mfma_f32_16x16x32_bf16 v[92:95], v[160:163], v[208:211], v[92:95]
	v_mfma_f32_16x16x32_bf16 v[88:91], v[168:171], v[208:211], v[88:91]
	v_mfma_f32_16x16x32_bf16 v[76:79], v[160:163], v[216:219], v[76:79]
	v_mfma_f32_16x16x32_bf16 v[72:75], v[168:171], v[216:219], v[72:75]
	v_mfma_f32_16x16x32_bf16 v[116:119], v[172:175], v[188:191], v[116:119]
	v_mfma_f32_16x16x32_bf16 v[112:115], v[180:183], v[188:191], v[112:115]
	v_mfma_f32_16x16x32_bf16 v[100:103], v[172:175], v[196:199], v[100:103]
	v_mfma_f32_16x16x32_bf16 v[96:99], v[180:183], v[196:199], v[96:99]
	v_mfma_f32_16x16x32_bf16 v[84:87], v[172:175], v[204:207], v[84:87]
	v_mfma_f32_16x16x32_bf16 v[80:83], v[180:183], v[204:207], v[80:83]
	v_mfma_f32_16x16x32_bf16 v[68:71], v[172:175], v[212:215], v[68:71]
	v_mfma_f32_16x16x32_bf16 v[64:67], v[180:183], v[212:215], v[64:67]
	v_mfma_f32_16x16x32_bf16 v[116:119], v[176:179], v[192:195], v[116:119]
	v_mfma_f32_16x16x32_bf16 v[112:115], v[184:187], v[192:195], v[112:115]
	v_mfma_f32_16x16x32_bf16 v[100:103], v[176:179], v[200:203], v[100:103]
	v_mfma_f32_16x16x32_bf16 v[96:99], v[184:187], v[200:203], v[96:99]
	v_mfma_f32_16x16x32_bf16 v[84:87], v[176:179], v[208:211], v[84:87]
	v_mfma_f32_16x16x32_bf16 v[80:83], v[184:187], v[208:211], v[80:83]
	v_mfma_f32_16x16x32_bf16 v[68:71], v[176:179], v[216:219], v[68:71]
	v_mfma_f32_16x16x32_bf16 v[64:67], v[184:187], v[216:219], v[64:67]
	s_barrier
	s_setprio 0
	ds_read_b128 v[188:191], v157 offset:49152
	ds_read_b128 v[192:195], v157 offset:50176
	ds_read_b128 v[196:199], v157 offset:51200
	ds_read_b128 v[200:203], v157 offset:52224
	ds_read_b128 v[204:207], v157 offset:53248
	ds_read_b128 v[208:211], v157 offset:54272
	ds_read_b128 v[212:215], v157 offset:55296
	ds_read_b128 v[216:219], v157 offset:56320
	s_add_i32 s76, s86, s94
	v_lshl_add_u64 v[220:221], v[220:221], 0, s[18:19]
	s_mov_b32 m0, s76
	s_nop 0
	global_load_lds_dwordx4 v[220:221], off
	s_add_i32 m0, s76, 0x2000
	s_add_u32 s74, s74, 0x80080
	v_lshl_add_u64 v[220:221], v[222:223], 0, s[18:19]
	s_addc_u32 s75, s75, 0
	s_add_i32 s76, s87, s94
	global_load_lds_dwordx4 v[220:221], off
	v_lshl_add_u64 v[220:221], s[74:75], 0, v[130:131]
	s_mov_b32 m0, s76
	s_nop 0
	global_load_lds_dwordx4 v[220:221], off
	v_lshl_add_u64 v[220:221], s[74:75], 0, v[134:135]
	s_add_i32 m0, s76, 0x2000
	s_nop 0
	global_load_lds_dwordx4 v[220:221], off
	v_lshl_add_u64 v[220:221], v[224:225], 0, s[18:19]
	s_mov_b32 m0, s34
	s_nop 0
	global_load_lds_dwordx4 v[220:221], off
	v_lshl_add_u64 v[220:221], v[226:227], 0, s[18:19]
	s_mov_b32 m0, s35
	s_nop 0
	global_load_lds_dwordx4 v[220:221], off
	s_waitcnt vmcnt(8)
	s_waitcnt lgkmcnt(0)
	s_barrier
	s_setprio 1
	s_waitcnt lgkmcnt(0)
	v_mfma_f32_16x16x32_bf16 v[60:63], v[146:149], v[188:191], v[60:63]
	v_mfma_f32_16x16x32_bf16 v[56:59], v[164:167], v[188:191], v[56:59]
	v_mfma_f32_16x16x32_bf16 v[44:47], v[146:149], v[196:199], v[44:47]
	v_mfma_f32_16x16x32_bf16 v[40:43], v[164:167], v[196:199], v[40:43]
	v_mfma_f32_16x16x32_bf16 v[28:31], v[146:149], v[204:207], v[28:31]
	v_mfma_f32_16x16x32_bf16 v[24:27], v[164:167], v[204:207], v[24:27]
	v_mfma_f32_16x16x32_bf16 v[12:15], v[146:149], v[212:215], v[12:15]
	v_mfma_f32_16x16x32_bf16 v[8:11], v[164:167], v[212:215], v[8:11]
	v_mfma_f32_16x16x32_bf16 v[60:63], v[160:163], v[192:195], v[60:63]
	v_mfma_f32_16x16x32_bf16 v[56:59], v[168:171], v[192:195], v[56:59]
	v_mfma_f32_16x16x32_bf16 v[44:47], v[160:163], v[200:203], v[44:47]
	v_mfma_f32_16x16x32_bf16 v[40:43], v[168:171], v[200:203], v[40:43]
	v_mfma_f32_16x16x32_bf16 v[28:31], v[160:163], v[208:211], v[28:31]
	v_mfma_f32_16x16x32_bf16 v[24:27], v[168:171], v[208:211], v[24:27]
	v_mfma_f32_16x16x32_bf16 v[12:15], v[160:163], v[216:219], v[12:15]
	v_mfma_f32_16x16x32_bf16 v[8:11], v[168:171], v[216:219], v[8:11]
	v_mfma_f32_16x16x32_bf16 v[52:55], v[172:175], v[188:191], v[52:55]
	v_mfma_f32_16x16x32_bf16 v[48:51], v[180:183], v[188:191], v[48:51]
	v_mfma_f32_16x16x32_bf16 v[36:39], v[172:175], v[196:199], v[36:39]
	v_mfma_f32_16x16x32_bf16 v[32:35], v[180:183], v[196:199], v[32:35]
	v_mfma_f32_16x16x32_bf16 v[20:23], v[172:175], v[204:207], v[20:23]
	v_mfma_f32_16x16x32_bf16 v[16:19], v[180:183], v[204:207], v[16:19]
	v_mfma_f32_16x16x32_bf16 v[4:7], v[172:175], v[212:215], v[4:7]
	v_mfma_f32_16x16x32_bf16 v[0:3], v[180:183], v[212:215], v[0:3]
	v_mfma_f32_16x16x32_bf16 v[52:55], v[176:179], v[192:195], v[52:55]
	v_mfma_f32_16x16x32_bf16 v[48:51], v[184:187], v[192:195], v[48:51]
	v_mfma_f32_16x16x32_bf16 v[36:39], v[176:179], v[200:203], v[36:39]
	v_mfma_f32_16x16x32_bf16 v[32:35], v[184:187], v[200:203], v[32:35]
	v_mfma_f32_16x16x32_bf16 v[20:23], v[176:179], v[208:211], v[20:23]
	v_mfma_f32_16x16x32_bf16 v[16:19], v[184:187], v[208:211], v[16:19]
	v_mfma_f32_16x16x32_bf16 v[4:7], v[176:179], v[216:219], v[4:7]
	v_mfma_f32_16x16x32_bf16 v[0:3], v[184:187], v[216:219], v[0:3]
	s_barrier
	s_setprio 0
	s_add_i32 s85, s85, 2
	s_add_u32 s72, s72, 0x100
	s_addc_u32 s73, s73, 0
	s_add_u32 s83, s83, 0x100
	s_addc_u32 s84, s84, 0
	s_cmp_gt_u32 s85, 29
	s_cbranch_scc0 .LBB0_849
	s_and_b64 vcc, exec, s[20:21]
	s_cbranch_vccz .LBB0_852
	s_barrier

.LBB0_946:
	ds_read_b128 v[148:151], v143
	ds_read_b128 v[152:155], v143 offset:1024
	ds_read_b128 v[156:159], v143 offset:2048
	ds_read_b128 v[160:163], v143 offset:3072
	ds_read_b128 v[164:167], v144
	ds_read_b128 v[168:171], v144 offset:1024
	ds_read_b128 v[172:175], v144 offset:2048
	ds_read_b128 v[176:179], v144 offset:3072
	ds_read_b128 v[180:183], v145
	ds_read_b128 v[184:187], v145 offset:1024
	ds_read_b128 v[188:191], v145 offset:2048
	ds_read_b128 v[192:195], v145 offset:3072
	ds_read_b128 v[196:199], v145 offset:4096
	ds_read_b128 v[200:203], v145 offset:5120
	ds_read_b128 v[204:207], v145 offset:6144
	ds_read_b128 v[208:211], v145 offset:7168
	s_add_u32 s18, s14, s16
	s_addc_u32 s19, s15, s17
	s_add_u32 s18, s18, 0x7498100
	s_addc_u32 s19, s19, 0
	s_add_u32 s20, s24, s16
	s_addc_u32 s21, s25, s17
	s_add_u32 s69, s20, 0x1308100
	s_addc_u32 s70, s21, 0
	s_cmpk_eq_i32 s16, 0xf00
	s_cselect_b32 s21, s11, s19
	s_cselect_b32 s20, s10, s18
	s_cselect_b32 s19, s9, s70
	s_cselect_b32 s18, s8, s69
	s_mov_b32 m0, s46
	v_lshl_add_u64 v[212:213], v[136:137], 0, s[16:17]
	global_load_lds_dwordx4 v[212:213], off
	v_lshl_add_u64 v[212:213], v[138:139], 0, s[16:17]
	s_mov_b32 m0, s56
	s_nop 0
	global_load_lds_dwordx4 v[212:213], off
	s_waitcnt vmcnt(8)
	s_waitcnt lgkmcnt(0)
	s_barrier
	s_setprio 1
	s_waitcnt lgkmcnt(0)
	v_mfma_f32_16x16x32_bf16 v[124:127], v[148:151], v[180:183], v[124:127]
	v_mfma_f32_16x16x32_bf16 v[120:123], v[156:159], v[180:183], v[120:123]
	v_mfma_f32_16x16x32_bf16 v[108:111], v[148:151], v[188:191], v[108:111]
	v_mfma_f32_16x16x32_bf16 v[104:107], v[156:159], v[188:191], v[104:107]
	v_mfma_f32_16x16x32_bf16 v[92:95], v[148:151], v[196:199], v[92:95]
	v_mfma_f32_16x16x32_bf16 v[88:91], v[156:159], v[196:199], v[88:91]
	v_mfma_f32_16x16x32_bf16 v[76:79], v[148:151], v[204:207], v[76:79]
	v_mfma_f32_16x16x32_bf16 v[72:75], v[156:159], v[204:207], v[72:75]
	v_mfma_f32_16x16x32_bf16 v[124:127], v[152:155], v[184:187], v[124:127]
	v_mfma_f32_16x16x32_bf16 v[120:123], v[160:163], v[184:187], v[120:123]
	v_mfma_f32_16x16x32_bf16 v[108:111], v[152:155], v[192:195], v[108:111]
	v_mfma_f32_16x16x32_bf16 v[104:107], v[160:163], v[192:195], v[104:107]
	v_mfma_f32_16x16x32_bf16 v[92:95], v[152:155], v[200:203], v[92:95]
	v_mfma_f32_16x16x32_bf16 v[88:91], v[160:163], v[200:203], v[88:91]
	v_mfma_f32_16x16x32_bf16 v[76:79], v[152:155], v[208:211], v[76:79]
	v_mfma_f32_16x16x32_bf16 v[72:75], v[160:163], v[208:211], v[72:75]
	v_mfma_f32_16x16x32_bf16 v[116:119], v[164:167], v[180:183], v[116:119]
	v_mfma_f32_16x16x32_bf16 v[112:115], v[172:175], v[180:183], v[112:115]
	v_mfma_f32_16x16x32_bf16 v[100:103], v[164:167], v[188:191], v[100:103]
	v_mfma_f32_16x16x32_bf16 v[96:99], v[172:175], v[188:191], v[96:99]
	v_mfma_f32_16x16x32_bf16 v[84:87], v[164:167], v[196:199], v[84:87]
	v_mfma_f32_16x16x32_bf16 v[80:83], v[172:175], v[196:199], v[80:83]
	v_mfma_f32_16x16x32_bf16 v[68:71], v[164:167], v[204:207], v[68:71]
	v_mfma_f32_16x16x32_bf16 v[64:67], v[172:175], v[204:207], v[64:67]
	v_mfma_f32_16x16x32_bf16 v[116:119], v[168:171], v[184:187], v[116:119]
	v_mfma_f32_16x16x32_bf16 v[112:115], v[176:179], v[184:187], v[112:115]
	v_mfma_f32_16x16x32_bf16 v[100:103], v[168:171], v[192:195], v[100:103]
	v_mfma_f32_16x16x32_bf16 v[96:99], v[176:179], v[192:195], v[96:99]
	v_mfma_f32_16x16x32_bf16 v[84:87], v[168:171], v[200:203], v[84:87]
	v_mfma_f32_16x16x32_bf16 v[80:83], v[176:179], v[200:203], v[80:83]
	v_mfma_f32_16x16x32_bf16 v[68:71], v[168:171], v[208:211], v[68:71]
	v_mfma_f32_16x16x32_bf16 v[64:67], v[176:179], v[208:211], v[64:67]
	s_barrier
	s_setprio 0
	ds_read_b128 v[180:183], v145 offset:16384
	ds_read_b128 v[184:187], v145 offset:17408
	ds_read_b128 v[188:191], v145 offset:18432
	ds_read_b128 v[192:195], v145 offset:19456
	ds_read_b128 v[196:199], v145 offset:20480
	ds_read_b128 v[200:203], v145 offset:21504
	ds_read_b128 v[204:207], v145 offset:22528
	ds_read_b128 v[208:211], v145 offset:23552
	s_mov_b32 m0, s57
	v_lshl_add_u64 v[212:213], s[18:19], 0, v[132:133]
	s_add_u32 s70, s18, 0x80000
	global_load_lds_dwordx4 v[212:213], off
	v_lshl_add_u64 v[214:215], s[18:19], 0, v[128:129]
	s_mov_b32 m0, s62
	s_addc_u32 s71, s19, 0
	global_load_lds_dwordx4 v[214:215], off
	v_lshl_add_u64 v[216:217], s[70:71], 0, v[132:133]
	s_mov_b32 m0, s63
	v_lshl_add_u64 v[218:219], s[20:21], 0, v[130:131]
	global_load_lds_dwordx4 v[216:217], off
	v_lshl_add_u64 v[216:217], s[70:71], 0, v[128:129]
	s_mov_b32 m0, s64
	s_nop 0
	global_load_lds_dwordx4 v[216:217], off
	v_lshl_add_u64 v[216:217], s[20:21], 0, v[134:135]
	s_mov_b32 m0, s3
	s_nop 0
	global_load_lds_dwordx4 v[216:217], off
	s_mov_b32 m0, s6
	s_nop 0
	global_load_lds_dwordx4 v[218:219], off
	s_waitcnt vmcnt(8)
	s_waitcnt lgkmcnt(0)
	s_barrier
	s_setprio 1
	s_waitcnt lgkmcnt(0)
	v_mfma_f32_16x16x32_bf16 v[60:63], v[148:151], v[180:183], v[60:63]
	v_mfma_f32_16x16x32_bf16 v[56:59], v[156:159], v[180:183], v[56:59]
	v_mfma_f32_16x16x32_bf16 v[44:47], v[148:151], v[188:191], v[44:47]
	v_mfma_f32_16x16x32_bf16 v[40:43], v[156:159], v[188:191], v[40:43]
	v_mfma_f32_16x16x32_bf16 v[28:31], v[148:151], v[196:199], v[28:31]
	v_mfma_f32_16x16x32_bf16 v[24:27], v[156:159], v[196:199], v[24:27]
	v_mfma_f32_16x16x32_bf16 v[12:15], v[148:151], v[204:207], v[12:15]
	v_mfma_f32_16x16x32_bf16 v[8:11], v[156:159], v[204:207], v[8:11]
	v_mfma_f32_16x16x32_bf16 v[60:63], v[152:155], v[184:187], v[60:63]
	v_mfma_f32_16x16x32_bf16 v[56:59], v[160:163], v[184:187], v[56:59]
	v_mfma_f32_16x16x32_bf16 v[44:47], v[152:155], v[192:195], v[44:47]
	v_mfma_f32_16x16x32_bf16 v[40:43], v[160:163], v[192:195], v[40:43]
	v_mfma_f32_16x16x32_bf16 v[28:31], v[152:155], v[200:203], v[28:31]
	v_mfma_f32_16x16x32_bf16 v[24:27], v[160:163], v[200:203], v[24:27]
	v_mfma_f32_16x16x32_bf16 v[12:15], v[152:155], v[208:211], v[12:15]
	v_mfma_f32_16x16x32_bf16 v[8:11], v[160:163], v[208:211], v[8:11]
	v_mfma_f32_16x16x32_bf16 v[52:55], v[164:167], v[180:183], v[52:55]
	v_mfma_f32_16x16x32_bf16 v[48:51], v[172:175], v[180:183], v[48:51]
	v_mfma_f32_16x16x32_bf16 v[36:39], v[164:167], v[188:191], v[36:39]
	v_mfma_f32_16x16x32_bf16 v[32:35], v[172:175], v[188:191], v[32:35]
	v_mfma_f32_16x16x32_bf16 v[20:23], v[164:167], v[196:199], v[20:23]
	v_mfma_f32_16x16x32_bf16 v[16:19], v[172:175], v[196:199], v[16:19]
	v_mfma_f32_16x16x32_bf16 v[4:7], v[164:167], v[204:207], v[4:7]
	v_mfma_f32_16x16x32_bf16 v[0:3], v[172:175], v[204:207], v[0:3]
	v_mfma_f32_16x16x32_bf16 v[52:55], v[168:171], v[184:187], v[52:55]
	v_mfma_f32_16x16x32_bf16 v[48:51], v[176:179], v[184:187], v[48:51]
	v_mfma_f32_16x16x32_bf16 v[36:39], v[168:171], v[192:195], v[36:39]
	v_mfma_f32_16x16x32_bf16 v[32:35], v[176:179], v[192:195], v[32:35]
	v_mfma_f32_16x16x32_bf16 v[20:23], v[168:171], v[200:203], v[20:23]
	v_mfma_f32_16x16x32_bf16 v[16:19], v[176:179], v[200:203], v[16:19]
	v_mfma_f32_16x16x32_bf16 v[4:7], v[168:171], v[208:211], v[4:7]
	v_mfma_f32_16x16x32_bf16 v[0:3], v[176:179], v[208:211], v[0:3]
	s_barrier
	s_setprio 0
	ds_read_b128 v[148:151], v146
	ds_read_b128 v[152:155], v146 offset:1024
	ds_read_b128 v[156:159], v146 offset:2048
	ds_read_b128 v[160:163], v146 offset:3072
	ds_read_b128 v[164:167], v147
	ds_read_b128 v[168:171], v147 offset:1024
	ds_read_b128 v[172:175], v147 offset:2048
	ds_read_b128 v[176:179], v147 offset:3072
	ds_read_b128 v[180:183], v145 offset:32768
	ds_read_b128 v[184:187], v145 offset:33792
	ds_read_b128 v[188:191], v145 offset:34816
	ds_read_b128 v[192:195], v145 offset:35840
	ds_read_b128 v[196:199], v145 offset:36864
	ds_read_b128 v[200:203], v145 offset:37888
	ds_read_b128 v[204:207], v145 offset:38912
	ds_read_b128 v[208:211], v145 offset:39936
	s_add_u32 s20, s20, 0x80000
	s_addc_u32 s21, s21, 0
	s_mov_b32 m0, s7
	v_lshl_add_u64 v[220:221], s[20:21], 0, v[134:135]
	global_load_lds_dwordx4 v[220:221], off
	v_lshl_add_u64 v[220:221], s[20:21], 0, v[130:131]
	s_mov_b32 m0, s29
	s_nop 0
	global_load_lds_dwordx4 v[220:221], off
	s_waitcnt vmcnt(8)
	s_waitcnt lgkmcnt(0)
	s_barrier
	s_setprio 1
	s_waitcnt lgkmcnt(0)
	v_mfma_f32_16x16x32_bf16 v[124:127], v[148:151], v[180:183], v[124:127]
	v_mfma_f32_16x16x32_bf16 v[120:123], v[156:159], v[180:183], v[120:123]
	v_mfma_f32_16x16x32_bf16 v[108:111], v[148:151], v[188:191], v[108:111]
	v_mfma_f32_16x16x32_bf16 v[104:107], v[156:159], v[188:191], v[104:107]
	v_mfma_f32_16x16x32_bf16 v[92:95], v[148:151], v[196:199], v[92:95]
	v_mfma_f32_16x16x32_bf16 v[88:91], v[156:159], v[196:199], v[88:91]
	v_mfma_f32_16x16x32_bf16 v[76:79], v[148:151], v[204:207], v[76:79]
	v_mfma_f32_16x16x32_bf16 v[72:75], v[156:159], v[204:207], v[72:75]
	v_mfma_f32_16x16x32_bf16 v[124:127], v[152:155], v[184:187], v[124:127]
	v_mfma_f32_16x16x32_bf16 v[120:123], v[160:163], v[184:187], v[120:123]
	v_mfma_f32_16x16x32_bf16 v[108:111], v[152:155], v[192:195], v[108:111]
	v_mfma_f32_16x16x32_bf16 v[104:107], v[160:163], v[192:195], v[104:107]
	v_mfma_f32_16x16x32_bf16 v[92:95], v[152:155], v[200:203], v[92:95]
	v_mfma_f32_16x16x32_bf16 v[88:91], v[160:163], v[200:203], v[88:91]
	v_mfma_f32_16x16x32_bf16 v[76:79], v[152:155], v[208:211], v[76:79]
	v_mfma_f32_16x16x32_bf16 v[72:75], v[160:163], v[208:211], v[72:75]
	v_mfma_f32_16x16x32_bf16 v[116:119], v[164:167], v[180:183], v[116:119]
	v_mfma_f32_16x16x32_bf16 v[112:115], v[172:175], v[180:183], v[112:115]
	v_mfma_f32_16x16x32_bf16 v[100:103], v[164:167], v[188:191], v[100:103]
	v_mfma_f32_16x16x32_bf16 v[96:99], v[172:175], v[188:191], v[96:99]
	v_mfma_f32_16x16x32_bf16 v[84:87], v[164:167], v[196:199], v[84:87]
	v_mfma_f32_16x16x32_bf16 v[80:83], v[172:175], v[196:199], v[80:83]
	v_mfma_f32_16x16x32_bf16 v[68:71], v[164:167], v[204:207], v[68:71]
	v_mfma_f32_16x16x32_bf16 v[64:67], v[172:175], v[204:207], v[64:67]
	v_mfma_f32_16x16x32_bf16 v[116:119], v[168:171], v[184:187], v[116:119]
	v_mfma_f32_16x16x32_bf16 v[112:115], v[176:179], v[184:187], v[112:115]
	v_mfma_f32_16x16x32_bf16 v[100:103], v[168:171], v[192:195], v[100:103]
	v_mfma_f32_16x16x32_bf16 v[96:99], v[176:179], v[192:195], v[96:99]
	v_mfma_f32_16x16x32_bf16 v[84:87], v[168:171], v[200:203], v[84:87]
	v_mfma_f32_16x16x32_bf16 v[80:83], v[176:179], v[200:203], v[80:83]
	v_mfma_f32_16x16x32_bf16 v[68:71], v[168:171], v[208:211], v[68:71]
	v_mfma_f32_16x16x32_bf16 v[64:67], v[176:179], v[208:211], v[64:67]
	s_barrier
	s_setprio 0
	ds_read_b128 v[180:183], v145 offset:49152
	ds_read_b128 v[184:187], v145 offset:50176
	ds_read_b128 v[188:191], v145 offset:51200
	ds_read_b128 v[192:195], v145 offset:52224
	ds_read_b128 v[196:199], v145 offset:53248
	ds_read_b128 v[200:203], v145 offset:54272
	ds_read_b128 v[204:207], v145 offset:55296
	ds_read_b128 v[208:211], v145 offset:56320
	s_mov_b32 m0, s65
	v_lshl_add_u64 v[212:213], v[212:213], 0, s[12:13]
	s_add_u32 s18, s18, 0x80080
	global_load_lds_dwordx4 v[212:213], off
	v_lshl_add_u64 v[212:213], v[214:215], 0, s[12:13]
	s_mov_b32 m0, s66
	s_addc_u32 s19, s19, 0
	global_load_lds_dwordx4 v[212:213], off
	v_lshl_add_u64 v[212:213], s[18:19], 0, v[132:133]
	s_mov_b32 m0, s67
	s_nop 0
	global_load_lds_dwordx4 v[212:213], off
	v_lshl_add_u64 v[212:213], s[18:19], 0, v[128:129]
	s_mov_b32 m0, s68
	s_nop 0
	global_load_lds_dwordx4 v[212:213], off
	v_lshl_add_u64 v[212:213], v[216:217], 0, s[12:13]
	s_mov_b32 m0, s30
	s_nop 0
	global_load_lds_dwordx4 v[212:213], off
	v_lshl_add_u64 v[212:213], v[218:219], 0, s[12:13]
	s_mov_b32 m0, s34
	s_nop 0
	global_load_lds_dwordx4 v[212:213], off
	s_waitcnt vmcnt(8)
	s_waitcnt lgkmcnt(0)
	s_barrier
	s_setprio 1
	s_waitcnt lgkmcnt(0)
	v_mfma_f32_16x16x32_bf16 v[60:63], v[148:151], v[180:183], v[60:63]
	v_mfma_f32_16x16x32_bf16 v[56:59], v[156:159], v[180:183], v[56:59]
	v_mfma_f32_16x16x32_bf16 v[44:47], v[148:151], v[188:191], v[44:47]
	v_mfma_f32_16x16x32_bf16 v[40:43], v[156:159], v[188:191], v[40:43]
	v_mfma_f32_16x16x32_bf16 v[28:31], v[148:151], v[196:199], v[28:31]
	v_mfma_f32_16x16x32_bf16 v[24:27], v[156:159], v[196:199], v[24:27]
	v_mfma_f32_16x16x32_bf16 v[12:15], v[148:151], v[204:207], v[12:15]
	v_mfma_f32_16x16x32_bf16 v[8:11], v[156:159], v[204:207], v[8:11]
	v_mfma_f32_16x16x32_bf16 v[60:63], v[152:155], v[184:187], v[60:63]
	v_mfma_f32_16x16x32_bf16 v[56:59], v[160:163], v[184:187], v[56:59]
	v_mfma_f32_16x16x32_bf16 v[44:47], v[152:155], v[192:195], v[44:47]
	v_mfma_f32_16x16x32_bf16 v[40:43], v[160:163], v[192:195], v[40:43]
	v_mfma_f32_16x16x32_bf16 v[28:31], v[152:155], v[200:203], v[28:31]
	v_mfma_f32_16x16x32_bf16 v[24:27], v[160:163], v[200:203], v[24:27]
	v_mfma_f32_16x16x32_bf16 v[12:15], v[152:155], v[208:211], v[12:15]
	v_mfma_f32_16x16x32_bf16 v[8:11], v[160:163], v[208:211], v[8:11]
	v_mfma_f32_16x16x32_bf16 v[52:55], v[164:167], v[180:183], v[52:55]
	v_mfma_f32_16x16x32_bf16 v[48:51], v[172:175], v[180:183], v[48:51]
	v_mfma_f32_16x16x32_bf16 v[36:39], v[164:167], v[188:191], v[36:39]
	v_mfma_f32_16x16x32_bf16 v[32:35], v[172:175], v[188:191], v[32:35]
	v_mfma_f32_16x16x32_bf16 v[20:23], v[164:167], v[196:199], v[20:23]
	v_mfma_f32_16x16x32_bf16 v[16:19], v[172:175], v[196:199], v[16:19]
	v_mfma_f32_16x16x32_bf16 v[4:7], v[164:167], v[204:207], v[4:7]
	v_mfma_f32_16x16x32_bf16 v[0:3], v[172:175], v[204:207], v[0:3]
	v_mfma_f32_16x16x32_bf16 v[52:55], v[168:171], v[184:187], v[52:55]
	v_mfma_f32_16x16x32_bf16 v[48:51], v[176:179], v[184:187], v[48:51]
	v_mfma_f32_16x16x32_bf16 v[36:39], v[168:171], v[192:195], v[36:39]
	v_mfma_f32_16x16x32_bf16 v[32:35], v[176:179], v[192:195], v[32:35]
	v_mfma_f32_16x16x32_bf16 v[20:23], v[168:171], v[200:203], v[20:23]
	v_mfma_f32_16x16x32_bf16 v[16:19], v[176:179], v[200:203], v[16:19]
	v_mfma_f32_16x16x32_bf16 v[4:7], v[168:171], v[208:211], v[4:7]
	v_mfma_f32_16x16x32_bf16 v[0:3], v[176:179], v[208:211], v[0:3]
	s_barrier
	s_setprio 0
	s_add_i32 s35, s35, 2
	s_add_u32 s16, s16, 0x100
	s_addc_u32 s17, s17, 0
	s_cmp_gt_u32 s35, 29
	s_cbranch_scc0 .LBB0_946
	s_cmpk_lt_u32 s80, 0x100
	s_cbranch_scc0 .LBB0_949
	s_barrier

.LBB0_1693:
	ds_read_b128 v[140:143], v149
	ds_read_b128 v[152:155], v149 offset:1024
	ds_read_b128 v[156:159], v149 offset:2048
	ds_read_b128 v[160:163], v149 offset:3072
	ds_read_b128 v[164:167], v150
	ds_read_b128 v[168:171], v150 offset:1024
	ds_read_b128 v[172:175], v150 offset:2048
	ds_read_b128 v[176:179], v150 offset:3072
	ds_read_b128 v[180:183], v151
	ds_read_b128 v[184:187], v151 offset:1024
	ds_read_b128 v[188:191], v151 offset:2048
	ds_read_b128 v[192:195], v151 offset:3072
	ds_read_b128 v[196:199], v151 offset:4096
	ds_read_b128 v[200:203], v151 offset:5120
	ds_read_b128 v[204:207], v151 offset:6144
	ds_read_b128 v[208:211], v151 offset:7168
	s_add_u32 s76, s74, 0xfff80080
	s_addc_u32 s77, s75, -1
	s_cmp_eq_u32 s86, 28
	s_cselect_b32 s79, s67, s77
	s_cselect_b32 s78, s73, s76
	s_cselect_b32 s77, s65, s85
	s_cselect_b32 s76, s83, s84
	v_lshl_add_u64 v[212:213], s[74:75], 0, v[132:133]
	s_add_i32 m0, s6, 0xc000
	s_nop 0
	global_load_lds_dwordx4 v[212:213], off
	v_lshl_add_u64 v[212:213], s[74:75], 0, v[134:135]
	s_add_i32 m0, s6, 0xe000
	s_nop 0
	global_load_lds_dwordx4 v[212:213], off
	s_waitcnt vmcnt(8)
	s_waitcnt lgkmcnt(0)
	s_barrier
	s_setprio 1
	s_waitcnt lgkmcnt(0)
	v_mfma_f32_16x16x32_bf16 v[124:127], v[140:143], v[180:183], v[124:127]
	v_mfma_f32_16x16x32_bf16 v[120:123], v[156:159], v[180:183], v[120:123]
	v_mfma_f32_16x16x32_bf16 v[108:111], v[140:143], v[188:191], v[108:111]
	v_mfma_f32_16x16x32_bf16 v[104:107], v[156:159], v[188:191], v[104:107]
	v_mfma_f32_16x16x32_bf16 v[92:95], v[140:143], v[196:199], v[92:95]
	v_mfma_f32_16x16x32_bf16 v[88:91], v[156:159], v[196:199], v[88:91]
	v_mfma_f32_16x16x32_bf16 v[76:79], v[140:143], v[204:207], v[76:79]
	v_mfma_f32_16x16x32_bf16 v[72:75], v[156:159], v[204:207], v[72:75]
	v_mfma_f32_16x16x32_bf16 v[124:127], v[152:155], v[184:187], v[124:127]
	v_mfma_f32_16x16x32_bf16 v[120:123], v[160:163], v[184:187], v[120:123]
	v_mfma_f32_16x16x32_bf16 v[108:111], v[152:155], v[192:195], v[108:111]
	v_mfma_f32_16x16x32_bf16 v[104:107], v[160:163], v[192:195], v[104:107]
	v_mfma_f32_16x16x32_bf16 v[92:95], v[152:155], v[200:203], v[92:95]
	v_mfma_f32_16x16x32_bf16 v[88:91], v[160:163], v[200:203], v[88:91]
	v_mfma_f32_16x16x32_bf16 v[76:79], v[152:155], v[208:211], v[76:79]
	v_mfma_f32_16x16x32_bf16 v[72:75], v[160:163], v[208:211], v[72:75]
	v_mfma_f32_16x16x32_bf16 v[116:119], v[164:167], v[180:183], v[116:119]
	v_mfma_f32_16x16x32_bf16 v[112:115], v[172:175], v[180:183], v[112:115]
	v_mfma_f32_16x16x32_bf16 v[100:103], v[164:167], v[188:191], v[100:103]
	v_mfma_f32_16x16x32_bf16 v[96:99], v[172:175], v[188:191], v[96:99]
	v_mfma_f32_16x16x32_bf16 v[84:87], v[164:167], v[196:199], v[84:87]
	v_mfma_f32_16x16x32_bf16 v[80:83], v[172:175], v[196:199], v[80:83]
	v_mfma_f32_16x16x32_bf16 v[68:71], v[164:167], v[204:207], v[68:71]
	v_mfma_f32_16x16x32_bf16 v[64:67], v[172:175], v[204:207], v[64:67]
	v_mfma_f32_16x16x32_bf16 v[116:119], v[168:171], v[184:187], v[116:119]
	v_mfma_f32_16x16x32_bf16 v[112:115], v[176:179], v[184:187], v[112:115]
	v_mfma_f32_16x16x32_bf16 v[100:103], v[168:171], v[192:195], v[100:103]
	v_mfma_f32_16x16x32_bf16 v[96:99], v[176:179], v[192:195], v[96:99]
	v_mfma_f32_16x16x32_bf16 v[84:87], v[168:171], v[200:203], v[84:87]
	v_mfma_f32_16x16x32_bf16 v[80:83], v[176:179], v[200:203], v[80:83]
	v_mfma_f32_16x16x32_bf16 v[68:71], v[168:171], v[208:211], v[68:71]
	v_mfma_f32_16x16x32_bf16 v[64:67], v[176:179], v[208:211], v[64:67]
	s_barrier
	s_setprio 0
	ds_read_b128 v[180:183], v151 offset:16384
	ds_read_b128 v[184:187], v151 offset:17408
	ds_read_b128 v[188:191], v151 offset:18432
	ds_read_b128 v[192:195], v151 offset:19456
	ds_read_b128 v[196:199], v151 offset:20480
	ds_read_b128 v[200:203], v151 offset:21504
	ds_read_b128 v[204:207], v151 offset:22528
	ds_read_b128 v[208:211], v151 offset:23552
	s_add_i32 s87, s57, s94
	v_lshl_add_u64 v[212:213], s[76:77], 0, v[128:129]
	s_mov_b32 m0, s87
	s_nop 0
	global_load_lds_dwordx4 v[212:213], off
	s_add_i32 m0, s87, 0x2000
	s_add_u32 s88, s76, 0x80000
	v_lshl_add_u64 v[214:215], s[76:77], 0, v[130:131]
	s_addc_u32 s89, s77, 0
	s_add_i32 s87, s81, s94
	global_load_lds_dwordx4 v[214:215], off
	v_lshl_add_u64 v[216:217], s[88:89], 0, v[128:129]
	s_mov_b32 m0, s87
	v_lshl_add_u64 v[218:219], s[78:79], 0, v[130:131]
	global_load_lds_dwordx4 v[216:217], off
	v_lshl_add_u64 v[216:217], s[88:89], 0, v[130:131]
	s_add_i32 m0, s87, 0x2000
	s_nop 0
	global_load_lds_dwordx4 v[216:217], off
	v_lshl_add_u64 v[216:217], s[78:79], 0, v[128:129]
	s_mov_b32 m0, s6
	s_nop 0
	global_load_lds_dwordx4 v[216:217], off
	s_mov_b32 m0, s7
	s_nop 0
	global_load_lds_dwordx4 v[218:219], off
	s_waitcnt vmcnt(8)
	s_waitcnt lgkmcnt(0)
	s_barrier
	s_setprio 1
	s_waitcnt lgkmcnt(0)
	v_mfma_f32_16x16x32_bf16 v[60:63], v[140:143], v[180:183], v[60:63]
	v_mfma_f32_16x16x32_bf16 v[56:59], v[156:159], v[180:183], v[56:59]
	v_mfma_f32_16x16x32_bf16 v[44:47], v[140:143], v[188:191], v[44:47]
	v_mfma_f32_16x16x32_bf16 v[40:43], v[156:159], v[188:191], v[40:43]
	v_mfma_f32_16x16x32_bf16 v[28:31], v[140:143], v[196:199], v[28:31]
	v_mfma_f32_16x16x32_bf16 v[24:27], v[156:159], v[196:199], v[24:27]
	v_mfma_f32_16x16x32_bf16 v[12:15], v[140:143], v[204:207], v[12:15]
	v_mfma_f32_16x16x32_bf16 v[8:11], v[156:159], v[204:207], v[8:11]
	v_mfma_f32_16x16x32_bf16 v[60:63], v[152:155], v[184:187], v[60:63]
	v_mfma_f32_16x16x32_bf16 v[56:59], v[160:163], v[184:187], v[56:59]
	v_mfma_f32_16x16x32_bf16 v[44:47], v[152:155], v[192:195], v[44:47]
	v_mfma_f32_16x16x32_bf16 v[40:43], v[160:163], v[192:195], v[40:43]
	v_mfma_f32_16x16x32_bf16 v[28:31], v[152:155], v[200:203], v[28:31]
	v_mfma_f32_16x16x32_bf16 v[24:27], v[160:163], v[200:203], v[24:27]
	v_mfma_f32_16x16x32_bf16 v[12:15], v[152:155], v[208:211], v[12:15]
	v_mfma_f32_16x16x32_bf16 v[8:11], v[160:163], v[208:211], v[8:11]
	v_mfma_f32_16x16x32_bf16 v[52:55], v[164:167], v[180:183], v[52:55]
	v_mfma_f32_16x16x32_bf16 v[48:51], v[172:175], v[180:183], v[48:51]
	v_mfma_f32_16x16x32_bf16 v[36:39], v[164:167], v[188:191], v[36:39]
	v_mfma_f32_16x16x32_bf16 v[32:35], v[172:175], v[188:191], v[32:35]
	v_mfma_f32_16x16x32_bf16 v[20:23], v[164:167], v[196:199], v[20:23]
	v_mfma_f32_16x16x32_bf16 v[16:19], v[172:175], v[196:199], v[16:19]
	v_mfma_f32_16x16x32_bf16 v[4:7], v[164:167], v[204:207], v[4:7]
	v_mfma_f32_16x16x32_bf16 v[0:3], v[172:175], v[204:207], v[0:3]
	v_mfma_f32_16x16x32_bf16 v[52:55], v[168:171], v[184:187], v[52:55]
	v_mfma_f32_16x16x32_bf16 v[48:51], v[176:179], v[184:187], v[48:51]
	v_mfma_f32_16x16x32_bf16 v[36:39], v[168:171], v[192:195], v[36:39]
	v_mfma_f32_16x16x32_bf16 v[32:35], v[176:179], v[192:195], v[32:35]
	v_mfma_f32_16x16x32_bf16 v[20:23], v[168:171], v[200:203], v[20:23]
	v_mfma_f32_16x16x32_bf16 v[16:19], v[176:179], v[200:203], v[16:19]
	v_mfma_f32_16x16x32_bf16 v[4:7], v[168:171], v[208:211], v[4:7]
	v_mfma_f32_16x16x32_bf16 v[0:3], v[176:179], v[208:211], v[0:3]
	s_barrier
	s_setprio 0
	s_add_i32 s87, 0, 0x18000
	s_add_i32 s88, 0, 0x1c000
	v_add_u32_e32 v160, s87, v145
	ds_read_b128 v[140:143], v160
	ds_read_b128 v[152:155], v160 offset:1024
	ds_read_b128 v[156:159], v160 offset:2048
	ds_read_b128 v[160:163], v160 offset:3072
	v_add_u32_e32 v176, s88, v145
	ds_read_b128 v[164:167], v176
	ds_read_b128 v[168:171], v176 offset:1024
	ds_read_b128 v[172:175], v176 offset:2048
	ds_read_b128 v[176:179], v176 offset:3072
	ds_read_b128 v[180:183], v151 offset:32768
	ds_read_b128 v[184:187], v151 offset:33792
	ds_read_b128 v[188:191], v151 offset:34816
	ds_read_b128 v[192:195], v151 offset:35840
	ds_read_b128 v[196:199], v151 offset:36864
	ds_read_b128 v[200:203], v151 offset:37888
	ds_read_b128 v[204:207], v151 offset:38912
	ds_read_b128 v[208:211], v151 offset:39936
	s_add_u32 s78, s78, 0x80000
	s_addc_u32 s79, s79, 0
	s_mov_b32 m0, s29
	v_lshl_add_u64 v[220:221], s[78:79], 0, v[128:129]
	global_load_lds_dwordx4 v[220:221], off
	v_lshl_add_u64 v[220:221], s[78:79], 0, v[130:131]
	s_mov_b32 m0, s30
	s_nop 0
	global_load_lds_dwordx4 v[220:221], off
	s_waitcnt vmcnt(8)
	s_waitcnt lgkmcnt(0)
	s_barrier
	s_setprio 1
	s_waitcnt lgkmcnt(0)
	v_mfma_f32_16x16x32_bf16 v[124:127], v[140:143], v[180:183], v[124:127]
	v_mfma_f32_16x16x32_bf16 v[120:123], v[156:159], v[180:183], v[120:123]
	v_mfma_f32_16x16x32_bf16 v[108:111], v[140:143], v[188:191], v[108:111]
	v_mfma_f32_16x16x32_bf16 v[104:107], v[156:159], v[188:191], v[104:107]
	v_mfma_f32_16x16x32_bf16 v[92:95], v[140:143], v[196:199], v[92:95]
	v_mfma_f32_16x16x32_bf16 v[88:91], v[156:159], v[196:199], v[88:91]
	v_mfma_f32_16x16x32_bf16 v[76:79], v[140:143], v[204:207], v[76:79]
	v_mfma_f32_16x16x32_bf16 v[72:75], v[156:159], v[204:207], v[72:75]
	v_mfma_f32_16x16x32_bf16 v[124:127], v[152:155], v[184:187], v[124:127]
	v_mfma_f32_16x16x32_bf16 v[120:123], v[160:163], v[184:187], v[120:123]
	v_mfma_f32_16x16x32_bf16 v[108:111], v[152:155], v[192:195], v[108:111]
	v_mfma_f32_16x16x32_bf16 v[104:107], v[160:163], v[192:195], v[104:107]
	v_mfma_f32_16x16x32_bf16 v[92:95], v[152:155], v[200:203], v[92:95]
	v_mfma_f32_16x16x32_bf16 v[88:91], v[160:163], v[200:203], v[88:91]
	v_mfma_f32_16x16x32_bf16 v[76:79], v[152:155], v[208:211], v[76:79]
	v_mfma_f32_16x16x32_bf16 v[72:75], v[160:163], v[208:211], v[72:75]
	v_mfma_f32_16x16x32_bf16 v[116:119], v[164:167], v[180:183], v[116:119]
	v_mfma_f32_16x16x32_bf16 v[112:115], v[172:175], v[180:183], v[112:115]
	v_mfma_f32_16x16x32_bf16 v[100:103], v[164:167], v[188:191], v[100:103]
	v_mfma_f32_16x16x32_bf16 v[96:99], v[172:175], v[188:191], v[96:99]
	v_mfma_f32_16x16x32_bf16 v[84:87], v[164:167], v[196:199], v[84:87]
	v_mfma_f32_16x16x32_bf16 v[80:83], v[172:175], v[196:199], v[80:83]
	v_mfma_f32_16x16x32_bf16 v[68:71], v[164:167], v[204:207], v[68:71]
	v_mfma_f32_16x16x32_bf16 v[64:67], v[172:175], v[204:207], v[64:67]
	v_mfma_f32_16x16x32_bf16 v[116:119], v[168:171], v[184:187], v[116:119]
	v_mfma_f32_16x16x32_bf16 v[112:115], v[176:179], v[184:187], v[112:115]
	v_mfma_f32_16x16x32_bf16 v[100:103], v[168:171], v[192:195], v[100:103]
	v_mfma_f32_16x16x32_bf16 v[96:99], v[176:179], v[192:195], v[96:99]
	v_mfma_f32_16x16x32_bf16 v[84:87], v[168:171], v[200:203], v[84:87]
	v_mfma_f32_16x16x32_bf16 v[80:83], v[176:179], v[200:203], v[80:83]
	v_mfma_f32_16x16x32_bf16 v[68:71], v[168:171], v[208:211], v[68:71]
	v_mfma_f32_16x16x32_bf16 v[64:67], v[176:179], v[208:211], v[64:67]
	s_barrier
	s_setprio 0
	ds_read_b128 v[180:183], v151 offset:49152
	ds_read_b128 v[184:187], v151 offset:50176
	ds_read_b128 v[188:191], v151 offset:51200
	ds_read_b128 v[192:195], v151 offset:52224
	ds_read_b128 v[196:199], v151 offset:53248
	ds_read_b128 v[200:203], v151 offset:54272
	ds_read_b128 v[204:207], v151 offset:55296
	ds_read_b128 v[208:211], v151 offset:56320
	s_add_i32 s78, s87, s94
	v_lshl_add_u64 v[212:213], v[212:213], 0, s[58:59]
	s_mov_b32 m0, s78
	s_nop 0
	global_load_lds_dwordx4 v[212:213], off
	s_add_i32 m0, s78, 0x2000
	s_add_u32 s76, s76, 0x80080
	v_lshl_add_u64 v[212:213], v[214:215], 0, s[58:59]
	s_addc_u32 s77, s77, 0
	s_add_i32 s78, s88, s94
	global_load_lds_dwordx4 v[212:213], off
	v_lshl_add_u64 v[212:213], s[76:77], 0, v[128:129]
	s_mov_b32 m0, s78
	s_nop 0
	global_load_lds_dwordx4 v[212:213], off
	v_lshl_add_u64 v[212:213], s[76:77], 0, v[130:131]
	s_add_i32 m0, s78, 0x2000
	s_nop 0
	global_load_lds_dwordx4 v[212:213], off
	v_lshl_add_u64 v[212:213], v[216:217], 0, s[58:59]
	s_mov_b32 m0, s34
	s_nop 0
	global_load_lds_dwordx4 v[212:213], off
	v_lshl_add_u64 v[212:213], v[218:219], 0, s[58:59]
	s_mov_b32 m0, s35
	s_nop 0
	global_load_lds_dwordx4 v[212:213], off
	s_waitcnt vmcnt(8)
	s_waitcnt lgkmcnt(0)
	s_barrier
	s_setprio 1
	s_waitcnt lgkmcnt(0)
	v_mfma_f32_16x16x32_bf16 v[60:63], v[140:143], v[180:183], v[60:63]
	v_mfma_f32_16x16x32_bf16 v[56:59], v[156:159], v[180:183], v[56:59]
	v_mfma_f32_16x16x32_bf16 v[44:47], v[140:143], v[188:191], v[44:47]
	v_mfma_f32_16x16x32_bf16 v[40:43], v[156:159], v[188:191], v[40:43]
	v_mfma_f32_16x16x32_bf16 v[28:31], v[140:143], v[196:199], v[28:31]
	v_mfma_f32_16x16x32_bf16 v[24:27], v[156:159], v[196:199], v[24:27]
	v_mfma_f32_16x16x32_bf16 v[12:15], v[140:143], v[204:207], v[12:15]
	v_mfma_f32_16x16x32_bf16 v[8:11], v[156:159], v[204:207], v[8:11]
	v_mfma_f32_16x16x32_bf16 v[60:63], v[152:155], v[184:187], v[60:63]
	v_mfma_f32_16x16x32_bf16 v[56:59], v[160:163], v[184:187], v[56:59]
	v_mfma_f32_16x16x32_bf16 v[44:47], v[152:155], v[192:195], v[44:47]
	v_mfma_f32_16x16x32_bf16 v[40:43], v[160:163], v[192:195], v[40:43]
	v_mfma_f32_16x16x32_bf16 v[28:31], v[152:155], v[200:203], v[28:31]
	v_mfma_f32_16x16x32_bf16 v[24:27], v[160:163], v[200:203], v[24:27]
	v_mfma_f32_16x16x32_bf16 v[12:15], v[152:155], v[208:211], v[12:15]
	v_mfma_f32_16x16x32_bf16 v[8:11], v[160:163], v[208:211], v[8:11]
	v_mfma_f32_16x16x32_bf16 v[52:55], v[164:167], v[180:183], v[52:55]
	v_mfma_f32_16x16x32_bf16 v[48:51], v[172:175], v[180:183], v[48:51]
	v_mfma_f32_16x16x32_bf16 v[36:39], v[164:167], v[188:191], v[36:39]
	v_mfma_f32_16x16x32_bf16 v[32:35], v[172:175], v[188:191], v[32:35]
	v_mfma_f32_16x16x32_bf16 v[20:23], v[164:167], v[196:199], v[20:23]
	v_mfma_f32_16x16x32_bf16 v[16:19], v[172:175], v[196:199], v[16:19]
	v_mfma_f32_16x16x32_bf16 v[4:7], v[164:167], v[204:207], v[4:7]
	v_mfma_f32_16x16x32_bf16 v[0:3], v[172:175], v[204:207], v[0:3]
	v_mfma_f32_16x16x32_bf16 v[52:55], v[168:171], v[184:187], v[52:55]
	v_mfma_f32_16x16x32_bf16 v[48:51], v[176:179], v[184:187], v[48:51]
	v_mfma_f32_16x16x32_bf16 v[36:39], v[168:171], v[192:195], v[36:39]
	v_mfma_f32_16x16x32_bf16 v[32:35], v[176:179], v[192:195], v[32:35]
	v_mfma_f32_16x16x32_bf16 v[20:23], v[168:171], v[200:203], v[20:23]
	v_mfma_f32_16x16x32_bf16 v[16:19], v[176:179], v[200:203], v[16:19]
	v_mfma_f32_16x16x32_bf16 v[4:7], v[168:171], v[208:211], v[4:7]
	v_mfma_f32_16x16x32_bf16 v[0:3], v[176:179], v[208:211], v[0:3]
	s_barrier
	s_setprio 0
	s_add_i32 s86, s86, 2
	s_add_u32 s74, s74, 0x100
	s_addc_u32 s75, s75, 0
	s_add_u32 s84, s84, 0x100
	s_addc_u32 s85, s85, 0
	s_cmp_gt_u32 s86, 29
	s_cbranch_scc0 .LBB0_1693
	s_and_b64 vcc, exec, s[60:61]
	s_cbranch_vccz .LBB0_1696
	s_barrier

.LBB0_1785:
	ds_read_b128 v[146:149], v155
	ds_read_b128 v[160:163], v155 offset:1024
	ds_read_b128 v[164:167], v155 offset:2048
	ds_read_b128 v[168:171], v155 offset:3072
	ds_read_b128 v[172:175], v156
	ds_read_b128 v[176:179], v156 offset:1024
	ds_read_b128 v[180:183], v156 offset:2048
	ds_read_b128 v[184:187], v156 offset:3072
	ds_read_b128 v[188:191], v157
	ds_read_b128 v[192:195], v157 offset:1024
	ds_read_b128 v[196:199], v157 offset:2048
	ds_read_b128 v[200:203], v157 offset:3072
	ds_read_b128 v[204:207], v157 offset:4096
	ds_read_b128 v[208:211], v157 offset:5120
	ds_read_b128 v[212:215], v157 offset:6144
	ds_read_b128 v[216:219], v157 offset:7168
	s_add_u32 s60, s72, 0xfff80080
	s_addc_u32 s61, s73, -1
	s_cmp_eq_u32 s78, 28
	s_cselect_b32 s77, s56, s61
	s_cselect_b32 s76, s57, s60
	s_cselect_b32 s75, s23, s71
	s_cselect_b32 s74, s63, s69
	v_lshl_add_u64 v[220:221], s[72:73], 0, v[138:139]
	s_add_i32 m0, s6, 0xc000
	s_nop 0
	global_load_lds_dwordx4 v[220:221], off
	v_lshl_add_u64 v[220:221], s[72:73], 0, v[140:141]
	s_add_i32 m0, s6, 0xe000
	s_nop 0
	global_load_lds_dwordx4 v[220:221], off
	s_waitcnt vmcnt(8)
	s_waitcnt lgkmcnt(0)
	s_barrier
	s_setprio 1
	s_waitcnt lgkmcnt(0)
	v_mfma_f32_16x16x32_bf16 v[124:127], v[146:149], v[188:191], v[124:127]
	v_mfma_f32_16x16x32_bf16 v[120:123], v[164:167], v[188:191], v[120:123]
	v_mfma_f32_16x16x32_bf16 v[108:111], v[146:149], v[196:199], v[108:111]
	v_mfma_f32_16x16x32_bf16 v[104:107], v[164:167], v[196:199], v[104:107]
	v_mfma_f32_16x16x32_bf16 v[92:95], v[146:149], v[204:207], v[92:95]
	v_mfma_f32_16x16x32_bf16 v[88:91], v[164:167], v[204:207], v[88:91]
	v_mfma_f32_16x16x32_bf16 v[76:79], v[146:149], v[212:215], v[76:79]
	v_mfma_f32_16x16x32_bf16 v[72:75], v[164:167], v[212:215], v[72:75]
	v_mfma_f32_16x16x32_bf16 v[124:127], v[160:163], v[192:195], v[124:127]
	v_mfma_f32_16x16x32_bf16 v[120:123], v[168:171], v[192:195], v[120:123]
	v_mfma_f32_16x16x32_bf16 v[108:111], v[160:163], v[200:203], v[108:111]
	v_mfma_f32_16x16x32_bf16 v[104:107], v[168:171], v[200:203], v[104:107]
	v_mfma_f32_16x16x32_bf16 v[92:95], v[160:163], v[208:211], v[92:95]
	v_mfma_f32_16x16x32_bf16 v[88:91], v[168:171], v[208:211], v[88:91]
	v_mfma_f32_16x16x32_bf16 v[76:79], v[160:163], v[216:219], v[76:79]
	v_mfma_f32_16x16x32_bf16 v[72:75], v[168:171], v[216:219], v[72:75]
	v_mfma_f32_16x16x32_bf16 v[116:119], v[172:175], v[188:191], v[116:119]
	v_mfma_f32_16x16x32_bf16 v[112:115], v[180:183], v[188:191], v[112:115]
	v_mfma_f32_16x16x32_bf16 v[100:103], v[172:175], v[196:199], v[100:103]
	v_mfma_f32_16x16x32_bf16 v[96:99], v[180:183], v[196:199], v[96:99]
	v_mfma_f32_16x16x32_bf16 v[84:87], v[172:175], v[204:207], v[84:87]
	v_mfma_f32_16x16x32_bf16 v[80:83], v[180:183], v[204:207], v[80:83]
	v_mfma_f32_16x16x32_bf16 v[68:71], v[172:175], v[212:215], v[68:71]
	v_mfma_f32_16x16x32_bf16 v[64:67], v[180:183], v[212:215], v[64:67]
	v_mfma_f32_16x16x32_bf16 v[116:119], v[176:179], v[192:195], v[116:119]
	v_mfma_f32_16x16x32_bf16 v[112:115], v[184:187], v[192:195], v[112:115]
	v_mfma_f32_16x16x32_bf16 v[100:103], v[176:179], v[200:203], v[100:103]
	v_mfma_f32_16x16x32_bf16 v[96:99], v[184:187], v[200:203], v[96:99]
	v_mfma_f32_16x16x32_bf16 v[84:87], v[176:179], v[208:211], v[84:87]
	v_mfma_f32_16x16x32_bf16 v[80:83], v[184:187], v[208:211], v[80:83]
	v_mfma_f32_16x16x32_bf16 v[68:71], v[176:179], v[216:219], v[68:71]
	v_mfma_f32_16x16x32_bf16 v[64:67], v[184:187], v[216:219], v[64:67]
	s_barrier
	s_setprio 0
	ds_read_b128 v[188:191], v157 offset:16384
	ds_read_b128 v[192:195], v157 offset:17408
	ds_read_b128 v[196:199], v157 offset:18432
	ds_read_b128 v[200:203], v157 offset:19456
	ds_read_b128 v[204:207], v157 offset:20480
	ds_read_b128 v[208:211], v157 offset:21504
	ds_read_b128 v[212:215], v157 offset:22528
	ds_read_b128 v[216:219], v157 offset:23552
	s_add_i32 s60, s35, s94
	v_lshl_add_u64 v[220:221], s[74:75], 0, v[130:131]
	s_mov_b32 m0, s60
	s_nop 0
	global_load_lds_dwordx4 v[220:221], off
	s_add_i32 m0, s60, 0x2000
	s_add_u32 s80, s74, 0x80000
	v_lshl_add_u64 v[222:223], s[74:75], 0, v[134:135]
	s_addc_u32 s81, s75, 0
	s_add_i32 s60, s46, s94
	global_load_lds_dwordx4 v[222:223], off
	v_lshl_add_u64 v[224:225], s[80:81], 0, v[130:131]
	s_mov_b32 m0, s60
	v_lshl_add_u64 v[226:227], s[76:77], 0, v[132:133]
	global_load_lds_dwordx4 v[224:225], off
	v_lshl_add_u64 v[224:225], s[80:81], 0, v[134:135]
	s_add_i32 m0, s60, 0x2000
	s_nop 0
	global_load_lds_dwordx4 v[224:225], off
	v_lshl_add_u64 v[224:225], s[76:77], 0, v[128:129]
	s_mov_b32 m0, s6
	s_nop 0
	global_load_lds_dwordx4 v[224:225], off
	s_mov_b32 m0, s7
	s_nop 0
	global_load_lds_dwordx4 v[226:227], off
	s_waitcnt vmcnt(8)
	s_waitcnt lgkmcnt(0)
	s_barrier
	s_setprio 1
	s_waitcnt lgkmcnt(0)
	v_mfma_f32_16x16x32_bf16 v[60:63], v[146:149], v[188:191], v[60:63]
	v_mfma_f32_16x16x32_bf16 v[56:59], v[164:167], v[188:191], v[56:59]
	v_mfma_f32_16x16x32_bf16 v[44:47], v[146:149], v[196:199], v[44:47]
	v_mfma_f32_16x16x32_bf16 v[40:43], v[164:167], v[196:199], v[40:43]
	v_mfma_f32_16x16x32_bf16 v[28:31], v[146:149], v[204:207], v[28:31]
	v_mfma_f32_16x16x32_bf16 v[24:27], v[164:167], v[204:207], v[24:27]
	v_mfma_f32_16x16x32_bf16 v[12:15], v[146:149], v[212:215], v[12:15]
	v_mfma_f32_16x16x32_bf16 v[8:11], v[164:167], v[212:215], v[8:11]
	v_mfma_f32_16x16x32_bf16 v[60:63], v[160:163], v[192:195], v[60:63]
	v_mfma_f32_16x16x32_bf16 v[56:59], v[168:171], v[192:195], v[56:59]
	v_mfma_f32_16x16x32_bf16 v[44:47], v[160:163], v[200:203], v[44:47]
	v_mfma_f32_16x16x32_bf16 v[40:43], v[168:171], v[200:203], v[40:43]
	v_mfma_f32_16x16x32_bf16 v[28:31], v[160:163], v[208:211], v[28:31]
	v_mfma_f32_16x16x32_bf16 v[24:27], v[168:171], v[208:211], v[24:27]
	v_mfma_f32_16x16x32_bf16 v[12:15], v[160:163], v[216:219], v[12:15]
	v_mfma_f32_16x16x32_bf16 v[8:11], v[168:171], v[216:219], v[8:11]
	v_mfma_f32_16x16x32_bf16 v[52:55], v[172:175], v[188:191], v[52:55]
	v_mfma_f32_16x16x32_bf16 v[48:51], v[180:183], v[188:191], v[48:51]
	v_mfma_f32_16x16x32_bf16 v[36:39], v[172:175], v[196:199], v[36:39]
	v_mfma_f32_16x16x32_bf16 v[32:35], v[180:183], v[196:199], v[32:35]
	v_mfma_f32_16x16x32_bf16 v[20:23], v[172:175], v[204:207], v[20:23]
	v_mfma_f32_16x16x32_bf16 v[16:19], v[180:183], v[204:207], v[16:19]
	v_mfma_f32_16x16x32_bf16 v[4:7], v[172:175], v[212:215], v[4:7]
	v_mfma_f32_16x16x32_bf16 v[0:3], v[180:183], v[212:215], v[0:3]
	v_mfma_f32_16x16x32_bf16 v[52:55], v[176:179], v[192:195], v[52:55]
	v_mfma_f32_16x16x32_bf16 v[48:51], v[184:187], v[192:195], v[48:51]
	v_mfma_f32_16x16x32_bf16 v[36:39], v[176:179], v[200:203], v[36:39]
	v_mfma_f32_16x16x32_bf16 v[32:35], v[184:187], v[200:203], v[32:35]
	v_mfma_f32_16x16x32_bf16 v[20:23], v[176:179], v[208:211], v[20:23]
	v_mfma_f32_16x16x32_bf16 v[16:19], v[184:187], v[208:211], v[16:19]
	v_mfma_f32_16x16x32_bf16 v[4:7], v[176:179], v[216:219], v[4:7]
	v_mfma_f32_16x16x32_bf16 v[0:3], v[184:187], v[216:219], v[0:3]
	s_barrier
	s_setprio 0
	s_add_i32 s60, 0, 0x18000
	v_add_u32_e32 v159, s60, v151
	ds_read_b128 v[146:149], v159
	ds_read_b128 v[160:163], v159 offset:1024
	ds_read_b128 v[164:167], v159 offset:2048
	ds_read_b128 v[168:171], v159 offset:3072
	s_add_i32 s61, 0, 0x1c000
	v_add_u32_e32 v159, s61, v151
	ds_read_b128 v[172:175], v159
	ds_read_b128 v[176:179], v159 offset:1024
	ds_read_b128 v[180:183], v159 offset:2048
	ds_read_b128 v[184:187], v159 offset:3072
	ds_read_b128 v[188:191], v157 offset:32768
	ds_read_b128 v[192:195], v157 offset:33792
	ds_read_b128 v[196:199], v157 offset:34816
	ds_read_b128 v[200:203], v157 offset:35840
	ds_read_b128 v[204:207], v157 offset:36864
	ds_read_b128 v[208:211], v157 offset:37888
	ds_read_b128 v[212:215], v157 offset:38912
	ds_read_b128 v[216:219], v157 offset:39936
	s_add_u32 s76, s76, 0x80000
	s_addc_u32 s77, s77, 0
	s_mov_b32 m0, s12
	v_lshl_add_u64 v[228:229], s[76:77], 0, v[128:129]
	global_load_lds_dwordx4 v[228:229], off
	v_lshl_add_u64 v[228:229], s[76:77], 0, v[132:133]
	s_mov_b32 m0, s13
	s_nop 0
	global_load_lds_dwordx4 v[228:229], off
	s_waitcnt vmcnt(8)
	s_waitcnt lgkmcnt(0)
	s_barrier
	s_setprio 1
	s_waitcnt lgkmcnt(0)
	v_mfma_f32_16x16x32_bf16 v[124:127], v[146:149], v[188:191], v[124:127]
	v_mfma_f32_16x16x32_bf16 v[120:123], v[164:167], v[188:191], v[120:123]
	v_mfma_f32_16x16x32_bf16 v[108:111], v[146:149], v[196:199], v[108:111]
	v_mfma_f32_16x16x32_bf16 v[104:107], v[164:167], v[196:199], v[104:107]
	v_mfma_f32_16x16x32_bf16 v[92:95], v[146:149], v[204:207], v[92:95]
	v_mfma_f32_16x16x32_bf16 v[88:91], v[164:167], v[204:207], v[88:91]
	v_mfma_f32_16x16x32_bf16 v[76:79], v[146:149], v[212:215], v[76:79]
	v_mfma_f32_16x16x32_bf16 v[72:75], v[164:167], v[212:215], v[72:75]
	v_mfma_f32_16x16x32_bf16 v[124:127], v[160:163], v[192:195], v[124:127]
	v_mfma_f32_16x16x32_bf16 v[120:123], v[168:171], v[192:195], v[120:123]
	v_mfma_f32_16x16x32_bf16 v[108:111], v[160:163], v[200:203], v[108:111]
	v_mfma_f32_16x16x32_bf16 v[104:107], v[168:171], v[200:203], v[104:107]
	v_mfma_f32_16x16x32_bf16 v[92:95], v[160:163], v[208:211], v[92:95]
	v_mfma_f32_16x16x32_bf16 v[88:91], v[168:171], v[208:211], v[88:91]
	v_mfma_f32_16x16x32_bf16 v[76:79], v[160:163], v[216:219], v[76:79]
	v_mfma_f32_16x16x32_bf16 v[72:75], v[168:171], v[216:219], v[72:75]
	v_mfma_f32_16x16x32_bf16 v[116:119], v[172:175], v[188:191], v[116:119]
	v_mfma_f32_16x16x32_bf16 v[112:115], v[180:183], v[188:191], v[112:115]
	v_mfma_f32_16x16x32_bf16 v[100:103], v[172:175], v[196:199], v[100:103]
	v_mfma_f32_16x16x32_bf16 v[96:99], v[180:183], v[196:199], v[96:99]
	v_mfma_f32_16x16x32_bf16 v[84:87], v[172:175], v[204:207], v[84:87]
	v_mfma_f32_16x16x32_bf16 v[80:83], v[180:183], v[204:207], v[80:83]
	v_mfma_f32_16x16x32_bf16 v[68:71], v[172:175], v[212:215], v[68:71]
	v_mfma_f32_16x16x32_bf16 v[64:67], v[180:183], v[212:215], v[64:67]
	v_mfma_f32_16x16x32_bf16 v[116:119], v[176:179], v[192:195], v[116:119]
	v_mfma_f32_16x16x32_bf16 v[112:115], v[184:187], v[192:195], v[112:115]
	v_mfma_f32_16x16x32_bf16 v[100:103], v[176:179], v[200:203], v[100:103]
	v_mfma_f32_16x16x32_bf16 v[96:99], v[184:187], v[200:203], v[96:99]
	v_mfma_f32_16x16x32_bf16 v[84:87], v[176:179], v[208:211], v[84:87]
	v_mfma_f32_16x16x32_bf16 v[80:83], v[184:187], v[208:211], v[80:83]
	v_mfma_f32_16x16x32_bf16 v[68:71], v[176:179], v[216:219], v[68:71]
	v_mfma_f32_16x16x32_bf16 v[64:67], v[184:187], v[216:219], v[64:67]
	s_barrier
	s_setprio 0
	ds_read_b128 v[188:191], v157 offset:49152
	ds_read_b128 v[192:195], v157 offset:50176
	ds_read_b128 v[196:199], v157 offset:51200
	ds_read_b128 v[200:203], v157 offset:52224
	ds_read_b128 v[204:207], v157 offset:53248
	ds_read_b128 v[208:211], v157 offset:54272
	ds_read_b128 v[212:215], v157 offset:55296
	ds_read_b128 v[216:219], v157 offset:56320
	s_add_i32 s60, s60, s94
	v_lshl_add_u64 v[220:221], v[220:221], 0, s[20:21]
	s_mov_b32 m0, s60
	s_nop 0
	global_load_lds_dwordx4 v[220:221], off
	s_add_i32 m0, s60, 0x2000
	s_add_u32 s74, s74, 0x80080
	v_lshl_add_u64 v[220:221], v[222:223], 0, s[20:21]
	s_addc_u32 s75, s75, 0
	s_add_i32 s60, s61, s94
	global_load_lds_dwordx4 v[220:221], off
	v_lshl_add_u64 v[220:221], s[74:75], 0, v[130:131]
	s_mov_b32 m0, s60
	s_nop 0
	global_load_lds_dwordx4 v[220:221], off
	v_lshl_add_u64 v[220:221], s[74:75], 0, v[134:135]
	s_add_i32 m0, s60, 0x2000
	s_nop 0
	global_load_lds_dwordx4 v[220:221], off
	v_lshl_add_u64 v[220:221], v[224:225], 0, s[20:21]
	s_mov_b32 m0, s30
	s_nop 0
	global_load_lds_dwordx4 v[220:221], off
	v_lshl_add_u64 v[220:221], v[226:227], 0, s[20:21]
	s_mov_b32 m0, s34
	s_nop 0
	global_load_lds_dwordx4 v[220:221], off
	s_waitcnt vmcnt(8)
	s_waitcnt lgkmcnt(0)
	s_barrier
	s_setprio 1
	s_waitcnt lgkmcnt(0)
	v_mfma_f32_16x16x32_bf16 v[60:63], v[146:149], v[188:191], v[60:63]
	v_mfma_f32_16x16x32_bf16 v[56:59], v[164:167], v[188:191], v[56:59]
	v_mfma_f32_16x16x32_bf16 v[44:47], v[146:149], v[196:199], v[44:47]
	v_mfma_f32_16x16x32_bf16 v[40:43], v[164:167], v[196:199], v[40:43]
	v_mfma_f32_16x16x32_bf16 v[28:31], v[146:149], v[204:207], v[28:31]
	v_mfma_f32_16x16x32_bf16 v[24:27], v[164:167], v[204:207], v[24:27]
	v_mfma_f32_16x16x32_bf16 v[12:15], v[146:149], v[212:215], v[12:15]
	v_mfma_f32_16x16x32_bf16 v[8:11], v[164:167], v[212:215], v[8:11]
	v_mfma_f32_16x16x32_bf16 v[60:63], v[160:163], v[192:195], v[60:63]
	v_mfma_f32_16x16x32_bf16 v[56:59], v[168:171], v[192:195], v[56:59]
	v_mfma_f32_16x16x32_bf16 v[44:47], v[160:163], v[200:203], v[44:47]
	v_mfma_f32_16x16x32_bf16 v[40:43], v[168:171], v[200:203], v[40:43]
	v_mfma_f32_16x16x32_bf16 v[28:31], v[160:163], v[208:211], v[28:31]
	v_mfma_f32_16x16x32_bf16 v[24:27], v[168:171], v[208:211], v[24:27]
	v_mfma_f32_16x16x32_bf16 v[12:15], v[160:163], v[216:219], v[12:15]
	v_mfma_f32_16x16x32_bf16 v[8:11], v[168:171], v[216:219], v[8:11]
	v_mfma_f32_16x16x32_bf16 v[52:55], v[172:175], v[188:191], v[52:55]
	v_mfma_f32_16x16x32_bf16 v[48:51], v[180:183], v[188:191], v[48:51]
	v_mfma_f32_16x16x32_bf16 v[36:39], v[172:175], v[196:199], v[36:39]
	v_mfma_f32_16x16x32_bf16 v[32:35], v[180:183], v[196:199], v[32:35]
	v_mfma_f32_16x16x32_bf16 v[20:23], v[172:175], v[204:207], v[20:23]
	v_mfma_f32_16x16x32_bf16 v[16:19], v[180:183], v[204:207], v[16:19]
	v_mfma_f32_16x16x32_bf16 v[4:7], v[172:175], v[212:215], v[4:7]
	v_mfma_f32_16x16x32_bf16 v[0:3], v[180:183], v[212:215], v[0:3]
	v_mfma_f32_16x16x32_bf16 v[52:55], v[176:179], v[192:195], v[52:55]
	v_mfma_f32_16x16x32_bf16 v[48:51], v[184:187], v[192:195], v[48:51]
	v_mfma_f32_16x16x32_bf16 v[36:39], v[176:179], v[200:203], v[36:39]
	v_mfma_f32_16x16x32_bf16 v[32:35], v[184:187], v[200:203], v[32:35]
	v_mfma_f32_16x16x32_bf16 v[20:23], v[176:179], v[208:211], v[20:23]
	v_mfma_f32_16x16x32_bf16 v[16:19], v[184:187], v[208:211], v[16:19]
	v_mfma_f32_16x16x32_bf16 v[4:7], v[176:179], v[216:219], v[4:7]
	v_mfma_f32_16x16x32_bf16 v[0:3], v[184:187], v[216:219], v[0:3]
	s_barrier
	s_setprio 0
	s_add_i32 s78, s78, 2
	s_add_u32 s72, s72, 0x100
	s_addc_u32 s73, s73, 0
	s_add_u32 s69, s69, 0x100
	s_addc_u32 s71, s71, 0
	s_cmp_gt_u32 s78, 29
	s_cbranch_scc0 .LBB0_1785
	s_and_b64 vcc, exec, s[58:59]
	s_cbranch_vccz .LBB0_1788
	s_barrier

.LBB0_1897:
	ds_read_b128 v[140:143], v149
	ds_read_b128 v[152:155], v149 offset:1024
	ds_read_b128 v[156:159], v149 offset:2048
	ds_read_b128 v[160:163], v149 offset:3072
	ds_read_b128 v[164:167], v150
	ds_read_b128 v[168:171], v150 offset:1024
	ds_read_b128 v[172:175], v150 offset:2048
	ds_read_b128 v[176:179], v150 offset:3072
	ds_read_b128 v[180:183], v151
	ds_read_b128 v[184:187], v151 offset:1024
	ds_read_b128 v[188:191], v151 offset:2048
	ds_read_b128 v[192:195], v151 offset:3072
	ds_read_b128 v[196:199], v151 offset:4096
	ds_read_b128 v[200:203], v151 offset:5120
	ds_read_b128 v[204:207], v151 offset:6144
	ds_read_b128 v[208:211], v151 offset:7168
	s_add_u32 s60, s72, 0xffe00080
	s_addc_u32 s61, s73, -1
	s_cmpk_eq_i32 s79, 0x7c
	s_cselect_b32 s77, s56, s61
	s_cselect_b32 s76, s57, s60
	s_cselect_b32 s75, s63, s78
	s_cselect_b32 s74, s65, s71
	v_lshl_add_u64 v[212:213], s[72:73], 0, v[132:133]
	s_add_i32 m0, s6, 0xc000
	s_nop 0
	global_load_lds_dwordx4 v[212:213], off
	v_lshl_add_u64 v[212:213], s[72:73], 0, v[134:135]
	s_add_i32 m0, s6, 0xe000
	s_nop 0
	global_load_lds_dwordx4 v[212:213], off
	s_waitcnt vmcnt(8)
	s_waitcnt lgkmcnt(0)
	s_barrier
	s_setprio 1
	s_waitcnt lgkmcnt(0)
	v_mfma_f32_16x16x32_bf16 v[124:127], v[140:143], v[180:183], v[124:127]
	v_mfma_f32_16x16x32_bf16 v[120:123], v[156:159], v[180:183], v[120:123]
	v_mfma_f32_16x16x32_bf16 v[108:111], v[140:143], v[188:191], v[108:111]
	v_mfma_f32_16x16x32_bf16 v[104:107], v[156:159], v[188:191], v[104:107]
	v_mfma_f32_16x16x32_bf16 v[92:95], v[140:143], v[196:199], v[92:95]
	v_mfma_f32_16x16x32_bf16 v[88:91], v[156:159], v[196:199], v[88:91]
	v_mfma_f32_16x16x32_bf16 v[76:79], v[140:143], v[204:207], v[76:79]
	v_mfma_f32_16x16x32_bf16 v[72:75], v[156:159], v[204:207], v[72:75]
	v_mfma_f32_16x16x32_bf16 v[124:127], v[152:155], v[184:187], v[124:127]
	v_mfma_f32_16x16x32_bf16 v[120:123], v[160:163], v[184:187], v[120:123]
	v_mfma_f32_16x16x32_bf16 v[108:111], v[152:155], v[192:195], v[108:111]
	v_mfma_f32_16x16x32_bf16 v[104:107], v[160:163], v[192:195], v[104:107]
	v_mfma_f32_16x16x32_bf16 v[92:95], v[152:155], v[200:203], v[92:95]
	v_mfma_f32_16x16x32_bf16 v[88:91], v[160:163], v[200:203], v[88:91]
	v_mfma_f32_16x16x32_bf16 v[76:79], v[152:155], v[208:211], v[76:79]
	v_mfma_f32_16x16x32_bf16 v[72:75], v[160:163], v[208:211], v[72:75]
	v_mfma_f32_16x16x32_bf16 v[116:119], v[164:167], v[180:183], v[116:119]
	v_mfma_f32_16x16x32_bf16 v[112:115], v[172:175], v[180:183], v[112:115]
	v_mfma_f32_16x16x32_bf16 v[100:103], v[164:167], v[188:191], v[100:103]
	v_mfma_f32_16x16x32_bf16 v[96:99], v[172:175], v[188:191], v[96:99]
	v_mfma_f32_16x16x32_bf16 v[84:87], v[164:167], v[196:199], v[84:87]
	v_mfma_f32_16x16x32_bf16 v[80:83], v[172:175], v[196:199], v[80:83]
	v_mfma_f32_16x16x32_bf16 v[68:71], v[164:167], v[204:207], v[68:71]
	v_mfma_f32_16x16x32_bf16 v[64:67], v[172:175], v[204:207], v[64:67]
	v_mfma_f32_16x16x32_bf16 v[116:119], v[168:171], v[184:187], v[116:119]
	v_mfma_f32_16x16x32_bf16 v[112:115], v[176:179], v[184:187], v[112:115]
	v_mfma_f32_16x16x32_bf16 v[100:103], v[168:171], v[192:195], v[100:103]
	v_mfma_f32_16x16x32_bf16 v[96:99], v[176:179], v[192:195], v[96:99]
	v_mfma_f32_16x16x32_bf16 v[84:87], v[168:171], v[200:203], v[84:87]
	v_mfma_f32_16x16x32_bf16 v[80:83], v[176:179], v[200:203], v[80:83]
	v_mfma_f32_16x16x32_bf16 v[68:71], v[168:171], v[208:211], v[68:71]
	v_mfma_f32_16x16x32_bf16 v[64:67], v[176:179], v[208:211], v[64:67]
	s_barrier
	s_setprio 0
	ds_read_b128 v[180:183], v151 offset:16384
	ds_read_b128 v[184:187], v151 offset:17408
	ds_read_b128 v[188:191], v151 offset:18432
	ds_read_b128 v[192:195], v151 offset:19456
	ds_read_b128 v[196:199], v151 offset:20480
	ds_read_b128 v[200:203], v151 offset:21504
	ds_read_b128 v[204:207], v151 offset:22528
	ds_read_b128 v[208:211], v151 offset:23552
	s_add_i32 s60, s34, s94
	v_lshl_add_u64 v[212:213], s[74:75], 0, v[128:129]
	s_mov_b32 m0, s60
	s_nop 0
	global_load_lds_dwordx4 v[212:213], off
	s_add_i32 m0, s60, 0x2000
	s_add_u32 s80, s74, 0x200000
	v_lshl_add_u64 v[214:215], s[74:75], 0, v[130:131]
	s_addc_u32 s81, s75, 0
	s_add_i32 s60, s35, s94
	global_load_lds_dwordx4 v[214:215], off
	v_lshl_add_u64 v[216:217], s[80:81], 0, v[128:129]
	s_mov_b32 m0, s60
	v_lshl_add_u64 v[218:219], s[76:77], 0, v[130:131]
	global_load_lds_dwordx4 v[216:217], off
	v_lshl_add_u64 v[216:217], s[80:81], 0, v[130:131]
	s_add_i32 m0, s60, 0x2000
	s_nop 0
	global_load_lds_dwordx4 v[216:217], off
	v_lshl_add_u64 v[216:217], s[76:77], 0, v[128:129]
	s_mov_b32 m0, s6
	s_nop 0
	global_load_lds_dwordx4 v[216:217], off
	s_mov_b32 m0, s7
	s_nop 0
	global_load_lds_dwordx4 v[218:219], off
	s_waitcnt vmcnt(8)
	s_waitcnt lgkmcnt(0)
	s_barrier
	s_setprio 1
	s_waitcnt lgkmcnt(0)
	v_mfma_f32_16x16x32_bf16 v[60:63], v[140:143], v[180:183], v[60:63]
	v_mfma_f32_16x16x32_bf16 v[56:59], v[156:159], v[180:183], v[56:59]
	v_mfma_f32_16x16x32_bf16 v[44:47], v[140:143], v[188:191], v[44:47]
	v_mfma_f32_16x16x32_bf16 v[40:43], v[156:159], v[188:191], v[40:43]
	v_mfma_f32_16x16x32_bf16 v[28:31], v[140:143], v[196:199], v[28:31]
	v_mfma_f32_16x16x32_bf16 v[24:27], v[156:159], v[196:199], v[24:27]
	v_mfma_f32_16x16x32_bf16 v[12:15], v[140:143], v[204:207], v[12:15]
	v_mfma_f32_16x16x32_bf16 v[8:11], v[156:159], v[204:207], v[8:11]
	v_mfma_f32_16x16x32_bf16 v[60:63], v[152:155], v[184:187], v[60:63]
	v_mfma_f32_16x16x32_bf16 v[56:59], v[160:163], v[184:187], v[56:59]
	v_mfma_f32_16x16x32_bf16 v[44:47], v[152:155], v[192:195], v[44:47]
	v_mfma_f32_16x16x32_bf16 v[40:43], v[160:163], v[192:195], v[40:43]
	v_mfma_f32_16x16x32_bf16 v[28:31], v[152:155], v[200:203], v[28:31]
	v_mfma_f32_16x16x32_bf16 v[24:27], v[160:163], v[200:203], v[24:27]
	v_mfma_f32_16x16x32_bf16 v[12:15], v[152:155], v[208:211], v[12:15]
	v_mfma_f32_16x16x32_bf16 v[8:11], v[160:163], v[208:211], v[8:11]
	v_mfma_f32_16x16x32_bf16 v[52:55], v[164:167], v[180:183], v[52:55]
	v_mfma_f32_16x16x32_bf16 v[48:51], v[172:175], v[180:183], v[48:51]
	v_mfma_f32_16x16x32_bf16 v[36:39], v[164:167], v[188:191], v[36:39]
	v_mfma_f32_16x16x32_bf16 v[32:35], v[172:175], v[188:191], v[32:35]
	v_mfma_f32_16x16x32_bf16 v[20:23], v[164:167], v[196:199], v[20:23]
	v_mfma_f32_16x16x32_bf16 v[16:19], v[172:175], v[196:199], v[16:19]
	v_mfma_f32_16x16x32_bf16 v[4:7], v[164:167], v[204:207], v[4:7]
	v_mfma_f32_16x16x32_bf16 v[0:3], v[172:175], v[204:207], v[0:3]
	v_mfma_f32_16x16x32_bf16 v[52:55], v[168:171], v[184:187], v[52:55]
	v_mfma_f32_16x16x32_bf16 v[48:51], v[176:179], v[184:187], v[48:51]
	v_mfma_f32_16x16x32_bf16 v[36:39], v[168:171], v[192:195], v[36:39]
	v_mfma_f32_16x16x32_bf16 v[32:35], v[176:179], v[192:195], v[32:35]
	v_mfma_f32_16x16x32_bf16 v[20:23], v[168:171], v[200:203], v[20:23]
	v_mfma_f32_16x16x32_bf16 v[16:19], v[176:179], v[200:203], v[16:19]
	v_mfma_f32_16x16x32_bf16 v[4:7], v[168:171], v[208:211], v[4:7]
	v_mfma_f32_16x16x32_bf16 v[0:3], v[176:179], v[208:211], v[0:3]
	s_barrier
	s_setprio 0
	s_add_i32 s60, 0, 0x18000
	s_add_i32 s61, 0, 0x1c000
	v_add_u32_e32 v160, s60, v145
	ds_read_b128 v[140:143], v160
	ds_read_b128 v[152:155], v160 offset:1024
	ds_read_b128 v[156:159], v160 offset:2048
	ds_read_b128 v[160:163], v160 offset:3072
	v_add_u32_e32 v176, s61, v145
	ds_read_b128 v[164:167], v176
	ds_read_b128 v[168:171], v176 offset:1024
	ds_read_b128 v[172:175], v176 offset:2048
	ds_read_b128 v[176:179], v176 offset:3072
	ds_read_b128 v[180:183], v151 offset:32768
	ds_read_b128 v[184:187], v151 offset:33792
	ds_read_b128 v[188:191], v151 offset:34816
	ds_read_b128 v[192:195], v151 offset:35840
	ds_read_b128 v[196:199], v151 offset:36864
	ds_read_b128 v[200:203], v151 offset:37888
	ds_read_b128 v[204:207], v151 offset:38912
	ds_read_b128 v[208:211], v151 offset:39936
	s_add_u32 s76, s76, 0x200000
	s_addc_u32 s77, s77, 0
	s_mov_b32 m0, s12
	v_lshl_add_u64 v[220:221], s[76:77], 0, v[128:129]
	global_load_lds_dwordx4 v[220:221], off
	v_lshl_add_u64 v[220:221], s[76:77], 0, v[130:131]
	s_mov_b32 m0, s13
	s_nop 0
	global_load_lds_dwordx4 v[220:221], off
	s_waitcnt vmcnt(8)
	s_waitcnt lgkmcnt(0)
	s_barrier
	s_setprio 1
	s_waitcnt lgkmcnt(0)
	v_mfma_f32_16x16x32_bf16 v[124:127], v[140:143], v[180:183], v[124:127]
	v_mfma_f32_16x16x32_bf16 v[120:123], v[156:159], v[180:183], v[120:123]
	v_mfma_f32_16x16x32_bf16 v[108:111], v[140:143], v[188:191], v[108:111]
	v_mfma_f32_16x16x32_bf16 v[104:107], v[156:159], v[188:191], v[104:107]
	v_mfma_f32_16x16x32_bf16 v[92:95], v[140:143], v[196:199], v[92:95]
	v_mfma_f32_16x16x32_bf16 v[88:91], v[156:159], v[196:199], v[88:91]
	v_mfma_f32_16x16x32_bf16 v[76:79], v[140:143], v[204:207], v[76:79]
	v_mfma_f32_16x16x32_bf16 v[72:75], v[156:159], v[204:207], v[72:75]
	v_mfma_f32_16x16x32_bf16 v[124:127], v[152:155], v[184:187], v[124:127]
	v_mfma_f32_16x16x32_bf16 v[120:123], v[160:163], v[184:187], v[120:123]
	v_mfma_f32_16x16x32_bf16 v[108:111], v[152:155], v[192:195], v[108:111]
	v_mfma_f32_16x16x32_bf16 v[104:107], v[160:163], v[192:195], v[104:107]
	v_mfma_f32_16x16x32_bf16 v[92:95], v[152:155], v[200:203], v[92:95]
	v_mfma_f32_16x16x32_bf16 v[88:91], v[160:163], v[200:203], v[88:91]
	v_mfma_f32_16x16x32_bf16 v[76:79], v[152:155], v[208:211], v[76:79]
	v_mfma_f32_16x16x32_bf16 v[72:75], v[160:163], v[208:211], v[72:75]
	v_mfma_f32_16x16x32_bf16 v[116:119], v[164:167], v[180:183], v[116:119]
	v_mfma_f32_16x16x32_bf16 v[112:115], v[172:175], v[180:183], v[112:115]
	v_mfma_f32_16x16x32_bf16 v[100:103], v[164:167], v[188:191], v[100:103]
	v_mfma_f32_16x16x32_bf16 v[96:99], v[172:175], v[188:191], v[96:99]
	v_mfma_f32_16x16x32_bf16 v[84:87], v[164:167], v[196:199], v[84:87]
	v_mfma_f32_16x16x32_bf16 v[80:83], v[172:175], v[196:199], v[80:83]
	v_mfma_f32_16x16x32_bf16 v[68:71], v[164:167], v[204:207], v[68:71]
	v_mfma_f32_16x16x32_bf16 v[64:67], v[172:175], v[204:207], v[64:67]
	v_mfma_f32_16x16x32_bf16 v[116:119], v[168:171], v[184:187], v[116:119]
	v_mfma_f32_16x16x32_bf16 v[112:115], v[176:179], v[184:187], v[112:115]
	v_mfma_f32_16x16x32_bf16 v[100:103], v[168:171], v[192:195], v[100:103]
	v_mfma_f32_16x16x32_bf16 v[96:99], v[176:179], v[192:195], v[96:99]
	v_mfma_f32_16x16x32_bf16 v[84:87], v[168:171], v[200:203], v[84:87]
	v_mfma_f32_16x16x32_bf16 v[80:83], v[176:179], v[200:203], v[80:83]
	v_mfma_f32_16x16x32_bf16 v[68:71], v[168:171], v[208:211], v[68:71]
	v_mfma_f32_16x16x32_bf16 v[64:67], v[176:179], v[208:211], v[64:67]
	s_barrier
	s_setprio 0
	ds_read_b128 v[180:183], v151 offset:49152
	ds_read_b128 v[184:187], v151 offset:50176
	ds_read_b128 v[188:191], v151 offset:51200
	ds_read_b128 v[192:195], v151 offset:52224
	ds_read_b128 v[196:199], v151 offset:53248
	ds_read_b128 v[200:203], v151 offset:54272
	ds_read_b128 v[204:207], v151 offset:55296
	ds_read_b128 v[208:211], v151 offset:56320
	s_add_i32 s60, s60, s94
	v_lshl_add_u64 v[212:213], v[212:213], 0, s[22:23]
	s_mov_b32 m0, s60
	s_nop 0
	global_load_lds_dwordx4 v[212:213], off
	s_add_i32 m0, s60, 0x2000
	s_add_u32 s74, s74, 0x200080
	v_lshl_add_u64 v[212:213], v[214:215], 0, s[22:23]
	s_addc_u32 s75, s75, 0
	s_add_i32 s60, s61, s94
	global_load_lds_dwordx4 v[212:213], off
	v_lshl_add_u64 v[212:213], s[74:75], 0, v[128:129]
	s_mov_b32 m0, s60
	s_nop 0
	global_load_lds_dwordx4 v[212:213], off
	v_lshl_add_u64 v[212:213], s[74:75], 0, v[130:131]
	s_add_i32 m0, s60, 0x2000
	s_nop 0
	global_load_lds_dwordx4 v[212:213], off
	v_lshl_add_u64 v[212:213], v[216:217], 0, s[22:23]
	s_mov_b32 m0, s29
	s_nop 0
	global_load_lds_dwordx4 v[212:213], off
	v_lshl_add_u64 v[212:213], v[218:219], 0, s[22:23]
	s_mov_b32 m0, s30
	s_nop 0
	global_load_lds_dwordx4 v[212:213], off
	s_waitcnt vmcnt(8)
	s_waitcnt lgkmcnt(0)
	s_barrier
	s_setprio 1
	s_waitcnt lgkmcnt(0)
	v_mfma_f32_16x16x32_bf16 v[60:63], v[140:143], v[180:183], v[60:63]
	v_mfma_f32_16x16x32_bf16 v[56:59], v[156:159], v[180:183], v[56:59]
	v_mfma_f32_16x16x32_bf16 v[44:47], v[140:143], v[188:191], v[44:47]
	v_mfma_f32_16x16x32_bf16 v[40:43], v[156:159], v[188:191], v[40:43]
	v_mfma_f32_16x16x32_bf16 v[28:31], v[140:143], v[196:199], v[28:31]
	v_mfma_f32_16x16x32_bf16 v[24:27], v[156:159], v[196:199], v[24:27]
	v_mfma_f32_16x16x32_bf16 v[12:15], v[140:143], v[204:207], v[12:15]
	v_mfma_f32_16x16x32_bf16 v[8:11], v[156:159], v[204:207], v[8:11]
	v_mfma_f32_16x16x32_bf16 v[60:63], v[152:155], v[184:187], v[60:63]
	v_mfma_f32_16x16x32_bf16 v[56:59], v[160:163], v[184:187], v[56:59]
	v_mfma_f32_16x16x32_bf16 v[44:47], v[152:155], v[192:195], v[44:47]
	v_mfma_f32_16x16x32_bf16 v[40:43], v[160:163], v[192:195], v[40:43]
	v_mfma_f32_16x16x32_bf16 v[28:31], v[152:155], v[200:203], v[28:31]
	v_mfma_f32_16x16x32_bf16 v[24:27], v[160:163], v[200:203], v[24:27]
	v_mfma_f32_16x16x32_bf16 v[12:15], v[152:155], v[208:211], v[12:15]
	v_mfma_f32_16x16x32_bf16 v[8:11], v[160:163], v[208:211], v[8:11]
	v_mfma_f32_16x16x32_bf16 v[52:55], v[164:167], v[180:183], v[52:55]
	v_mfma_f32_16x16x32_bf16 v[48:51], v[172:175], v[180:183], v[48:51]
	v_mfma_f32_16x16x32_bf16 v[36:39], v[164:167], v[188:191], v[36:39]
	v_mfma_f32_16x16x32_bf16 v[32:35], v[172:175], v[188:191], v[32:35]
	v_mfma_f32_16x16x32_bf16 v[20:23], v[164:167], v[196:199], v[20:23]
	v_mfma_f32_16x16x32_bf16 v[16:19], v[172:175], v[196:199], v[16:19]
	v_mfma_f32_16x16x32_bf16 v[4:7], v[164:167], v[204:207], v[4:7]
	v_mfma_f32_16x16x32_bf16 v[0:3], v[172:175], v[204:207], v[0:3]
	v_mfma_f32_16x16x32_bf16 v[52:55], v[168:171], v[184:187], v[52:55]
	v_mfma_f32_16x16x32_bf16 v[48:51], v[176:179], v[184:187], v[48:51]
	v_mfma_f32_16x16x32_bf16 v[36:39], v[168:171], v[192:195], v[36:39]
	v_mfma_f32_16x16x32_bf16 v[32:35], v[176:179], v[192:195], v[32:35]
	v_mfma_f32_16x16x32_bf16 v[20:23], v[168:171], v[200:203], v[20:23]
	v_mfma_f32_16x16x32_bf16 v[16:19], v[176:179], v[200:203], v[16:19]
	v_mfma_f32_16x16x32_bf16 v[4:7], v[168:171], v[208:211], v[4:7]
	v_mfma_f32_16x16x32_bf16 v[0:3], v[176:179], v[208:211], v[0:3]
	s_barrier
	s_setprio 0
	s_add_i32 s79, s79, 2
	s_add_u32 s72, s72, 0x100
	s_addc_u32 s73, s73, 0
	s_add_u32 s71, s71, 0x100
	s_addc_u32 s78, s78, 0
	s_cmpk_gt_u32 s79, 0x7d
	s_cbranch_scc0 .LBB0_1897
	s_and_b64 vcc, exec, s[58:59]
	s_cbranch_vccz .LBB0_1900
	s_barrier

.LBB0_2128:
	ds_read_b128 v[148:151], v179
	ds_read_b128 v[152:155], v179 offset:1024
	ds_read_b128 v[156:159], v179 offset:2048
	ds_read_b128 v[160:163], v179 offset:3072
	ds_read_b128 v[164:167], v180
	ds_read_b128 v[168:171], v180 offset:1024
	ds_read_b128 v[184:187], v180 offset:2048
	ds_read_b128 v[188:191], v180 offset:3072
	ds_read_b128 v[192:195], v181
	ds_read_b128 v[196:199], v181 offset:1024
	ds_read_b128 v[200:203], v181 offset:2048
	ds_read_b128 v[204:207], v181 offset:3072
	ds_read_b128 v[208:211], v181 offset:4096
	ds_read_b128 v[212:215], v181 offset:5120
	ds_read_b128 v[216:219], v181 offset:6144
	ds_read_b128 v[220:223], v181 offset:7168
	s_add_u32 s60, s84, 0xfff80080
	s_addc_u32 s61, s85, -1
	s_cmp_eq_u32 s95, 28
	s_cselect_b32 s89, s23, s61
	s_cselect_b32 s88, s79, s60
	s_cselect_b32 s87, s77, s97
	s_cselect_b32 s86, vcc_lo, vcc_hi
	v_lshl_add_u64 v[172:173], s[84:85], 0, v[140:141]
	s_add_i32 m0, s6, 0xc000
	s_nop 0
	global_load_lds_dwordx4 v[172:173], off
	v_lshl_add_u64 v[172:173], s[84:85], 0, v[142:143]
	s_add_i32 m0, s6, 0xe000
	s_nop 0
	global_load_lds_dwordx4 v[172:173], off
	s_waitcnt vmcnt(8)
	s_waitcnt lgkmcnt(0)
	s_barrier
	s_setprio 1
	s_waitcnt lgkmcnt(0)
	v_mfma_f32_16x16x32_bf16 v[124:127], v[148:151], v[192:195], v[124:127]
	v_mfma_f32_16x16x32_bf16 v[120:123], v[156:159], v[192:195], v[120:123]
	v_mfma_f32_16x16x32_bf16 v[108:111], v[148:151], v[200:203], v[108:111]
	v_mfma_f32_16x16x32_bf16 v[104:107], v[156:159], v[200:203], v[104:107]
	v_mfma_f32_16x16x32_bf16 v[92:95], v[148:151], v[208:211], v[92:95]
	v_mfma_f32_16x16x32_bf16 v[88:91], v[156:159], v[208:211], v[88:91]
	v_mfma_f32_16x16x32_bf16 v[76:79], v[148:151], v[216:219], v[76:79]
	v_mfma_f32_16x16x32_bf16 v[72:75], v[156:159], v[216:219], v[72:75]
	v_mfma_f32_16x16x32_bf16 v[124:127], v[152:155], v[196:199], v[124:127]
	v_mfma_f32_16x16x32_bf16 v[120:123], v[160:163], v[196:199], v[120:123]
	v_mfma_f32_16x16x32_bf16 v[108:111], v[152:155], v[204:207], v[108:111]
	v_mfma_f32_16x16x32_bf16 v[104:107], v[160:163], v[204:207], v[104:107]
	v_mfma_f32_16x16x32_bf16 v[92:95], v[152:155], v[212:215], v[92:95]
	v_mfma_f32_16x16x32_bf16 v[88:91], v[160:163], v[212:215], v[88:91]
	v_mfma_f32_16x16x32_bf16 v[76:79], v[152:155], v[220:223], v[76:79]
	v_mfma_f32_16x16x32_bf16 v[72:75], v[160:163], v[220:223], v[72:75]
	v_mfma_f32_16x16x32_bf16 v[116:119], v[164:167], v[192:195], v[116:119]
	v_mfma_f32_16x16x32_bf16 v[112:115], v[184:187], v[192:195], v[112:115]
	v_mfma_f32_16x16x32_bf16 v[100:103], v[164:167], v[200:203], v[100:103]
	v_mfma_f32_16x16x32_bf16 v[96:99], v[184:187], v[200:203], v[96:99]
	v_mfma_f32_16x16x32_bf16 v[84:87], v[164:167], v[208:211], v[84:87]
	v_mfma_f32_16x16x32_bf16 v[80:83], v[184:187], v[208:211], v[80:83]
	v_mfma_f32_16x16x32_bf16 v[68:71], v[164:167], v[216:219], v[68:71]
	v_mfma_f32_16x16x32_bf16 v[64:67], v[184:187], v[216:219], v[64:67]
	v_mfma_f32_16x16x32_bf16 v[116:119], v[168:171], v[196:199], v[116:119]
	v_mfma_f32_16x16x32_bf16 v[112:115], v[188:191], v[196:199], v[112:115]
	v_mfma_f32_16x16x32_bf16 v[100:103], v[168:171], v[204:207], v[100:103]
	v_mfma_f32_16x16x32_bf16 v[96:99], v[188:191], v[204:207], v[96:99]
	v_mfma_f32_16x16x32_bf16 v[84:87], v[168:171], v[212:215], v[84:87]
	v_mfma_f32_16x16x32_bf16 v[80:83], v[188:191], v[212:215], v[80:83]
	v_mfma_f32_16x16x32_bf16 v[68:71], v[168:171], v[220:223], v[68:71]
	v_mfma_f32_16x16x32_bf16 v[64:67], v[188:191], v[220:223], v[64:67]
	s_barrier
	s_setprio 0
	ds_read_b128 v[192:195], v181 offset:16384
	ds_read_b128 v[196:199], v181 offset:17408
	ds_read_b128 v[200:203], v181 offset:18432
	ds_read_b128 v[204:207], v181 offset:19456
	ds_read_b128 v[208:211], v181 offset:20480
	ds_read_b128 v[212:215], v181 offset:21504
	ds_read_b128 v[216:219], v181 offset:22528
	ds_read_b128 v[220:223], v181 offset:23552
	s_add_i32 s60, s12, s94
	v_lshl_add_u64 v[172:173], s[86:87], 0, v[130:131]
	s_mov_b32 m0, s60
	s_nop 0
	global_load_lds_dwordx4 v[172:173], off
	s_add_i32 m0, s60, 0x2000
	s_add_u32 s60, s86, 0x80000
	v_lshl_add_u64 v[224:225], s[86:87], 0, v[134:135]
	s_addc_u32 s61, s87, 0
	s_add_i32 s96, s13, s94
	global_load_lds_dwordx4 v[224:225], off
	v_lshl_add_u64 v[226:227], s[60:61], 0, v[130:131]
	s_mov_b32 m0, s96
	v_lshl_add_u64 v[228:229], s[88:89], 0, v[132:133]
	global_load_lds_dwordx4 v[226:227], off
	v_lshl_add_u64 v[226:227], s[60:61], 0, v[134:135]
	s_add_i32 m0, s96, 0x2000
	s_nop 0
	global_load_lds_dwordx4 v[226:227], off
	v_lshl_add_u64 v[226:227], s[88:89], 0, v[128:129]
	s_mov_b32 m0, s6
	s_nop 0
	global_load_lds_dwordx4 v[226:227], off
	s_mov_b32 m0, s7
	s_nop 0
	global_load_lds_dwordx4 v[228:229], off
	s_waitcnt vmcnt(8)
	s_waitcnt lgkmcnt(0)
	s_barrier
	s_setprio 1
	s_waitcnt lgkmcnt(0)
	v_mfma_f32_16x16x32_bf16 v[60:63], v[148:151], v[192:195], v[60:63]
	v_mfma_f32_16x16x32_bf16 v[56:59], v[156:159], v[192:195], v[56:59]
	v_mfma_f32_16x16x32_bf16 v[44:47], v[148:151], v[200:203], v[44:47]
	v_mfma_f32_16x16x32_bf16 v[40:43], v[156:159], v[200:203], v[40:43]
	v_mfma_f32_16x16x32_bf16 v[28:31], v[148:151], v[208:211], v[28:31]
	v_mfma_f32_16x16x32_bf16 v[24:27], v[156:159], v[208:211], v[24:27]
	v_mfma_f32_16x16x32_bf16 v[12:15], v[148:151], v[216:219], v[12:15]
	v_mfma_f32_16x16x32_bf16 v[8:11], v[156:159], v[216:219], v[8:11]
	v_mfma_f32_16x16x32_bf16 v[60:63], v[152:155], v[196:199], v[60:63]
	v_mfma_f32_16x16x32_bf16 v[56:59], v[160:163], v[196:199], v[56:59]
	v_mfma_f32_16x16x32_bf16 v[44:47], v[152:155], v[204:207], v[44:47]
	v_mfma_f32_16x16x32_bf16 v[40:43], v[160:163], v[204:207], v[40:43]
	v_mfma_f32_16x16x32_bf16 v[28:31], v[152:155], v[212:215], v[28:31]
	v_mfma_f32_16x16x32_bf16 v[24:27], v[160:163], v[212:215], v[24:27]
	v_mfma_f32_16x16x32_bf16 v[12:15], v[152:155], v[220:223], v[12:15]
	v_mfma_f32_16x16x32_bf16 v[8:11], v[160:163], v[220:223], v[8:11]
	v_mfma_f32_16x16x32_bf16 v[52:55], v[164:167], v[192:195], v[52:55]
	v_mfma_f32_16x16x32_bf16 v[48:51], v[184:187], v[192:195], v[48:51]
	v_mfma_f32_16x16x32_bf16 v[36:39], v[164:167], v[200:203], v[36:39]
	v_mfma_f32_16x16x32_bf16 v[32:35], v[184:187], v[200:203], v[32:35]
	v_mfma_f32_16x16x32_bf16 v[20:23], v[164:167], v[208:211], v[20:23]
	v_mfma_f32_16x16x32_bf16 v[16:19], v[184:187], v[208:211], v[16:19]
	v_mfma_f32_16x16x32_bf16 v[4:7], v[164:167], v[216:219], v[4:7]
	v_mfma_f32_16x16x32_bf16 v[0:3], v[184:187], v[216:219], v[0:3]
	v_mfma_f32_16x16x32_bf16 v[52:55], v[168:171], v[196:199], v[52:55]
	v_mfma_f32_16x16x32_bf16 v[48:51], v[188:191], v[196:199], v[48:51]
	v_mfma_f32_16x16x32_bf16 v[36:39], v[168:171], v[204:207], v[36:39]
	v_mfma_f32_16x16x32_bf16 v[32:35], v[188:191], v[204:207], v[32:35]
	v_mfma_f32_16x16x32_bf16 v[20:23], v[168:171], v[212:215], v[20:23]
	v_mfma_f32_16x16x32_bf16 v[16:19], v[188:191], v[212:215], v[16:19]
	v_mfma_f32_16x16x32_bf16 v[4:7], v[168:171], v[220:223], v[4:7]
	v_mfma_f32_16x16x32_bf16 v[0:3], v[188:191], v[220:223], v[0:3]
	s_barrier
	s_setprio 0
	s_add_i32 s96, 0, 0x18000
	v_add_u32_e32 v136, s96, v175
	ds_read_b128 v[148:151], v136
	ds_read_b128 v[152:155], v136 offset:1024
	ds_read_b128 v[156:159], v136 offset:2048
	ds_read_b128 v[160:163], v136 offset:3072
	s_add_i32 s8, 0, 0x1c000
	v_add_u32_e32 v136, s8, v175
	ds_read_b128 v[164:167], v136
	ds_read_b128 v[168:171], v136 offset:1024
	ds_read_b128 v[184:187], v136 offset:2048
	ds_read_b128 v[188:191], v136 offset:3072
	ds_read_b128 v[192:195], v181 offset:32768
	ds_read_b128 v[196:199], v181 offset:33792
	ds_read_b128 v[200:203], v181 offset:34816
	ds_read_b128 v[204:207], v181 offset:35840
	ds_read_b128 v[208:211], v181 offset:36864
	ds_read_b128 v[212:215], v181 offset:37888
	ds_read_b128 v[216:219], v181 offset:38912
	ds_read_b128 v[220:223], v181 offset:39936
	s_add_u32 s60, s88, 0x80000
	s_addc_u32 s61, s89, 0
	s_mov_b32 m0, s34
	v_lshl_add_u64 v[230:231], s[60:61], 0, v[128:129]
	global_load_lds_dwordx4 v[230:231], off
	v_lshl_add_u64 v[230:231], s[60:61], 0, v[132:133]
	s_mov_b32 m0, s46
	s_nop 0
	global_load_lds_dwordx4 v[230:231], off
	s_waitcnt vmcnt(8)
	s_waitcnt lgkmcnt(0)
	s_barrier
	s_setprio 1
	s_waitcnt lgkmcnt(0)
	v_mfma_f32_16x16x32_bf16 v[124:127], v[148:151], v[192:195], v[124:127]
	v_mfma_f32_16x16x32_bf16 v[120:123], v[156:159], v[192:195], v[120:123]
	v_mfma_f32_16x16x32_bf16 v[108:111], v[148:151], v[200:203], v[108:111]
	v_mfma_f32_16x16x32_bf16 v[104:107], v[156:159], v[200:203], v[104:107]
	v_mfma_f32_16x16x32_bf16 v[92:95], v[148:151], v[208:211], v[92:95]
	v_mfma_f32_16x16x32_bf16 v[88:91], v[156:159], v[208:211], v[88:91]
	v_mfma_f32_16x16x32_bf16 v[76:79], v[148:151], v[216:219], v[76:79]
	v_mfma_f32_16x16x32_bf16 v[72:75], v[156:159], v[216:219], v[72:75]
	v_mfma_f32_16x16x32_bf16 v[124:127], v[152:155], v[196:199], v[124:127]
	v_mfma_f32_16x16x32_bf16 v[120:123], v[160:163], v[196:199], v[120:123]
	v_mfma_f32_16x16x32_bf16 v[108:111], v[152:155], v[204:207], v[108:111]
	v_mfma_f32_16x16x32_bf16 v[104:107], v[160:163], v[204:207], v[104:107]
	v_mfma_f32_16x16x32_bf16 v[92:95], v[152:155], v[212:215], v[92:95]
	v_mfma_f32_16x16x32_bf16 v[88:91], v[160:163], v[212:215], v[88:91]
	v_mfma_f32_16x16x32_bf16 v[76:79], v[152:155], v[220:223], v[76:79]
	v_mfma_f32_16x16x32_bf16 v[72:75], v[160:163], v[220:223], v[72:75]
	v_mfma_f32_16x16x32_bf16 v[116:119], v[164:167], v[192:195], v[116:119]
	v_mfma_f32_16x16x32_bf16 v[112:115], v[184:187], v[192:195], v[112:115]
	v_mfma_f32_16x16x32_bf16 v[100:103], v[164:167], v[200:203], v[100:103]
	v_mfma_f32_16x16x32_bf16 v[96:99], v[184:187], v[200:203], v[96:99]
	v_mfma_f32_16x16x32_bf16 v[84:87], v[164:167], v[208:211], v[84:87]
	v_mfma_f32_16x16x32_bf16 v[80:83], v[184:187], v[208:211], v[80:83]
	v_mfma_f32_16x16x32_bf16 v[68:71], v[164:167], v[216:219], v[68:71]
	v_mfma_f32_16x16x32_bf16 v[64:67], v[184:187], v[216:219], v[64:67]
	v_mfma_f32_16x16x32_bf16 v[116:119], v[168:171], v[196:199], v[116:119]
	v_mfma_f32_16x16x32_bf16 v[112:115], v[188:191], v[196:199], v[112:115]
	v_mfma_f32_16x16x32_bf16 v[100:103], v[168:171], v[204:207], v[100:103]
	v_mfma_f32_16x16x32_bf16 v[96:99], v[188:191], v[204:207], v[96:99]
	v_mfma_f32_16x16x32_bf16 v[84:87], v[168:171], v[212:215], v[84:87]
	v_mfma_f32_16x16x32_bf16 v[80:83], v[188:191], v[212:215], v[80:83]
	v_mfma_f32_16x16x32_bf16 v[68:71], v[168:171], v[220:223], v[68:71]
	v_mfma_f32_16x16x32_bf16 v[64:67], v[188:191], v[220:223], v[64:67]
	s_barrier
	s_setprio 0
	ds_read_b128 v[192:195], v181 offset:49152
	ds_read_b128 v[196:199], v181 offset:50176
	ds_read_b128 v[200:203], v181 offset:51200
	ds_read_b128 v[204:207], v181 offset:52224
	ds_read_b128 v[208:211], v181 offset:53248
	ds_read_b128 v[212:215], v181 offset:54272
	ds_read_b128 v[216:219], v181 offset:55296
	ds_read_b128 v[220:223], v181 offset:56320
	s_add_i32 s9, s96, s94
	v_lshl_add_u64 v[172:173], v[172:173], 0, s[74:75]
	s_mov_b32 m0, s9
	s_nop 0
	global_load_lds_dwordx4 v[172:173], off
	s_add_i32 m0, s9, 0x2000
	s_add_u32 s60, s86, 0x80080
	v_lshl_add_u64 v[172:173], v[224:225], 0, s[74:75]
	s_addc_u32 s61, s87, 0
	s_add_i32 s8, s8, s94
	global_load_lds_dwordx4 v[172:173], off
	v_lshl_add_u64 v[172:173], s[60:61], 0, v[130:131]
	s_mov_b32 m0, s8
	s_nop 0
	global_load_lds_dwordx4 v[172:173], off
	v_lshl_add_u64 v[172:173], s[60:61], 0, v[134:135]
	s_add_i32 m0, s8, 0x2000
	s_nop 0
	global_load_lds_dwordx4 v[172:173], off
	v_lshl_add_u64 v[172:173], v[226:227], 0, s[74:75]
	s_mov_b32 m0, s56
	s_nop 0
	global_load_lds_dwordx4 v[172:173], off
	v_lshl_add_u64 v[172:173], v[228:229], 0, s[74:75]
	s_mov_b32 m0, s57
	s_nop 0
	global_load_lds_dwordx4 v[172:173], off
	s_waitcnt vmcnt(8)
	s_waitcnt lgkmcnt(0)
	s_barrier
	s_setprio 1
	s_waitcnt lgkmcnt(0)
	v_mfma_f32_16x16x32_bf16 v[60:63], v[148:151], v[192:195], v[60:63]
	v_mfma_f32_16x16x32_bf16 v[56:59], v[156:159], v[192:195], v[56:59]
	v_mfma_f32_16x16x32_bf16 v[44:47], v[148:151], v[200:203], v[44:47]
	v_mfma_f32_16x16x32_bf16 v[40:43], v[156:159], v[200:203], v[40:43]
	v_mfma_f32_16x16x32_bf16 v[28:31], v[148:151], v[208:211], v[28:31]
	v_mfma_f32_16x16x32_bf16 v[24:27], v[156:159], v[208:211], v[24:27]
	v_mfma_f32_16x16x32_bf16 v[12:15], v[148:151], v[216:219], v[12:15]
	v_mfma_f32_16x16x32_bf16 v[8:11], v[156:159], v[216:219], v[8:11]
	v_mfma_f32_16x16x32_bf16 v[60:63], v[152:155], v[196:199], v[60:63]
	v_mfma_f32_16x16x32_bf16 v[56:59], v[160:163], v[196:199], v[56:59]
	v_mfma_f32_16x16x32_bf16 v[44:47], v[152:155], v[204:207], v[44:47]
	v_mfma_f32_16x16x32_bf16 v[40:43], v[160:163], v[204:207], v[40:43]
	v_mfma_f32_16x16x32_bf16 v[28:31], v[152:155], v[212:215], v[28:31]
	v_mfma_f32_16x16x32_bf16 v[24:27], v[160:163], v[212:215], v[24:27]
	v_mfma_f32_16x16x32_bf16 v[12:15], v[152:155], v[220:223], v[12:15]
	v_mfma_f32_16x16x32_bf16 v[8:11], v[160:163], v[220:223], v[8:11]
	v_mfma_f32_16x16x32_bf16 v[52:55], v[164:167], v[192:195], v[52:55]
	v_mfma_f32_16x16x32_bf16 v[48:51], v[184:187], v[192:195], v[48:51]
	v_mfma_f32_16x16x32_bf16 v[36:39], v[164:167], v[200:203], v[36:39]
	v_mfma_f32_16x16x32_bf16 v[32:35], v[184:187], v[200:203], v[32:35]
	v_mfma_f32_16x16x32_bf16 v[20:23], v[164:167], v[208:211], v[20:23]
	v_mfma_f32_16x16x32_bf16 v[16:19], v[184:187], v[208:211], v[16:19]
	v_mfma_f32_16x16x32_bf16 v[4:7], v[164:167], v[216:219], v[4:7]
	v_mfma_f32_16x16x32_bf16 v[0:3], v[184:187], v[216:219], v[0:3]
	v_mfma_f32_16x16x32_bf16 v[52:55], v[168:171], v[196:199], v[52:55]
	v_mfma_f32_16x16x32_bf16 v[48:51], v[188:191], v[196:199], v[48:51]
	v_mfma_f32_16x16x32_bf16 v[36:39], v[168:171], v[204:207], v[36:39]
	v_mfma_f32_16x16x32_bf16 v[32:35], v[188:191], v[204:207], v[32:35]
	v_mfma_f32_16x16x32_bf16 v[20:23], v[168:171], v[212:215], v[20:23]
	v_mfma_f32_16x16x32_bf16 v[16:19], v[188:191], v[212:215], v[16:19]
	v_mfma_f32_16x16x32_bf16 v[4:7], v[168:171], v[220:223], v[4:7]
	v_mfma_f32_16x16x32_bf16 v[0:3], v[188:191], v[220:223], v[0:3]
	s_barrier
	s_setprio 0
	s_add_i32 s95, s95, 2
	s_add_u32 s84, s84, 0x100
	s_addc_u32 s85, s85, 0
	s_add_u32 vcc_hi, vcc_hi, 0x100
	s_addc_u32 s97, s97, 0
	s_cmp_gt_u32 s95, 29
	s_cbranch_scc0 .LBB0_2128
	s_and_b64 vcc, exec, s[58:59]
	s_cbranch_vccz .LBB0_2131
	s_barrier

.LBB0_2459:
	ds_read_b128 v[148:151], v163
	ds_read_b128 v[152:155], v163 offset:1024
	ds_read_b128 v[168:171], v163 offset:2048
	ds_read_b128 v[172:175], v163 offset:3072
	ds_read_b128 v[176:179], v164
	ds_read_b128 v[180:183], v164 offset:1024
	ds_read_b128 v[184:187], v164 offset:2048
	ds_read_b128 v[188:191], v164 offset:3072
	ds_read_b128 v[192:195], v165
	ds_read_b128 v[196:199], v165 offset:1024
	ds_read_b128 v[200:203], v165 offset:2048
	ds_read_b128 v[204:207], v165 offset:3072
	ds_read_b128 v[208:211], v165 offset:4096
	ds_read_b128 v[212:215], v165 offset:5120
	ds_read_b128 v[216:219], v165 offset:6144
	ds_read_b128 v[220:223], v165 offset:7168
	s_add_u32 s16, s70, 0x100
	s_addc_u32 s17, s71, 0
	s_cmp_eq_u32 s86, 8
	s_cselect_b32 s75, s23, s17
	s_cselect_b32 s74, s22, s16
	s_cselect_b32 s73, s49, s85
	s_cselect_b32 s72, s48, s84
	v_lshl_add_u64 v[156:157], s[70:71], 0, v[140:141]
	s_add_i32 m0, s12, 0xc000
	s_nop 0
	global_load_lds_dwordx4 v[156:157], off
	v_lshl_add_u64 v[156:157], s[70:71], 0, v[142:143]
	s_add_i32 m0, s12, 0xe000
	s_nop 0
	global_load_lds_dwordx4 v[156:157], off
	s_waitcnt vmcnt(8)
	s_waitcnt lgkmcnt(0)
	s_barrier
	s_setprio 1
	s_waitcnt lgkmcnt(0)
	v_mfma_f32_16x16x32_bf16 v[124:127], v[148:151], v[192:195], v[124:127]
	v_mfma_f32_16x16x32_bf16 v[120:123], v[168:171], v[192:195], v[120:123]
	v_mfma_f32_16x16x32_bf16 v[108:111], v[148:151], v[200:203], v[108:111]
	v_mfma_f32_16x16x32_bf16 v[104:107], v[168:171], v[200:203], v[104:107]
	v_mfma_f32_16x16x32_bf16 v[92:95], v[148:151], v[208:211], v[92:95]
	v_mfma_f32_16x16x32_bf16 v[88:91], v[168:171], v[208:211], v[88:91]
	v_mfma_f32_16x16x32_bf16 v[76:79], v[148:151], v[216:219], v[76:79]
	v_mfma_f32_16x16x32_bf16 v[72:75], v[168:171], v[216:219], v[72:75]
	v_mfma_f32_16x16x32_bf16 v[124:127], v[152:155], v[196:199], v[124:127]
	v_mfma_f32_16x16x32_bf16 v[120:123], v[172:175], v[196:199], v[120:123]
	v_mfma_f32_16x16x32_bf16 v[108:111], v[152:155], v[204:207], v[108:111]
	v_mfma_f32_16x16x32_bf16 v[104:107], v[172:175], v[204:207], v[104:107]
	v_mfma_f32_16x16x32_bf16 v[92:95], v[152:155], v[212:215], v[92:95]
	v_mfma_f32_16x16x32_bf16 v[88:91], v[172:175], v[212:215], v[88:91]
	v_mfma_f32_16x16x32_bf16 v[76:79], v[152:155], v[220:223], v[76:79]
	v_mfma_f32_16x16x32_bf16 v[72:75], v[172:175], v[220:223], v[72:75]
	v_mfma_f32_16x16x32_bf16 v[116:119], v[176:179], v[192:195], v[116:119]
	v_mfma_f32_16x16x32_bf16 v[112:115], v[184:187], v[192:195], v[112:115]
	v_mfma_f32_16x16x32_bf16 v[100:103], v[176:179], v[200:203], v[100:103]
	v_mfma_f32_16x16x32_bf16 v[96:99], v[184:187], v[200:203], v[96:99]
	v_mfma_f32_16x16x32_bf16 v[84:87], v[176:179], v[208:211], v[84:87]
	v_mfma_f32_16x16x32_bf16 v[80:83], v[184:187], v[208:211], v[80:83]
	v_mfma_f32_16x16x32_bf16 v[68:71], v[176:179], v[216:219], v[68:71]
	v_mfma_f32_16x16x32_bf16 v[64:67], v[184:187], v[216:219], v[64:67]
	v_mfma_f32_16x16x32_bf16 v[116:119], v[180:183], v[196:199], v[116:119]
	v_mfma_f32_16x16x32_bf16 v[112:115], v[188:191], v[196:199], v[112:115]
	v_mfma_f32_16x16x32_bf16 v[100:103], v[180:183], v[204:207], v[100:103]
	v_mfma_f32_16x16x32_bf16 v[96:99], v[188:191], v[204:207], v[96:99]
	v_mfma_f32_16x16x32_bf16 v[84:87], v[180:183], v[212:215], v[84:87]
	v_mfma_f32_16x16x32_bf16 v[80:83], v[188:191], v[212:215], v[80:83]
	v_mfma_f32_16x16x32_bf16 v[68:71], v[180:183], v[220:223], v[68:71]
	v_mfma_f32_16x16x32_bf16 v[64:67], v[188:191], v[220:223], v[64:67]
	s_barrier
	s_setprio 0
	ds_read_b128 v[192:195], v165 offset:16384
	ds_read_b128 v[196:199], v165 offset:17408
	ds_read_b128 v[200:203], v165 offset:18432
	ds_read_b128 v[204:207], v165 offset:19456
	ds_read_b128 v[208:211], v165 offset:20480
	ds_read_b128 v[212:215], v165 offset:21504
	ds_read_b128 v[216:219], v165 offset:22528
	ds_read_b128 v[220:223], v165 offset:23552
	s_add_i32 s8, s76, s94
	v_lshl_add_u64 v[156:157], s[72:73], 0, v[130:131]
	s_mov_b32 m0, s8
	s_nop 0
	global_load_lds_dwordx4 v[156:157], off
	s_add_i32 m0, s8, 0x2000
	s_add_u32 s60, s72, 0x30000
	v_lshl_add_u64 v[224:225], s[72:73], 0, v[134:135]
	s_addc_u32 s61, s73, 0
	s_add_i32 s8, s77, s94
	global_load_lds_dwordx4 v[224:225], off
	v_lshl_add_u64 v[226:227], s[60:61], 0, v[130:131]
	s_mov_b32 m0, s8
	v_lshl_add_u64 v[228:229], s[74:75], 0, v[132:133]
	global_load_lds_dwordx4 v[226:227], off
	v_lshl_add_u64 v[226:227], s[60:61], 0, v[134:135]
	s_add_i32 m0, s8, 0x2000
	s_nop 0
	global_load_lds_dwordx4 v[226:227], off
	v_lshl_add_u64 v[226:227], s[74:75], 0, v[128:129]
	s_mov_b32 m0, s12
	s_nop 0
	global_load_lds_dwordx4 v[226:227], off
	s_mov_b32 m0, s13
	s_nop 0
	global_load_lds_dwordx4 v[228:229], off
	s_waitcnt vmcnt(8)
	s_waitcnt lgkmcnt(0)
	s_barrier
	s_setprio 1
	s_waitcnt lgkmcnt(0)
	v_mfma_f32_16x16x32_bf16 v[60:63], v[148:151], v[192:195], v[60:63]
	v_mfma_f32_16x16x32_bf16 v[56:59], v[168:171], v[192:195], v[56:59]
	v_mfma_f32_16x16x32_bf16 v[44:47], v[148:151], v[200:203], v[44:47]
	v_mfma_f32_16x16x32_bf16 v[40:43], v[168:171], v[200:203], v[40:43]
	v_mfma_f32_16x16x32_bf16 v[28:31], v[148:151], v[208:211], v[28:31]
	v_mfma_f32_16x16x32_bf16 v[24:27], v[168:171], v[208:211], v[24:27]
	v_mfma_f32_16x16x32_bf16 v[12:15], v[148:151], v[216:219], v[12:15]
	v_mfma_f32_16x16x32_bf16 v[8:11], v[168:171], v[216:219], v[8:11]
	v_mfma_f32_16x16x32_bf16 v[60:63], v[152:155], v[196:199], v[60:63]
	v_mfma_f32_16x16x32_bf16 v[56:59], v[172:175], v[196:199], v[56:59]
	v_mfma_f32_16x16x32_bf16 v[44:47], v[152:155], v[204:207], v[44:47]
	v_mfma_f32_16x16x32_bf16 v[40:43], v[172:175], v[204:207], v[40:43]
	v_mfma_f32_16x16x32_bf16 v[28:31], v[152:155], v[212:215], v[28:31]
	v_mfma_f32_16x16x32_bf16 v[24:27], v[172:175], v[212:215], v[24:27]
	v_mfma_f32_16x16x32_bf16 v[12:15], v[152:155], v[220:223], v[12:15]
	v_mfma_f32_16x16x32_bf16 v[8:11], v[172:175], v[220:223], v[8:11]
	v_mfma_f32_16x16x32_bf16 v[52:55], v[176:179], v[192:195], v[52:55]
	v_mfma_f32_16x16x32_bf16 v[48:51], v[184:187], v[192:195], v[48:51]
	v_mfma_f32_16x16x32_bf16 v[36:39], v[176:179], v[200:203], v[36:39]
	v_mfma_f32_16x16x32_bf16 v[32:35], v[184:187], v[200:203], v[32:35]
	v_mfma_f32_16x16x32_bf16 v[20:23], v[176:179], v[208:211], v[20:23]
	v_mfma_f32_16x16x32_bf16 v[16:19], v[184:187], v[208:211], v[16:19]
	v_mfma_f32_16x16x32_bf16 v[4:7], v[176:179], v[216:219], v[4:7]
	v_mfma_f32_16x16x32_bf16 v[0:3], v[184:187], v[216:219], v[0:3]
	v_mfma_f32_16x16x32_bf16 v[52:55], v[180:183], v[196:199], v[52:55]
	v_mfma_f32_16x16x32_bf16 v[48:51], v[188:191], v[196:199], v[48:51]
	v_mfma_f32_16x16x32_bf16 v[36:39], v[180:183], v[204:207], v[36:39]
	v_mfma_f32_16x16x32_bf16 v[32:35], v[188:191], v[204:207], v[32:35]
	v_mfma_f32_16x16x32_bf16 v[20:23], v[180:183], v[212:215], v[20:23]
	v_mfma_f32_16x16x32_bf16 v[16:19], v[188:191], v[212:215], v[16:19]
	v_mfma_f32_16x16x32_bf16 v[4:7], v[180:183], v[220:223], v[4:7]
	v_mfma_f32_16x16x32_bf16 v[0:3], v[188:191], v[220:223], v[0:3]
	s_barrier
	s_setprio 0
	s_add_i32 s8, 0, 0x18000
	v_add_u32_e32 v136, s8, v159
	ds_read_b128 v[148:151], v136
	ds_read_b128 v[152:155], v136 offset:1024
	ds_read_b128 v[168:171], v136 offset:2048
	ds_read_b128 v[172:175], v136 offset:3072
	s_add_i32 s9, 0, 0x1c000
	v_add_u32_e32 v136, s9, v159
	ds_read_b128 v[176:179], v136
	ds_read_b128 v[180:183], v136 offset:1024
	ds_read_b128 v[184:187], v136 offset:2048
	ds_read_b128 v[188:191], v136 offset:3072
	ds_read_b128 v[192:195], v165 offset:32768
	ds_read_b128 v[196:199], v165 offset:33792
	ds_read_b128 v[200:203], v165 offset:34816
	ds_read_b128 v[204:207], v165 offset:35840
	ds_read_b128 v[208:211], v165 offset:36864
	ds_read_b128 v[212:215], v165 offset:37888
	ds_read_b128 v[216:219], v165 offset:38912
	ds_read_b128 v[220:223], v165 offset:39936
	s_add_u32 s60, s74, 0x60000
	s_addc_u32 s61, s75, 0
	s_mov_b32 m0, s29
	v_lshl_add_u64 v[230:231], s[60:61], 0, v[128:129]
	global_load_lds_dwordx4 v[230:231], off
	v_lshl_add_u64 v[230:231], s[60:61], 0, v[132:133]
	s_mov_b32 m0, s30
	s_nop 0
	global_load_lds_dwordx4 v[230:231], off
	s_waitcnt vmcnt(8)
	s_waitcnt lgkmcnt(0)
	s_barrier
	s_setprio 1
	s_waitcnt lgkmcnt(0)
	v_mfma_f32_16x16x32_bf16 v[124:127], v[148:151], v[192:195], v[124:127]
	v_mfma_f32_16x16x32_bf16 v[120:123], v[168:171], v[192:195], v[120:123]
	v_mfma_f32_16x16x32_bf16 v[108:111], v[148:151], v[200:203], v[108:111]
	v_mfma_f32_16x16x32_bf16 v[104:107], v[168:171], v[200:203], v[104:107]
	v_mfma_f32_16x16x32_bf16 v[92:95], v[148:151], v[208:211], v[92:95]
	v_mfma_f32_16x16x32_bf16 v[88:91], v[168:171], v[208:211], v[88:91]
	v_mfma_f32_16x16x32_bf16 v[76:79], v[148:151], v[216:219], v[76:79]
	v_mfma_f32_16x16x32_bf16 v[72:75], v[168:171], v[216:219], v[72:75]
	v_mfma_f32_16x16x32_bf16 v[124:127], v[152:155], v[196:199], v[124:127]
	v_mfma_f32_16x16x32_bf16 v[120:123], v[172:175], v[196:199], v[120:123]
	v_mfma_f32_16x16x32_bf16 v[108:111], v[152:155], v[204:207], v[108:111]
	v_mfma_f32_16x16x32_bf16 v[104:107], v[172:175], v[204:207], v[104:107]
	v_mfma_f32_16x16x32_bf16 v[92:95], v[152:155], v[212:215], v[92:95]
	v_mfma_f32_16x16x32_bf16 v[88:91], v[172:175], v[212:215], v[88:91]
	v_mfma_f32_16x16x32_bf16 v[76:79], v[152:155], v[220:223], v[76:79]
	v_mfma_f32_16x16x32_bf16 v[72:75], v[172:175], v[220:223], v[72:75]
	v_mfma_f32_16x16x32_bf16 v[116:119], v[176:179], v[192:195], v[116:119]
	v_mfma_f32_16x16x32_bf16 v[112:115], v[184:187], v[192:195], v[112:115]
	v_mfma_f32_16x16x32_bf16 v[100:103], v[176:179], v[200:203], v[100:103]
	v_mfma_f32_16x16x32_bf16 v[96:99], v[184:187], v[200:203], v[96:99]
	v_mfma_f32_16x16x32_bf16 v[84:87], v[176:179], v[208:211], v[84:87]
	v_mfma_f32_16x16x32_bf16 v[80:83], v[184:187], v[208:211], v[80:83]
	v_mfma_f32_16x16x32_bf16 v[68:71], v[176:179], v[216:219], v[68:71]
	v_mfma_f32_16x16x32_bf16 v[64:67], v[184:187], v[216:219], v[64:67]
	v_mfma_f32_16x16x32_bf16 v[116:119], v[180:183], v[196:199], v[116:119]
	v_mfma_f32_16x16x32_bf16 v[112:115], v[188:191], v[196:199], v[112:115]
	v_mfma_f32_16x16x32_bf16 v[100:103], v[180:183], v[204:207], v[100:103]
	v_mfma_f32_16x16x32_bf16 v[96:99], v[188:191], v[204:207], v[96:99]
	v_mfma_f32_16x16x32_bf16 v[84:87], v[180:183], v[212:215], v[84:87]
	v_mfma_f32_16x16x32_bf16 v[80:83], v[188:191], v[212:215], v[80:83]
	v_mfma_f32_16x16x32_bf16 v[68:71], v[180:183], v[220:223], v[68:71]
	v_mfma_f32_16x16x32_bf16 v[64:67], v[188:191], v[220:223], v[64:67]
	s_barrier
	s_setprio 0
	ds_read_b128 v[192:195], v165 offset:49152
	ds_read_b128 v[196:199], v165 offset:50176
	ds_read_b128 v[200:203], v165 offset:51200
	ds_read_b128 v[204:207], v165 offset:52224
	ds_read_b128 v[208:211], v165 offset:53248
	ds_read_b128 v[212:215], v165 offset:54272
	ds_read_b128 v[216:219], v165 offset:55296
	ds_read_b128 v[220:223], v165 offset:56320
	s_add_i32 s8, s8, s94
	v_lshl_add_u64 v[156:157], v[156:157], 0, s[20:21]
	s_mov_b32 m0, s8
	s_nop 0
	global_load_lds_dwordx4 v[156:157], off
	s_add_i32 m0, s8, 0x2000
	s_add_u32 s60, s72, 0x30080
	v_lshl_add_u64 v[156:157], v[224:225], 0, s[20:21]
	s_addc_u32 s61, s73, 0
	s_add_i32 s8, s9, s94
	global_load_lds_dwordx4 v[156:157], off
	v_lshl_add_u64 v[156:157], s[60:61], 0, v[130:131]
	s_mov_b32 m0, s8
	s_nop 0
	global_load_lds_dwordx4 v[156:157], off
	v_lshl_add_u64 v[156:157], s[60:61], 0, v[134:135]
	s_add_i32 m0, s8, 0x2000
	s_nop 0
	global_load_lds_dwordx4 v[156:157], off
	v_lshl_add_u64 v[156:157], v[226:227], 0, s[20:21]
	s_mov_b32 m0, s46
	s_nop 0
	global_load_lds_dwordx4 v[156:157], off
	v_lshl_add_u64 v[156:157], v[228:229], 0, s[20:21]
	s_mov_b32 m0, s56
	s_nop 0
	global_load_lds_dwordx4 v[156:157], off
	s_waitcnt vmcnt(8)
	s_waitcnt lgkmcnt(0)
	s_barrier
	s_setprio 1
	s_waitcnt lgkmcnt(0)
	v_mfma_f32_16x16x32_bf16 v[60:63], v[148:151], v[192:195], v[60:63]
	v_mfma_f32_16x16x32_bf16 v[56:59], v[168:171], v[192:195], v[56:59]
	v_mfma_f32_16x16x32_bf16 v[44:47], v[148:151], v[200:203], v[44:47]
	v_mfma_f32_16x16x32_bf16 v[40:43], v[168:171], v[200:203], v[40:43]
	v_mfma_f32_16x16x32_bf16 v[28:31], v[148:151], v[208:211], v[28:31]
	v_mfma_f32_16x16x32_bf16 v[24:27], v[168:171], v[208:211], v[24:27]
	v_mfma_f32_16x16x32_bf16 v[12:15], v[148:151], v[216:219], v[12:15]
	v_mfma_f32_16x16x32_bf16 v[8:11], v[168:171], v[216:219], v[8:11]
	v_mfma_f32_16x16x32_bf16 v[60:63], v[152:155], v[196:199], v[60:63]
	v_mfma_f32_16x16x32_bf16 v[56:59], v[172:175], v[196:199], v[56:59]
	v_mfma_f32_16x16x32_bf16 v[44:47], v[152:155], v[204:207], v[44:47]
	v_mfma_f32_16x16x32_bf16 v[40:43], v[172:175], v[204:207], v[40:43]
	v_mfma_f32_16x16x32_bf16 v[28:31], v[152:155], v[212:215], v[28:31]
	v_mfma_f32_16x16x32_bf16 v[24:27], v[172:175], v[212:215], v[24:27]
	v_mfma_f32_16x16x32_bf16 v[12:15], v[152:155], v[220:223], v[12:15]
	v_mfma_f32_16x16x32_bf16 v[8:11], v[172:175], v[220:223], v[8:11]
	v_mfma_f32_16x16x32_bf16 v[52:55], v[176:179], v[192:195], v[52:55]
	v_mfma_f32_16x16x32_bf16 v[48:51], v[184:187], v[192:195], v[48:51]
	v_mfma_f32_16x16x32_bf16 v[36:39], v[176:179], v[200:203], v[36:39]
	v_mfma_f32_16x16x32_bf16 v[32:35], v[184:187], v[200:203], v[32:35]
	v_mfma_f32_16x16x32_bf16 v[20:23], v[176:179], v[208:211], v[20:23]
	v_mfma_f32_16x16x32_bf16 v[16:19], v[184:187], v[208:211], v[16:19]
	v_mfma_f32_16x16x32_bf16 v[4:7], v[176:179], v[216:219], v[4:7]
	v_mfma_f32_16x16x32_bf16 v[0:3], v[184:187], v[216:219], v[0:3]
	v_mfma_f32_16x16x32_bf16 v[52:55], v[180:183], v[196:199], v[52:55]
	v_mfma_f32_16x16x32_bf16 v[48:51], v[188:191], v[196:199], v[48:51]
	v_mfma_f32_16x16x32_bf16 v[36:39], v[180:183], v[204:207], v[36:39]
	v_mfma_f32_16x16x32_bf16 v[32:35], v[188:191], v[204:207], v[32:35]
	v_mfma_f32_16x16x32_bf16 v[20:23], v[180:183], v[212:215], v[20:23]
	v_mfma_f32_16x16x32_bf16 v[16:19], v[188:191], v[212:215], v[16:19]
	v_mfma_f32_16x16x32_bf16 v[4:7], v[180:183], v[220:223], v[4:7]
	v_mfma_f32_16x16x32_bf16 v[0:3], v[188:191], v[220:223], v[0:3]
	s_barrier
	s_setprio 0
	s_add_i32 s86, s86, 2
	s_add_u32 s84, s84, 0x100
	s_addc_u32 s85, s85, 0
	s_cmp_gt_u32 s86, 9
	s_mov_b64 s[70:71], s[16:17]
	s_cbranch_scc0 .LBB0_2459
	s_and_b64 vcc, exec, s[58:59]
	s_cbranch_vccz .LBB0_2462
	s_barrier

.LBB0_2535:
	ds_read_b128 v[146:149], v155
	ds_read_b128 v[160:163], v155 offset:1024
	ds_read_b128 v[164:167], v155 offset:2048
	ds_read_b128 v[168:171], v155 offset:3072
	ds_read_b128 v[172:175], v156
	ds_read_b128 v[176:179], v156 offset:1024
	ds_read_b128 v[180:183], v156 offset:2048
	ds_read_b128 v[184:187], v156 offset:3072
	ds_read_b128 v[188:191], v157
	ds_read_b128 v[192:195], v157 offset:1024
	ds_read_b128 v[196:199], v157 offset:2048
	ds_read_b128 v[200:203], v157 offset:3072
	ds_read_b128 v[204:207], v157 offset:4096
	ds_read_b128 v[208:211], v157 offset:5120
	ds_read_b128 v[212:215], v157 offset:6144
	ds_read_b128 v[216:219], v157 offset:7168
	s_add_u32 s16, s68, 0x100
	s_addc_u32 s17, s69, 0
	s_cmp_eq_u32 s80, 4
	s_cselect_b32 s73, s49, s17
	s_cselect_b32 s72, s48, s16
	s_cselect_b32 s71, s43, s79
	s_cselect_b32 s70, s77, s78
	v_lshl_add_u64 v[220:221], s[68:69], 0, v[138:139]
	s_add_i32 m0, s29, 0xc000
	s_nop 0
	global_load_lds_dwordx4 v[220:221], off
	v_lshl_add_u64 v[220:221], s[68:69], 0, v[140:141]
	s_add_i32 m0, s29, 0xe000
	s_nop 0
	global_load_lds_dwordx4 v[220:221], off
	s_waitcnt vmcnt(8)
	s_waitcnt lgkmcnt(0)
	s_barrier
	s_setprio 1
	s_waitcnt lgkmcnt(0)
	v_mfma_f32_16x16x32_bf16 v[124:127], v[146:149], v[188:191], v[124:127]
	v_mfma_f32_16x16x32_bf16 v[120:123], v[164:167], v[188:191], v[120:123]
	v_mfma_f32_16x16x32_bf16 v[108:111], v[146:149], v[196:199], v[108:111]
	v_mfma_f32_16x16x32_bf16 v[104:107], v[164:167], v[196:199], v[104:107]
	v_mfma_f32_16x16x32_bf16 v[92:95], v[146:149], v[204:207], v[92:95]
	v_mfma_f32_16x16x32_bf16 v[88:91], v[164:167], v[204:207], v[88:91]
	v_mfma_f32_16x16x32_bf16 v[76:79], v[146:149], v[212:215], v[76:79]
	v_mfma_f32_16x16x32_bf16 v[72:75], v[164:167], v[212:215], v[72:75]
	v_mfma_f32_16x16x32_bf16 v[124:127], v[160:163], v[192:195], v[124:127]
	v_mfma_f32_16x16x32_bf16 v[120:123], v[168:171], v[192:195], v[120:123]
	v_mfma_f32_16x16x32_bf16 v[108:111], v[160:163], v[200:203], v[108:111]
	v_mfma_f32_16x16x32_bf16 v[104:107], v[168:171], v[200:203], v[104:107]
	v_mfma_f32_16x16x32_bf16 v[92:95], v[160:163], v[208:211], v[92:95]
	v_mfma_f32_16x16x32_bf16 v[88:91], v[168:171], v[208:211], v[88:91]
	v_mfma_f32_16x16x32_bf16 v[76:79], v[160:163], v[216:219], v[76:79]
	v_mfma_f32_16x16x32_bf16 v[72:75], v[168:171], v[216:219], v[72:75]
	v_mfma_f32_16x16x32_bf16 v[116:119], v[172:175], v[188:191], v[116:119]
	v_mfma_f32_16x16x32_bf16 v[112:115], v[180:183], v[188:191], v[112:115]
	v_mfma_f32_16x16x32_bf16 v[100:103], v[172:175], v[196:199], v[100:103]
	v_mfma_f32_16x16x32_bf16 v[96:99], v[180:183], v[196:199], v[96:99]
	v_mfma_f32_16x16x32_bf16 v[84:87], v[172:175], v[204:207], v[84:87]
	v_mfma_f32_16x16x32_bf16 v[80:83], v[180:183], v[204:207], v[80:83]
	v_mfma_f32_16x16x32_bf16 v[68:71], v[172:175], v[212:215], v[68:71]
	v_mfma_f32_16x16x32_bf16 v[64:67], v[180:183], v[212:215], v[64:67]
	v_mfma_f32_16x16x32_bf16 v[116:119], v[176:179], v[192:195], v[116:119]
	v_mfma_f32_16x16x32_bf16 v[112:115], v[184:187], v[192:195], v[112:115]
	v_mfma_f32_16x16x32_bf16 v[100:103], v[176:179], v[200:203], v[100:103]
	v_mfma_f32_16x16x32_bf16 v[96:99], v[184:187], v[200:203], v[96:99]
	v_mfma_f32_16x16x32_bf16 v[84:87], v[176:179], v[208:211], v[84:87]
	v_mfma_f32_16x16x32_bf16 v[80:83], v[184:187], v[208:211], v[80:83]
	v_mfma_f32_16x16x32_bf16 v[68:71], v[176:179], v[216:219], v[68:71]
	v_mfma_f32_16x16x32_bf16 v[64:67], v[184:187], v[216:219], v[64:67]
	s_barrier
	s_setprio 0
	ds_read_b128 v[188:191], v157 offset:16384
	ds_read_b128 v[192:195], v157 offset:17408
	ds_read_b128 v[196:199], v157 offset:18432
	ds_read_b128 v[200:203], v157 offset:19456
	ds_read_b128 v[204:207], v157 offset:20480
	ds_read_b128 v[208:211], v157 offset:21504
	ds_read_b128 v[212:215], v157 offset:22528
	ds_read_b128 v[216:219], v157 offset:23552
	s_add_i32 s8, s67, s94
	v_lshl_add_u64 v[220:221], s[70:71], 0, v[130:131]
	s_mov_b32 m0, s8
	s_nop 0
	global_load_lds_dwordx4 v[220:221], off
	s_add_i32 m0, s8, 0x2000
	s_add_u32 s60, s70, 0x20000
	v_lshl_add_u64 v[222:223], s[70:71], 0, v[134:135]
	s_addc_u32 s61, s71, 0
	s_add_i32 s8, s74, s94
	global_load_lds_dwordx4 v[222:223], off
	v_lshl_add_u64 v[224:225], s[60:61], 0, v[130:131]
	s_mov_b32 m0, s8
	v_lshl_add_u64 v[226:227], s[72:73], 0, v[132:133]
	global_load_lds_dwordx4 v[224:225], off
	v_lshl_add_u64 v[224:225], s[60:61], 0, v[134:135]
	s_add_i32 m0, s8, 0x2000
	s_nop 0
	global_load_lds_dwordx4 v[224:225], off
	v_lshl_add_u64 v[224:225], s[72:73], 0, v[128:129]
	s_mov_b32 m0, s29
	s_nop 0
	global_load_lds_dwordx4 v[224:225], off
	s_mov_b32 m0, s30
	s_nop 0
	global_load_lds_dwordx4 v[226:227], off
	s_waitcnt vmcnt(8)
	s_waitcnt lgkmcnt(0)
	s_barrier
	s_setprio 1
	s_waitcnt lgkmcnt(0)
	v_mfma_f32_16x16x32_bf16 v[60:63], v[146:149], v[188:191], v[60:63]
	v_mfma_f32_16x16x32_bf16 v[56:59], v[164:167], v[188:191], v[56:59]
	v_mfma_f32_16x16x32_bf16 v[44:47], v[146:149], v[196:199], v[44:47]
	v_mfma_f32_16x16x32_bf16 v[40:43], v[164:167], v[196:199], v[40:43]
	v_mfma_f32_16x16x32_bf16 v[28:31], v[146:149], v[204:207], v[28:31]
	v_mfma_f32_16x16x32_bf16 v[24:27], v[164:167], v[204:207], v[24:27]
	v_mfma_f32_16x16x32_bf16 v[12:15], v[146:149], v[212:215], v[12:15]
	v_mfma_f32_16x16x32_bf16 v[8:11], v[164:167], v[212:215], v[8:11]
	v_mfma_f32_16x16x32_bf16 v[60:63], v[160:163], v[192:195], v[60:63]
	v_mfma_f32_16x16x32_bf16 v[56:59], v[168:171], v[192:195], v[56:59]
	v_mfma_f32_16x16x32_bf16 v[44:47], v[160:163], v[200:203], v[44:47]
	v_mfma_f32_16x16x32_bf16 v[40:43], v[168:171], v[200:203], v[40:43]
	v_mfma_f32_16x16x32_bf16 v[28:31], v[160:163], v[208:211], v[28:31]
	v_mfma_f32_16x16x32_bf16 v[24:27], v[168:171], v[208:211], v[24:27]
	v_mfma_f32_16x16x32_bf16 v[12:15], v[160:163], v[216:219], v[12:15]
	v_mfma_f32_16x16x32_bf16 v[8:11], v[168:171], v[216:219], v[8:11]
	v_mfma_f32_16x16x32_bf16 v[52:55], v[172:175], v[188:191], v[52:55]
	v_mfma_f32_16x16x32_bf16 v[48:51], v[180:183], v[188:191], v[48:51]
	v_mfma_f32_16x16x32_bf16 v[36:39], v[172:175], v[196:199], v[36:39]
	v_mfma_f32_16x16x32_bf16 v[32:35], v[180:183], v[196:199], v[32:35]
	v_mfma_f32_16x16x32_bf16 v[20:23], v[172:175], v[204:207], v[20:23]
	v_mfma_f32_16x16x32_bf16 v[16:19], v[180:183], v[204:207], v[16:19]
	v_mfma_f32_16x16x32_bf16 v[4:7], v[172:175], v[212:215], v[4:7]
	v_mfma_f32_16x16x32_bf16 v[0:3], v[180:183], v[212:215], v[0:3]
	v_mfma_f32_16x16x32_bf16 v[52:55], v[176:179], v[192:195], v[52:55]
	v_mfma_f32_16x16x32_bf16 v[48:51], v[184:187], v[192:195], v[48:51]
	v_mfma_f32_16x16x32_bf16 v[36:39], v[176:179], v[200:203], v[36:39]
	v_mfma_f32_16x16x32_bf16 v[32:35], v[184:187], v[200:203], v[32:35]
	v_mfma_f32_16x16x32_bf16 v[20:23], v[176:179], v[208:211], v[20:23]
	v_mfma_f32_16x16x32_bf16 v[16:19], v[184:187], v[208:211], v[16:19]
	v_mfma_f32_16x16x32_bf16 v[4:7], v[176:179], v[216:219], v[4:7]
	v_mfma_f32_16x16x32_bf16 v[0:3], v[184:187], v[216:219], v[0:3]
	s_barrier
	s_setprio 0
	s_add_i32 s8, 0, 0x18000
	v_add_u32_e32 v159, s8, v151
	ds_read_b128 v[146:149], v159
	ds_read_b128 v[160:163], v159 offset:1024
	ds_read_b128 v[164:167], v159 offset:2048
	ds_read_b128 v[168:171], v159 offset:3072
	s_add_i32 s9, 0, 0x1c000
	v_add_u32_e32 v159, s9, v151
	ds_read_b128 v[172:175], v159
	ds_read_b128 v[176:179], v159 offset:1024
	ds_read_b128 v[180:183], v159 offset:2048
	ds_read_b128 v[184:187], v159 offset:3072
	ds_read_b128 v[188:191], v157 offset:32768
	ds_read_b128 v[192:195], v157 offset:33792
	ds_read_b128 v[196:199], v157 offset:34816
	ds_read_b128 v[200:203], v157 offset:35840
	ds_read_b128 v[204:207], v157 offset:36864
	ds_read_b128 v[208:211], v157 offset:37888
	ds_read_b128 v[212:215], v157 offset:38912
	ds_read_b128 v[216:219], v157 offset:39936
	s_add_u32 s60, s72, 0x60000
	s_addc_u32 s61, s73, 0
	s_mov_b32 m0, s34
	v_lshl_add_u64 v[228:229], s[60:61], 0, v[128:129]
	global_load_lds_dwordx4 v[228:229], off
	v_lshl_add_u64 v[228:229], s[60:61], 0, v[132:133]
	s_mov_b32 m0, s35
	s_nop 0
	global_load_lds_dwordx4 v[228:229], off
	s_waitcnt vmcnt(8)
	s_waitcnt lgkmcnt(0)
	s_barrier
	s_setprio 1
	s_waitcnt lgkmcnt(0)
	v_mfma_f32_16x16x32_bf16 v[124:127], v[146:149], v[188:191], v[124:127]
	v_mfma_f32_16x16x32_bf16 v[120:123], v[164:167], v[188:191], v[120:123]
	v_mfma_f32_16x16x32_bf16 v[108:111], v[146:149], v[196:199], v[108:111]
	v_mfma_f32_16x16x32_bf16 v[104:107], v[164:167], v[196:199], v[104:107]
	v_mfma_f32_16x16x32_bf16 v[92:95], v[146:149], v[204:207], v[92:95]
	v_mfma_f32_16x16x32_bf16 v[88:91], v[164:167], v[204:207], v[88:91]
	v_mfma_f32_16x16x32_bf16 v[76:79], v[146:149], v[212:215], v[76:79]
	v_mfma_f32_16x16x32_bf16 v[72:75], v[164:167], v[212:215], v[72:75]
	v_mfma_f32_16x16x32_bf16 v[124:127], v[160:163], v[192:195], v[124:127]
	v_mfma_f32_16x16x32_bf16 v[120:123], v[168:171], v[192:195], v[120:123]
	v_mfma_f32_16x16x32_bf16 v[108:111], v[160:163], v[200:203], v[108:111]
	v_mfma_f32_16x16x32_bf16 v[104:107], v[168:171], v[200:203], v[104:107]
	v_mfma_f32_16x16x32_bf16 v[92:95], v[160:163], v[208:211], v[92:95]
	v_mfma_f32_16x16x32_bf16 v[88:91], v[168:171], v[208:211], v[88:91]
	v_mfma_f32_16x16x32_bf16 v[76:79], v[160:163], v[216:219], v[76:79]
	v_mfma_f32_16x16x32_bf16 v[72:75], v[168:171], v[216:219], v[72:75]
	v_mfma_f32_16x16x32_bf16 v[116:119], v[172:175], v[188:191], v[116:119]
	v_mfma_f32_16x16x32_bf16 v[112:115], v[180:183], v[188:191], v[112:115]
	v_mfma_f32_16x16x32_bf16 v[100:103], v[172:175], v[196:199], v[100:103]
	v_mfma_f32_16x16x32_bf16 v[96:99], v[180:183], v[196:199], v[96:99]
	v_mfma_f32_16x16x32_bf16 v[84:87], v[172:175], v[204:207], v[84:87]
	v_mfma_f32_16x16x32_bf16 v[80:83], v[180:183], v[204:207], v[80:83]
	v_mfma_f32_16x16x32_bf16 v[68:71], v[172:175], v[212:215], v[68:71]
	v_mfma_f32_16x16x32_bf16 v[64:67], v[180:183], v[212:215], v[64:67]
	v_mfma_f32_16x16x32_bf16 v[116:119], v[176:179], v[192:195], v[116:119]
	v_mfma_f32_16x16x32_bf16 v[112:115], v[184:187], v[192:195], v[112:115]
	v_mfma_f32_16x16x32_bf16 v[100:103], v[176:179], v[200:203], v[100:103]
	v_mfma_f32_16x16x32_bf16 v[96:99], v[184:187], v[200:203], v[96:99]
	v_mfma_f32_16x16x32_bf16 v[84:87], v[176:179], v[208:211], v[84:87]
	v_mfma_f32_16x16x32_bf16 v[80:83], v[184:187], v[208:211], v[80:83]
	v_mfma_f32_16x16x32_bf16 v[68:71], v[176:179], v[216:219], v[68:71]
	v_mfma_f32_16x16x32_bf16 v[64:67], v[184:187], v[216:219], v[64:67]
	s_barrier
	s_setprio 0
	ds_read_b128 v[188:191], v157 offset:49152
	ds_read_b128 v[192:195], v157 offset:50176
	ds_read_b128 v[196:199], v157 offset:51200
	ds_read_b128 v[200:203], v157 offset:52224
	ds_read_b128 v[204:207], v157 offset:53248
	ds_read_b128 v[208:211], v157 offset:54272
	ds_read_b128 v[212:215], v157 offset:55296
	ds_read_b128 v[216:219], v157 offset:56320
	s_add_i32 s8, s8, s94
	v_lshl_add_u64 v[220:221], v[220:221], 0, s[22:23]
	s_mov_b32 m0, s8
	s_nop 0
	global_load_lds_dwordx4 v[220:221], off
	s_add_i32 m0, s8, 0x2000
	s_add_u32 s60, s70, 0x20080
	v_lshl_add_u64 v[220:221], v[222:223], 0, s[22:23]
	s_addc_u32 s61, s71, 0
	s_add_i32 s8, s9, s94
	global_load_lds_dwordx4 v[220:221], off
	v_lshl_add_u64 v[220:221], s[60:61], 0, v[130:131]
	s_mov_b32 m0, s8
	s_nop 0
	global_load_lds_dwordx4 v[220:221], off
	v_lshl_add_u64 v[220:221], s[60:61], 0, v[134:135]
	s_add_i32 m0, s8, 0x2000
	s_nop 0
	global_load_lds_dwordx4 v[220:221], off
	v_lshl_add_u64 v[220:221], v[224:225], 0, s[22:23]
	s_mov_b32 m0, s56
	s_nop 0
	global_load_lds_dwordx4 v[220:221], off
	v_lshl_add_u64 v[220:221], v[226:227], 0, s[22:23]
	s_mov_b32 m0, s57
	s_nop 0
	global_load_lds_dwordx4 v[220:221], off
	s_waitcnt vmcnt(8)
	s_waitcnt lgkmcnt(0)
	s_barrier
	s_setprio 1
	s_waitcnt lgkmcnt(0)
	v_mfma_f32_16x16x32_bf16 v[60:63], v[146:149], v[188:191], v[60:63]
	v_mfma_f32_16x16x32_bf16 v[56:59], v[164:167], v[188:191], v[56:59]
	v_mfma_f32_16x16x32_bf16 v[44:47], v[146:149], v[196:199], v[44:47]
	v_mfma_f32_16x16x32_bf16 v[40:43], v[164:167], v[196:199], v[40:43]
	v_mfma_f32_16x16x32_bf16 v[28:31], v[146:149], v[204:207], v[28:31]
	v_mfma_f32_16x16x32_bf16 v[24:27], v[164:167], v[204:207], v[24:27]
	v_mfma_f32_16x16x32_bf16 v[12:15], v[146:149], v[212:215], v[12:15]
	v_mfma_f32_16x16x32_bf16 v[8:11], v[164:167], v[212:215], v[8:11]
	v_mfma_f32_16x16x32_bf16 v[60:63], v[160:163], v[192:195], v[60:63]
	v_mfma_f32_16x16x32_bf16 v[56:59], v[168:171], v[192:195], v[56:59]
	v_mfma_f32_16x16x32_bf16 v[44:47], v[160:163], v[200:203], v[44:47]
	v_mfma_f32_16x16x32_bf16 v[40:43], v[168:171], v[200:203], v[40:43]
	v_mfma_f32_16x16x32_bf16 v[28:31], v[160:163], v[208:211], v[28:31]
	v_mfma_f32_16x16x32_bf16 v[24:27], v[168:171], v[208:211], v[24:27]
	v_mfma_f32_16x16x32_bf16 v[12:15], v[160:163], v[216:219], v[12:15]
	v_mfma_f32_16x16x32_bf16 v[8:11], v[168:171], v[216:219], v[8:11]
	v_mfma_f32_16x16x32_bf16 v[52:55], v[172:175], v[188:191], v[52:55]
	v_mfma_f32_16x16x32_bf16 v[48:51], v[180:183], v[188:191], v[48:51]
	v_mfma_f32_16x16x32_bf16 v[36:39], v[172:175], v[196:199], v[36:39]
	v_mfma_f32_16x16x32_bf16 v[32:35], v[180:183], v[196:199], v[32:35]
	v_mfma_f32_16x16x32_bf16 v[20:23], v[172:175], v[204:207], v[20:23]
	v_mfma_f32_16x16x32_bf16 v[16:19], v[180:183], v[204:207], v[16:19]
	v_mfma_f32_16x16x32_bf16 v[4:7], v[172:175], v[212:215], v[4:7]
	v_mfma_f32_16x16x32_bf16 v[0:3], v[180:183], v[212:215], v[0:3]
	v_mfma_f32_16x16x32_bf16 v[52:55], v[176:179], v[192:195], v[52:55]
	v_mfma_f32_16x16x32_bf16 v[48:51], v[184:187], v[192:195], v[48:51]
	v_mfma_f32_16x16x32_bf16 v[36:39], v[176:179], v[200:203], v[36:39]
	v_mfma_f32_16x16x32_bf16 v[32:35], v[184:187], v[200:203], v[32:35]
	v_mfma_f32_16x16x32_bf16 v[20:23], v[176:179], v[208:211], v[20:23]
	v_mfma_f32_16x16x32_bf16 v[16:19], v[184:187], v[208:211], v[16:19]
	v_mfma_f32_16x16x32_bf16 v[4:7], v[176:179], v[216:219], v[4:7]
	v_mfma_f32_16x16x32_bf16 v[0:3], v[184:187], v[216:219], v[0:3]
	s_barrier
	s_setprio 0
	s_add_i32 s80, s80, 2
	s_add_u32 s78, s78, 0x100
	s_addc_u32 s79, s79, 0
	s_cmp_gt_u32 s80, 5
	s_mov_b64 s[68:69], s[16:17]
	s_cbranch_scc0 .LBB0_2535
	s_and_b64 vcc, exec, s[58:59]
	s_cbranch_vccz .LBB0_2538
	s_barrier

.LBB0_2713:
	ds_read_b128 v[140:143], v149
	ds_read_b128 v[152:155], v149 offset:1024
	ds_read_b128 v[156:159], v149 offset:2048
	ds_read_b128 v[160:163], v149 offset:3072
	ds_read_b128 v[164:167], v150
	ds_read_b128 v[168:171], v150 offset:1024
	ds_read_b128 v[172:175], v150 offset:2048
	ds_read_b128 v[176:179], v150 offset:3072
	ds_read_b128 v[180:183], v151
	ds_read_b128 v[184:187], v151 offset:1024
	ds_read_b128 v[188:191], v151 offset:2048
	ds_read_b128 v[192:195], v151 offset:3072
	ds_read_b128 v[196:199], v151 offset:4096
	ds_read_b128 v[200:203], v151 offset:5120
	ds_read_b128 v[204:207], v151 offset:6144
	ds_read_b128 v[208:211], v151 offset:7168
	s_add_u32 s8, s62, 0xfff80080
	s_addc_u32 s9, s63, -1
	s_cmp_eq_u32 s72, 28
	s_cselect_b32 s67, s43, s9
	s_cselect_b32 s66, s57, s8
	s_cselect_b32 s65, s23, s71
	s_cselect_b32 s64, s69, s70
	v_lshl_add_u64 v[212:213], s[62:63], 0, v[132:133]
	s_add_i32 m0, s12, 0xc000
	s_nop 0
	global_load_lds_dwordx4 v[212:213], off
	v_lshl_add_u64 v[212:213], s[62:63], 0, v[134:135]
	s_add_i32 m0, s12, 0xe000
	s_nop 0
	global_load_lds_dwordx4 v[212:213], off
	s_waitcnt vmcnt(8)
	s_waitcnt lgkmcnt(0)
	s_barrier
	s_setprio 1
	s_waitcnt lgkmcnt(0)
	v_mfma_f32_16x16x32_bf16 v[124:127], v[140:143], v[180:183], v[124:127]
	v_mfma_f32_16x16x32_bf16 v[120:123], v[156:159], v[180:183], v[120:123]
	v_mfma_f32_16x16x32_bf16 v[108:111], v[140:143], v[188:191], v[108:111]
	v_mfma_f32_16x16x32_bf16 v[104:107], v[156:159], v[188:191], v[104:107]
	v_mfma_f32_16x16x32_bf16 v[92:95], v[140:143], v[196:199], v[92:95]
	v_mfma_f32_16x16x32_bf16 v[88:91], v[156:159], v[196:199], v[88:91]
	v_mfma_f32_16x16x32_bf16 v[76:79], v[140:143], v[204:207], v[76:79]
	v_mfma_f32_16x16x32_bf16 v[72:75], v[156:159], v[204:207], v[72:75]
	v_mfma_f32_16x16x32_bf16 v[124:127], v[152:155], v[184:187], v[124:127]
	v_mfma_f32_16x16x32_bf16 v[120:123], v[160:163], v[184:187], v[120:123]
	v_mfma_f32_16x16x32_bf16 v[108:111], v[152:155], v[192:195], v[108:111]
	v_mfma_f32_16x16x32_bf16 v[104:107], v[160:163], v[192:195], v[104:107]
	v_mfma_f32_16x16x32_bf16 v[92:95], v[152:155], v[200:203], v[92:95]
	v_mfma_f32_16x16x32_bf16 v[88:91], v[160:163], v[200:203], v[88:91]
	v_mfma_f32_16x16x32_bf16 v[76:79], v[152:155], v[208:211], v[76:79]
	v_mfma_f32_16x16x32_bf16 v[72:75], v[160:163], v[208:211], v[72:75]
	v_mfma_f32_16x16x32_bf16 v[116:119], v[164:167], v[180:183], v[116:119]
	v_mfma_f32_16x16x32_bf16 v[112:115], v[172:175], v[180:183], v[112:115]
	v_mfma_f32_16x16x32_bf16 v[100:103], v[164:167], v[188:191], v[100:103]
	v_mfma_f32_16x16x32_bf16 v[96:99], v[172:175], v[188:191], v[96:99]
	v_mfma_f32_16x16x32_bf16 v[84:87], v[164:167], v[196:199], v[84:87]
	v_mfma_f32_16x16x32_bf16 v[80:83], v[172:175], v[196:199], v[80:83]
	v_mfma_f32_16x16x32_bf16 v[68:71], v[164:167], v[204:207], v[68:71]
	v_mfma_f32_16x16x32_bf16 v[64:67], v[172:175], v[204:207], v[64:67]
	v_mfma_f32_16x16x32_bf16 v[116:119], v[168:171], v[184:187], v[116:119]
	v_mfma_f32_16x16x32_bf16 v[112:115], v[176:179], v[184:187], v[112:115]
	v_mfma_f32_16x16x32_bf16 v[100:103], v[168:171], v[192:195], v[100:103]
	v_mfma_f32_16x16x32_bf16 v[96:99], v[176:179], v[192:195], v[96:99]
	v_mfma_f32_16x16x32_bf16 v[84:87], v[168:171], v[200:203], v[84:87]
	v_mfma_f32_16x16x32_bf16 v[80:83], v[176:179], v[200:203], v[80:83]
	v_mfma_f32_16x16x32_bf16 v[68:71], v[168:171], v[208:211], v[68:71]
	v_mfma_f32_16x16x32_bf16 v[64:67], v[176:179], v[208:211], v[64:67]
	s_barrier
	s_setprio 0
	ds_read_b128 v[180:183], v151 offset:16384
	ds_read_b128 v[184:187], v151 offset:17408
	ds_read_b128 v[188:191], v151 offset:18432
	ds_read_b128 v[192:195], v151 offset:19456
	ds_read_b128 v[196:199], v151 offset:20480
	ds_read_b128 v[200:203], v151 offset:21504
	ds_read_b128 v[204:207], v151 offset:22528
	ds_read_b128 v[208:211], v151 offset:23552
	s_add_i32 s8, s46, s94
	v_lshl_add_u64 v[212:213], s[64:65], 0, v[128:129]
	s_mov_b32 m0, s8
	s_nop 0
	global_load_lds_dwordx4 v[212:213], off
	s_add_i32 m0, s8, 0x2000
	s_add_u32 s60, s64, 0x80000
	v_lshl_add_u64 v[214:215], s[64:65], 0, v[130:131]
	s_addc_u32 s61, s65, 0
	s_add_i32 s8, s47, s94
	global_load_lds_dwordx4 v[214:215], off
	v_lshl_add_u64 v[216:217], s[60:61], 0, v[128:129]
	s_mov_b32 m0, s8
	v_lshl_add_u64 v[218:219], s[66:67], 0, v[130:131]
	global_load_lds_dwordx4 v[216:217], off
	v_lshl_add_u64 v[216:217], s[60:61], 0, v[130:131]
	s_add_i32 m0, s8, 0x2000
	s_nop 0
	global_load_lds_dwordx4 v[216:217], off
	v_lshl_add_u64 v[216:217], s[66:67], 0, v[128:129]
	s_mov_b32 m0, s12
	s_nop 0
	global_load_lds_dwordx4 v[216:217], off
	s_mov_b32 m0, s13
	s_nop 0
	global_load_lds_dwordx4 v[218:219], off
	s_waitcnt vmcnt(8)
	s_waitcnt lgkmcnt(0)
	s_barrier
	s_setprio 1
	s_waitcnt lgkmcnt(0)
	v_mfma_f32_16x16x32_bf16 v[60:63], v[140:143], v[180:183], v[60:63]
	v_mfma_f32_16x16x32_bf16 v[56:59], v[156:159], v[180:183], v[56:59]
	v_mfma_f32_16x16x32_bf16 v[44:47], v[140:143], v[188:191], v[44:47]
	v_mfma_f32_16x16x32_bf16 v[40:43], v[156:159], v[188:191], v[40:43]
	v_mfma_f32_16x16x32_bf16 v[28:31], v[140:143], v[196:199], v[28:31]
	v_mfma_f32_16x16x32_bf16 v[24:27], v[156:159], v[196:199], v[24:27]
	v_mfma_f32_16x16x32_bf16 v[12:15], v[140:143], v[204:207], v[12:15]
	v_mfma_f32_16x16x32_bf16 v[8:11], v[156:159], v[204:207], v[8:11]
	v_mfma_f32_16x16x32_bf16 v[60:63], v[152:155], v[184:187], v[60:63]
	v_mfma_f32_16x16x32_bf16 v[56:59], v[160:163], v[184:187], v[56:59]
	v_mfma_f32_16x16x32_bf16 v[44:47], v[152:155], v[192:195], v[44:47]
	v_mfma_f32_16x16x32_bf16 v[40:43], v[160:163], v[192:195], v[40:43]
	v_mfma_f32_16x16x32_bf16 v[28:31], v[152:155], v[200:203], v[28:31]
	v_mfma_f32_16x16x32_bf16 v[24:27], v[160:163], v[200:203], v[24:27]
	v_mfma_f32_16x16x32_bf16 v[12:15], v[152:155], v[208:211], v[12:15]
	v_mfma_f32_16x16x32_bf16 v[8:11], v[160:163], v[208:211], v[8:11]
	v_mfma_f32_16x16x32_bf16 v[52:55], v[164:167], v[180:183], v[52:55]
	v_mfma_f32_16x16x32_bf16 v[48:51], v[172:175], v[180:183], v[48:51]
	v_mfma_f32_16x16x32_bf16 v[36:39], v[164:167], v[188:191], v[36:39]
	v_mfma_f32_16x16x32_bf16 v[32:35], v[172:175], v[188:191], v[32:35]
	v_mfma_f32_16x16x32_bf16 v[20:23], v[164:167], v[196:199], v[20:23]
	v_mfma_f32_16x16x32_bf16 v[16:19], v[172:175], v[196:199], v[16:19]
	v_mfma_f32_16x16x32_bf16 v[4:7], v[164:167], v[204:207], v[4:7]
	v_mfma_f32_16x16x32_bf16 v[0:3], v[172:175], v[204:207], v[0:3]
	v_mfma_f32_16x16x32_bf16 v[52:55], v[168:171], v[184:187], v[52:55]
	v_mfma_f32_16x16x32_bf16 v[48:51], v[176:179], v[184:187], v[48:51]
	v_mfma_f32_16x16x32_bf16 v[36:39], v[168:171], v[192:195], v[36:39]
	v_mfma_f32_16x16x32_bf16 v[32:35], v[176:179], v[192:195], v[32:35]
	v_mfma_f32_16x16x32_bf16 v[20:23], v[168:171], v[200:203], v[20:23]
	v_mfma_f32_16x16x32_bf16 v[16:19], v[176:179], v[200:203], v[16:19]
	v_mfma_f32_16x16x32_bf16 v[4:7], v[168:171], v[208:211], v[4:7]
	v_mfma_f32_16x16x32_bf16 v[0:3], v[176:179], v[208:211], v[0:3]
	s_barrier
	s_setprio 0
	s_add_i32 s8, 0, 0x18000
	s_add_i32 s9, 0, 0x1c000
	v_add_u32_e32 v160, s8, v145
	ds_read_b128 v[140:143], v160
	ds_read_b128 v[152:155], v160 offset:1024
	ds_read_b128 v[156:159], v160 offset:2048
	ds_read_b128 v[160:163], v160 offset:3072
	v_add_u32_e32 v176, s9, v145
	ds_read_b128 v[164:167], v176
	ds_read_b128 v[168:171], v176 offset:1024
	ds_read_b128 v[172:175], v176 offset:2048
	ds_read_b128 v[176:179], v176 offset:3072
	ds_read_b128 v[180:183], v151 offset:32768
	ds_read_b128 v[184:187], v151 offset:33792
	ds_read_b128 v[188:191], v151 offset:34816
	ds_read_b128 v[192:195], v151 offset:35840
	ds_read_b128 v[196:199], v151 offset:36864
	ds_read_b128 v[200:203], v151 offset:37888
	ds_read_b128 v[204:207], v151 offset:38912
	ds_read_b128 v[208:211], v151 offset:39936
	s_add_u32 s60, s66, 0x80000
	s_addc_u32 s61, s67, 0
	s_mov_b32 m0, s29
	v_lshl_add_u64 v[220:221], s[60:61], 0, v[128:129]
	global_load_lds_dwordx4 v[220:221], off
	v_lshl_add_u64 v[220:221], s[60:61], 0, v[130:131]
	s_mov_b32 m0, s30
	s_nop 0
	global_load_lds_dwordx4 v[220:221], off
	s_waitcnt vmcnt(8)
	s_waitcnt lgkmcnt(0)
	s_barrier
	s_setprio 1
	s_waitcnt lgkmcnt(0)
	v_mfma_f32_16x16x32_bf16 v[124:127], v[140:143], v[180:183], v[124:127]
	v_mfma_f32_16x16x32_bf16 v[120:123], v[156:159], v[180:183], v[120:123]
	v_mfma_f32_16x16x32_bf16 v[108:111], v[140:143], v[188:191], v[108:111]
	v_mfma_f32_16x16x32_bf16 v[104:107], v[156:159], v[188:191], v[104:107]
	v_mfma_f32_16x16x32_bf16 v[92:95], v[140:143], v[196:199], v[92:95]
	v_mfma_f32_16x16x32_bf16 v[88:91], v[156:159], v[196:199], v[88:91]
	v_mfma_f32_16x16x32_bf16 v[76:79], v[140:143], v[204:207], v[76:79]
	v_mfma_f32_16x16x32_bf16 v[72:75], v[156:159], v[204:207], v[72:75]
	v_mfma_f32_16x16x32_bf16 v[124:127], v[152:155], v[184:187], v[124:127]
	v_mfma_f32_16x16x32_bf16 v[120:123], v[160:163], v[184:187], v[120:123]
	v_mfma_f32_16x16x32_bf16 v[108:111], v[152:155], v[192:195], v[108:111]
	v_mfma_f32_16x16x32_bf16 v[104:107], v[160:163], v[192:195], v[104:107]
	v_mfma_f32_16x16x32_bf16 v[92:95], v[152:155], v[200:203], v[92:95]
	v_mfma_f32_16x16x32_bf16 v[88:91], v[160:163], v[200:203], v[88:91]
	v_mfma_f32_16x16x32_bf16 v[76:79], v[152:155], v[208:211], v[76:79]
	v_mfma_f32_16x16x32_bf16 v[72:75], v[160:163], v[208:211], v[72:75]
	v_mfma_f32_16x16x32_bf16 v[116:119], v[164:167], v[180:183], v[116:119]
	v_mfma_f32_16x16x32_bf16 v[112:115], v[172:175], v[180:183], v[112:115]
	v_mfma_f32_16x16x32_bf16 v[100:103], v[164:167], v[188:191], v[100:103]
	v_mfma_f32_16x16x32_bf16 v[96:99], v[172:175], v[188:191], v[96:99]
	v_mfma_f32_16x16x32_bf16 v[84:87], v[164:167], v[196:199], v[84:87]
	v_mfma_f32_16x16x32_bf16 v[80:83], v[172:175], v[196:199], v[80:83]
	v_mfma_f32_16x16x32_bf16 v[68:71], v[164:167], v[204:207], v[68:71]
	v_mfma_f32_16x16x32_bf16 v[64:67], v[172:175], v[204:207], v[64:67]
	v_mfma_f32_16x16x32_bf16 v[116:119], v[168:171], v[184:187], v[116:119]
	v_mfma_f32_16x16x32_bf16 v[112:115], v[176:179], v[184:187], v[112:115]
	v_mfma_f32_16x16x32_bf16 v[100:103], v[168:171], v[192:195], v[100:103]
	v_mfma_f32_16x16x32_bf16 v[96:99], v[176:179], v[192:195], v[96:99]
	v_mfma_f32_16x16x32_bf16 v[84:87], v[168:171], v[200:203], v[84:87]
	v_mfma_f32_16x16x32_bf16 v[80:83], v[176:179], v[200:203], v[80:83]
	v_mfma_f32_16x16x32_bf16 v[68:71], v[168:171], v[208:211], v[68:71]
	v_mfma_f32_16x16x32_bf16 v[64:67], v[176:179], v[208:211], v[64:67]
	s_barrier
	s_setprio 0
	ds_read_b128 v[180:183], v151 offset:49152
	ds_read_b128 v[184:187], v151 offset:50176
	ds_read_b128 v[188:191], v151 offset:51200
	ds_read_b128 v[192:195], v151 offset:52224
	ds_read_b128 v[196:199], v151 offset:53248
	ds_read_b128 v[200:203], v151 offset:54272
	ds_read_b128 v[204:207], v151 offset:55296
	ds_read_b128 v[208:211], v151 offset:56320
	s_add_i32 s8, s8, s94
	v_lshl_add_u64 v[212:213], v[212:213], 0, s[20:21]
	s_mov_b32 m0, s8
	s_nop 0
	global_load_lds_dwordx4 v[212:213], off
	s_add_i32 m0, s8, 0x2000
	s_add_u32 s60, s64, 0x80080
	v_lshl_add_u64 v[212:213], v[214:215], 0, s[20:21]
	s_addc_u32 s61, s65, 0
	s_add_i32 s8, s9, s94
	global_load_lds_dwordx4 v[212:213], off
	v_lshl_add_u64 v[212:213], s[60:61], 0, v[128:129]
	s_mov_b32 m0, s8
	s_nop 0
	global_load_lds_dwordx4 v[212:213], off
	v_lshl_add_u64 v[212:213], s[60:61], 0, v[130:131]
	s_add_i32 m0, s8, 0x2000
	s_nop 0
	global_load_lds_dwordx4 v[212:213], off
	v_lshl_add_u64 v[212:213], v[216:217], 0, s[20:21]
	s_mov_b32 m0, s34
	s_nop 0
	global_load_lds_dwordx4 v[212:213], off
	v_lshl_add_u64 v[212:213], v[218:219], 0, s[20:21]
	s_mov_b32 m0, s35
	s_nop 0
	global_load_lds_dwordx4 v[212:213], off
	s_waitcnt vmcnt(8)
	s_waitcnt lgkmcnt(0)
	s_barrier
	s_setprio 1
	s_waitcnt lgkmcnt(0)
	v_mfma_f32_16x16x32_bf16 v[60:63], v[140:143], v[180:183], v[60:63]
	v_mfma_f32_16x16x32_bf16 v[56:59], v[156:159], v[180:183], v[56:59]
	v_mfma_f32_16x16x32_bf16 v[44:47], v[140:143], v[188:191], v[44:47]
	v_mfma_f32_16x16x32_bf16 v[40:43], v[156:159], v[188:191], v[40:43]
	v_mfma_f32_16x16x32_bf16 v[28:31], v[140:143], v[196:199], v[28:31]
	v_mfma_f32_16x16x32_bf16 v[24:27], v[156:159], v[196:199], v[24:27]
	v_mfma_f32_16x16x32_bf16 v[12:15], v[140:143], v[204:207], v[12:15]
	v_mfma_f32_16x16x32_bf16 v[8:11], v[156:159], v[204:207], v[8:11]
	v_mfma_f32_16x16x32_bf16 v[60:63], v[152:155], v[184:187], v[60:63]
	v_mfma_f32_16x16x32_bf16 v[56:59], v[160:163], v[184:187], v[56:59]
	v_mfma_f32_16x16x32_bf16 v[44:47], v[152:155], v[192:195], v[44:47]
	v_mfma_f32_16x16x32_bf16 v[40:43], v[160:163], v[192:195], v[40:43]
	v_mfma_f32_16x16x32_bf16 v[28:31], v[152:155], v[200:203], v[28:31]
	v_mfma_f32_16x16x32_bf16 v[24:27], v[160:163], v[200:203], v[24:27]
	v_mfma_f32_16x16x32_bf16 v[12:15], v[152:155], v[208:211], v[12:15]
	v_mfma_f32_16x16x32_bf16 v[8:11], v[160:163], v[208:211], v[8:11]
	v_mfma_f32_16x16x32_bf16 v[52:55], v[164:167], v[180:183], v[52:55]
	v_mfma_f32_16x16x32_bf16 v[48:51], v[172:175], v[180:183], v[48:51]
	v_mfma_f32_16x16x32_bf16 v[36:39], v[164:167], v[188:191], v[36:39]
	v_mfma_f32_16x16x32_bf16 v[32:35], v[172:175], v[188:191], v[32:35]
	v_mfma_f32_16x16x32_bf16 v[20:23], v[164:167], v[196:199], v[20:23]
	v_mfma_f32_16x16x32_bf16 v[16:19], v[172:175], v[196:199], v[16:19]
	v_mfma_f32_16x16x32_bf16 v[4:7], v[164:167], v[204:207], v[4:7]
	v_mfma_f32_16x16x32_bf16 v[0:3], v[172:175], v[204:207], v[0:3]
	v_mfma_f32_16x16x32_bf16 v[52:55], v[168:171], v[184:187], v[52:55]
	v_mfma_f32_16x16x32_bf16 v[48:51], v[176:179], v[184:187], v[48:51]
	v_mfma_f32_16x16x32_bf16 v[36:39], v[168:171], v[192:195], v[36:39]
	v_mfma_f32_16x16x32_bf16 v[32:35], v[176:179], v[192:195], v[32:35]
	v_mfma_f32_16x16x32_bf16 v[20:23], v[168:171], v[200:203], v[20:23]
	v_mfma_f32_16x16x32_bf16 v[16:19], v[176:179], v[200:203], v[16:19]
	v_mfma_f32_16x16x32_bf16 v[4:7], v[168:171], v[208:211], v[4:7]
	v_mfma_f32_16x16x32_bf16 v[0:3], v[176:179], v[208:211], v[0:3]
	s_barrier
	s_setprio 0
	s_add_i32 s72, s72, 2
	s_add_u32 s62, s62, 0x100
	s_addc_u32 s63, s63, 0
	s_add_u32 s70, s70, 0x100
	s_addc_u32 s71, s71, 0
	s_cmp_gt_u32 s72, 29
	s_cbranch_scc0 .LBB0_2713
	s_and_b64 vcc, exec, s[58:59]
	s_cbranch_vccz .LBB0_2716
	s_barrier

.LBB0_2805:
	ds_read_b128 v[146:149], v155
	ds_read_b128 v[160:163], v155 offset:1024
	ds_read_b128 v[164:167], v155 offset:2048
	ds_read_b128 v[168:171], v155 offset:3072
	ds_read_b128 v[172:175], v156
	ds_read_b128 v[176:179], v156 offset:1024
	ds_read_b128 v[180:183], v156 offset:2048
	ds_read_b128 v[184:187], v156 offset:3072
	ds_read_b128 v[188:191], v157
	ds_read_b128 v[192:195], v157 offset:1024
	ds_read_b128 v[196:199], v157 offset:2048
	ds_read_b128 v[200:203], v157 offset:3072
	ds_read_b128 v[204:207], v157 offset:4096
	ds_read_b128 v[208:211], v157 offset:5120
	ds_read_b128 v[212:215], v157 offset:6144
	ds_read_b128 v[216:219], v157 offset:7168
	s_add_u32 s8, s48, 0xfff80080
	s_addc_u32 s9, s49, -1
	s_cmp_eq_u32 s67, 28
	s_cselect_b32 s61, s21, s9
	s_cselect_b32 s60, s43, s8
	s_cselect_b32 s57, s19, s66
	s_cselect_b32 s56, s45, s65
	v_lshl_add_u64 v[220:221], s[48:49], 0, v[138:139]
	s_add_i32 m0, s29, 0xc000
	s_nop 0
	global_load_lds_dwordx4 v[220:221], off
	v_lshl_add_u64 v[220:221], s[48:49], 0, v[140:141]
	s_add_i32 m0, s29, 0xe000
	s_nop 0
	global_load_lds_dwordx4 v[220:221], off
	s_waitcnt vmcnt(8)
	s_waitcnt lgkmcnt(0)
	s_barrier
	s_setprio 1
	s_waitcnt lgkmcnt(0)
	v_mfma_f32_16x16x32_bf16 v[124:127], v[146:149], v[188:191], v[124:127]
	v_mfma_f32_16x16x32_bf16 v[120:123], v[164:167], v[188:191], v[120:123]
	v_mfma_f32_16x16x32_bf16 v[108:111], v[146:149], v[196:199], v[108:111]
	v_mfma_f32_16x16x32_bf16 v[104:107], v[164:167], v[196:199], v[104:107]
	v_mfma_f32_16x16x32_bf16 v[92:95], v[146:149], v[204:207], v[92:95]
	v_mfma_f32_16x16x32_bf16 v[88:91], v[164:167], v[204:207], v[88:91]
	v_mfma_f32_16x16x32_bf16 v[76:79], v[146:149], v[212:215], v[76:79]
	v_mfma_f32_16x16x32_bf16 v[72:75], v[164:167], v[212:215], v[72:75]
	v_mfma_f32_16x16x32_bf16 v[124:127], v[160:163], v[192:195], v[124:127]
	v_mfma_f32_16x16x32_bf16 v[120:123], v[168:171], v[192:195], v[120:123]
	v_mfma_f32_16x16x32_bf16 v[108:111], v[160:163], v[200:203], v[108:111]
	v_mfma_f32_16x16x32_bf16 v[104:107], v[168:171], v[200:203], v[104:107]
	v_mfma_f32_16x16x32_bf16 v[92:95], v[160:163], v[208:211], v[92:95]
	v_mfma_f32_16x16x32_bf16 v[88:91], v[168:171], v[208:211], v[88:91]
	v_mfma_f32_16x16x32_bf16 v[76:79], v[160:163], v[216:219], v[76:79]
	v_mfma_f32_16x16x32_bf16 v[72:75], v[168:171], v[216:219], v[72:75]
	v_mfma_f32_16x16x32_bf16 v[116:119], v[172:175], v[188:191], v[116:119]
	v_mfma_f32_16x16x32_bf16 v[112:115], v[180:183], v[188:191], v[112:115]
	v_mfma_f32_16x16x32_bf16 v[100:103], v[172:175], v[196:199], v[100:103]
	v_mfma_f32_16x16x32_bf16 v[96:99], v[180:183], v[196:199], v[96:99]
	v_mfma_f32_16x16x32_bf16 v[84:87], v[172:175], v[204:207], v[84:87]
	v_mfma_f32_16x16x32_bf16 v[80:83], v[180:183], v[204:207], v[80:83]
	v_mfma_f32_16x16x32_bf16 v[68:71], v[172:175], v[212:215], v[68:71]
	v_mfma_f32_16x16x32_bf16 v[64:67], v[180:183], v[212:215], v[64:67]
	v_mfma_f32_16x16x32_bf16 v[116:119], v[176:179], v[192:195], v[116:119]
	v_mfma_f32_16x16x32_bf16 v[112:115], v[184:187], v[192:195], v[112:115]
	v_mfma_f32_16x16x32_bf16 v[100:103], v[176:179], v[200:203], v[100:103]
	v_mfma_f32_16x16x32_bf16 v[96:99], v[184:187], v[200:203], v[96:99]
	v_mfma_f32_16x16x32_bf16 v[84:87], v[176:179], v[208:211], v[84:87]
	v_mfma_f32_16x16x32_bf16 v[80:83], v[184:187], v[208:211], v[80:83]
	v_mfma_f32_16x16x32_bf16 v[68:71], v[176:179], v[216:219], v[68:71]
	v_mfma_f32_16x16x32_bf16 v[64:67], v[184:187], v[216:219], v[64:67]
	s_barrier
	s_setprio 0
	ds_read_b128 v[188:191], v157 offset:16384
	ds_read_b128 v[192:195], v157 offset:17408
	ds_read_b128 v[196:199], v157 offset:18432
	ds_read_b128 v[200:203], v157 offset:19456
	ds_read_b128 v[204:207], v157 offset:20480
	ds_read_b128 v[208:211], v157 offset:21504
	ds_read_b128 v[212:215], v157 offset:22528
	ds_read_b128 v[216:219], v157 offset:23552
	s_add_i32 s8, s63, s94
	v_lshl_add_u64 v[220:221], s[56:57], 0, v[130:131]
	s_mov_b32 m0, s8
	s_nop 0
	global_load_lds_dwordx4 v[220:221], off
	s_add_i32 m0, s8, 0x2000
	s_add_u32 s68, s56, 0x80000
	v_lshl_add_u64 v[222:223], s[56:57], 0, v[134:135]
	s_addc_u32 s69, s57, 0
	s_add_i32 s8, s64, s94
	global_load_lds_dwordx4 v[222:223], off
	v_lshl_add_u64 v[224:225], s[68:69], 0, v[130:131]
	s_mov_b32 m0, s8
	v_lshl_add_u64 v[226:227], s[60:61], 0, v[132:133]
	global_load_lds_dwordx4 v[224:225], off
	v_lshl_add_u64 v[224:225], s[68:69], 0, v[134:135]
	s_add_i32 m0, s8, 0x2000
	s_nop 0
	global_load_lds_dwordx4 v[224:225], off
	v_lshl_add_u64 v[224:225], s[60:61], 0, v[128:129]
	s_mov_b32 m0, s29
	s_nop 0
	global_load_lds_dwordx4 v[224:225], off
	s_mov_b32 m0, s30
	s_nop 0
	global_load_lds_dwordx4 v[226:227], off
	s_waitcnt vmcnt(8)
	s_waitcnt lgkmcnt(0)
	s_barrier
	s_setprio 1
	s_waitcnt lgkmcnt(0)
	v_mfma_f32_16x16x32_bf16 v[60:63], v[146:149], v[188:191], v[60:63]
	v_mfma_f32_16x16x32_bf16 v[56:59], v[164:167], v[188:191], v[56:59]
	v_mfma_f32_16x16x32_bf16 v[44:47], v[146:149], v[196:199], v[44:47]
	v_mfma_f32_16x16x32_bf16 v[40:43], v[164:167], v[196:199], v[40:43]
	v_mfma_f32_16x16x32_bf16 v[28:31], v[146:149], v[204:207], v[28:31]
	v_mfma_f32_16x16x32_bf16 v[24:27], v[164:167], v[204:207], v[24:27]
	v_mfma_f32_16x16x32_bf16 v[12:15], v[146:149], v[212:215], v[12:15]
	v_mfma_f32_16x16x32_bf16 v[8:11], v[164:167], v[212:215], v[8:11]
	v_mfma_f32_16x16x32_bf16 v[60:63], v[160:163], v[192:195], v[60:63]
	v_mfma_f32_16x16x32_bf16 v[56:59], v[168:171], v[192:195], v[56:59]
	v_mfma_f32_16x16x32_bf16 v[44:47], v[160:163], v[200:203], v[44:47]
	v_mfma_f32_16x16x32_bf16 v[40:43], v[168:171], v[200:203], v[40:43]
	v_mfma_f32_16x16x32_bf16 v[28:31], v[160:163], v[208:211], v[28:31]
	v_mfma_f32_16x16x32_bf16 v[24:27], v[168:171], v[208:211], v[24:27]
	v_mfma_f32_16x16x32_bf16 v[12:15], v[160:163], v[216:219], v[12:15]
	v_mfma_f32_16x16x32_bf16 v[8:11], v[168:171], v[216:219], v[8:11]
	v_mfma_f32_16x16x32_bf16 v[52:55], v[172:175], v[188:191], v[52:55]
	v_mfma_f32_16x16x32_bf16 v[48:51], v[180:183], v[188:191], v[48:51]
	v_mfma_f32_16x16x32_bf16 v[36:39], v[172:175], v[196:199], v[36:39]
	v_mfma_f32_16x16x32_bf16 v[32:35], v[180:183], v[196:199], v[32:35]
	v_mfma_f32_16x16x32_bf16 v[20:23], v[172:175], v[204:207], v[20:23]
	v_mfma_f32_16x16x32_bf16 v[16:19], v[180:183], v[204:207], v[16:19]
	v_mfma_f32_16x16x32_bf16 v[4:7], v[172:175], v[212:215], v[4:7]
	v_mfma_f32_16x16x32_bf16 v[0:3], v[180:183], v[212:215], v[0:3]
	v_mfma_f32_16x16x32_bf16 v[52:55], v[176:179], v[192:195], v[52:55]
	v_mfma_f32_16x16x32_bf16 v[48:51], v[184:187], v[192:195], v[48:51]
	v_mfma_f32_16x16x32_bf16 v[36:39], v[176:179], v[200:203], v[36:39]
	v_mfma_f32_16x16x32_bf16 v[32:35], v[184:187], v[200:203], v[32:35]
	v_mfma_f32_16x16x32_bf16 v[20:23], v[176:179], v[208:211], v[20:23]
	v_mfma_f32_16x16x32_bf16 v[16:19], v[184:187], v[208:211], v[16:19]
	v_mfma_f32_16x16x32_bf16 v[4:7], v[176:179], v[216:219], v[4:7]
	v_mfma_f32_16x16x32_bf16 v[0:3], v[184:187], v[216:219], v[0:3]
	s_barrier
	s_setprio 0
	s_add_i32 s8, 0, 0x18000
	v_add_u32_e32 v159, s8, v151
	ds_read_b128 v[146:149], v159
	ds_read_b128 v[160:163], v159 offset:1024
	ds_read_b128 v[164:167], v159 offset:2048
	ds_read_b128 v[168:171], v159 offset:3072
	s_add_i32 s9, 0, 0x1c000
	v_add_u32_e32 v159, s9, v151
	ds_read_b128 v[172:175], v159
	ds_read_b128 v[176:179], v159 offset:1024
	ds_read_b128 v[180:183], v159 offset:2048
	ds_read_b128 v[184:187], v159 offset:3072
	ds_read_b128 v[188:191], v157 offset:32768
	ds_read_b128 v[192:195], v157 offset:33792
	ds_read_b128 v[196:199], v157 offset:34816
	ds_read_b128 v[200:203], v157 offset:35840
	ds_read_b128 v[204:207], v157 offset:36864
	ds_read_b128 v[208:211], v157 offset:37888
	ds_read_b128 v[212:215], v157 offset:38912
	ds_read_b128 v[216:219], v157 offset:39936
	s_add_u32 s60, s60, 0x80000
	s_addc_u32 s61, s61, 0
	s_mov_b32 m0, s34
	v_lshl_add_u64 v[228:229], s[60:61], 0, v[128:129]
	global_load_lds_dwordx4 v[228:229], off
	v_lshl_add_u64 v[228:229], s[60:61], 0, v[132:133]
	s_mov_b32 m0, s35
	s_nop 0
	global_load_lds_dwordx4 v[228:229], off
	s_waitcnt vmcnt(8)
	s_waitcnt lgkmcnt(0)
	s_barrier
	s_setprio 1
	s_waitcnt lgkmcnt(0)
	v_mfma_f32_16x16x32_bf16 v[124:127], v[146:149], v[188:191], v[124:127]
	v_mfma_f32_16x16x32_bf16 v[120:123], v[164:167], v[188:191], v[120:123]
	v_mfma_f32_16x16x32_bf16 v[108:111], v[146:149], v[196:199], v[108:111]
	v_mfma_f32_16x16x32_bf16 v[104:107], v[164:167], v[196:199], v[104:107]
	v_mfma_f32_16x16x32_bf16 v[92:95], v[146:149], v[204:207], v[92:95]
	v_mfma_f32_16x16x32_bf16 v[88:91], v[164:167], v[204:207], v[88:91]
	v_mfma_f32_16x16x32_bf16 v[76:79], v[146:149], v[212:215], v[76:79]
	v_mfma_f32_16x16x32_bf16 v[72:75], v[164:167], v[212:215], v[72:75]
	v_mfma_f32_16x16x32_bf16 v[124:127], v[160:163], v[192:195], v[124:127]
	v_mfma_f32_16x16x32_bf16 v[120:123], v[168:171], v[192:195], v[120:123]
	v_mfma_f32_16x16x32_bf16 v[108:111], v[160:163], v[200:203], v[108:111]
	v_mfma_f32_16x16x32_bf16 v[104:107], v[168:171], v[200:203], v[104:107]
	v_mfma_f32_16x16x32_bf16 v[92:95], v[160:163], v[208:211], v[92:95]
	v_mfma_f32_16x16x32_bf16 v[88:91], v[168:171], v[208:211], v[88:91]
	v_mfma_f32_16x16x32_bf16 v[76:79], v[160:163], v[216:219], v[76:79]
	v_mfma_f32_16x16x32_bf16 v[72:75], v[168:171], v[216:219], v[72:75]
	v_mfma_f32_16x16x32_bf16 v[116:119], v[172:175], v[188:191], v[116:119]
	v_mfma_f32_16x16x32_bf16 v[112:115], v[180:183], v[188:191], v[112:115]
	v_mfma_f32_16x16x32_bf16 v[100:103], v[172:175], v[196:199], v[100:103]
	v_mfma_f32_16x16x32_bf16 v[96:99], v[180:183], v[196:199], v[96:99]
	v_mfma_f32_16x16x32_bf16 v[84:87], v[172:175], v[204:207], v[84:87]
	v_mfma_f32_16x16x32_bf16 v[80:83], v[180:183], v[204:207], v[80:83]
	v_mfma_f32_16x16x32_bf16 v[68:71], v[172:175], v[212:215], v[68:71]
	v_mfma_f32_16x16x32_bf16 v[64:67], v[180:183], v[212:215], v[64:67]
	v_mfma_f32_16x16x32_bf16 v[116:119], v[176:179], v[192:195], v[116:119]
	v_mfma_f32_16x16x32_bf16 v[112:115], v[184:187], v[192:195], v[112:115]
	v_mfma_f32_16x16x32_bf16 v[100:103], v[176:179], v[200:203], v[100:103]
	v_mfma_f32_16x16x32_bf16 v[96:99], v[184:187], v[200:203], v[96:99]
	v_mfma_f32_16x16x32_bf16 v[84:87], v[176:179], v[208:211], v[84:87]
	v_mfma_f32_16x16x32_bf16 v[80:83], v[184:187], v[208:211], v[80:83]
	v_mfma_f32_16x16x32_bf16 v[68:71], v[176:179], v[216:219], v[68:71]
	v_mfma_f32_16x16x32_bf16 v[64:67], v[184:187], v[216:219], v[64:67]
	s_barrier
	s_setprio 0
	ds_read_b128 v[188:191], v157 offset:49152
	ds_read_b128 v[192:195], v157 offset:50176
	ds_read_b128 v[196:199], v157 offset:51200
	ds_read_b128 v[200:203], v157 offset:52224
	ds_read_b128 v[204:207], v157 offset:53248
	ds_read_b128 v[208:211], v157 offset:54272
	ds_read_b128 v[212:215], v157 offset:55296
	ds_read_b128 v[216:219], v157 offset:56320
	s_add_i32 s8, s8, s94
	v_lshl_add_u64 v[220:221], v[220:221], 0, s[16:17]
	s_mov_b32 m0, s8
	s_nop 0
	global_load_lds_dwordx4 v[220:221], off
	s_add_i32 m0, s8, 0x2000
	s_add_u32 s56, s56, 0x80080
	v_lshl_add_u64 v[220:221], v[222:223], 0, s[16:17]
	s_addc_u32 s57, s57, 0
	s_add_i32 s8, s9, s94
	global_load_lds_dwordx4 v[220:221], off
	v_lshl_add_u64 v[220:221], s[56:57], 0, v[130:131]
	s_mov_b32 m0, s8
	s_nop 0
	global_load_lds_dwordx4 v[220:221], off
	v_lshl_add_u64 v[220:221], s[56:57], 0, v[134:135]
	s_add_i32 m0, s8, 0x2000
	s_nop 0
	global_load_lds_dwordx4 v[220:221], off
	v_lshl_add_u64 v[220:221], v[224:225], 0, s[16:17]
	s_mov_b32 m0, s47
	s_nop 0
	global_load_lds_dwordx4 v[220:221], off
	v_lshl_add_u64 v[220:221], v[226:227], 0, s[16:17]
	s_mov_b32 m0, s62
	s_nop 0
	global_load_lds_dwordx4 v[220:221], off
	s_waitcnt vmcnt(8)
	s_waitcnt lgkmcnt(0)
	s_barrier
	s_setprio 1
	s_waitcnt lgkmcnt(0)
	v_mfma_f32_16x16x32_bf16 v[60:63], v[146:149], v[188:191], v[60:63]
	v_mfma_f32_16x16x32_bf16 v[56:59], v[164:167], v[188:191], v[56:59]
	v_mfma_f32_16x16x32_bf16 v[44:47], v[146:149], v[196:199], v[44:47]
	v_mfma_f32_16x16x32_bf16 v[40:43], v[164:167], v[196:199], v[40:43]
	v_mfma_f32_16x16x32_bf16 v[28:31], v[146:149], v[204:207], v[28:31]
	v_mfma_f32_16x16x32_bf16 v[24:27], v[164:167], v[204:207], v[24:27]
	v_mfma_f32_16x16x32_bf16 v[12:15], v[146:149], v[212:215], v[12:15]
	v_mfma_f32_16x16x32_bf16 v[8:11], v[164:167], v[212:215], v[8:11]
	v_mfma_f32_16x16x32_bf16 v[60:63], v[160:163], v[192:195], v[60:63]
	v_mfma_f32_16x16x32_bf16 v[56:59], v[168:171], v[192:195], v[56:59]
	v_mfma_f32_16x16x32_bf16 v[44:47], v[160:163], v[200:203], v[44:47]
	v_mfma_f32_16x16x32_bf16 v[40:43], v[168:171], v[200:203], v[40:43]
	v_mfma_f32_16x16x32_bf16 v[28:31], v[160:163], v[208:211], v[28:31]
	v_mfma_f32_16x16x32_bf16 v[24:27], v[168:171], v[208:211], v[24:27]
	v_mfma_f32_16x16x32_bf16 v[12:15], v[160:163], v[216:219], v[12:15]
	v_mfma_f32_16x16x32_bf16 v[8:11], v[168:171], v[216:219], v[8:11]
	v_mfma_f32_16x16x32_bf16 v[52:55], v[172:175], v[188:191], v[52:55]
	v_mfma_f32_16x16x32_bf16 v[48:51], v[180:183], v[188:191], v[48:51]
	v_mfma_f32_16x16x32_bf16 v[36:39], v[172:175], v[196:199], v[36:39]
	v_mfma_f32_16x16x32_bf16 v[32:35], v[180:183], v[196:199], v[32:35]
	v_mfma_f32_16x16x32_bf16 v[20:23], v[172:175], v[204:207], v[20:23]
	v_mfma_f32_16x16x32_bf16 v[16:19], v[180:183], v[204:207], v[16:19]
	v_mfma_f32_16x16x32_bf16 v[4:7], v[172:175], v[212:215], v[4:7]
	v_mfma_f32_16x16x32_bf16 v[0:3], v[180:183], v[212:215], v[0:3]
	v_mfma_f32_16x16x32_bf16 v[52:55], v[176:179], v[192:195], v[52:55]
	v_mfma_f32_16x16x32_bf16 v[48:51], v[184:187], v[192:195], v[48:51]
	v_mfma_f32_16x16x32_bf16 v[36:39], v[176:179], v[200:203], v[36:39]
	v_mfma_f32_16x16x32_bf16 v[32:35], v[184:187], v[200:203], v[32:35]
	v_mfma_f32_16x16x32_bf16 v[20:23], v[176:179], v[208:211], v[20:23]
	v_mfma_f32_16x16x32_bf16 v[16:19], v[184:187], v[208:211], v[16:19]
	v_mfma_f32_16x16x32_bf16 v[4:7], v[176:179], v[216:219], v[4:7]
	v_mfma_f32_16x16x32_bf16 v[0:3], v[184:187], v[216:219], v[0:3]
	s_barrier
	s_setprio 0
	s_add_i32 s67, s67, 2
	s_add_u32 s48, s48, 0x100
	s_addc_u32 s49, s49, 0
	s_add_u32 s65, s65, 0x100
	s_addc_u32 s66, s66, 0
	s_cmp_gt_u32 s67, 29
	s_cbranch_scc0 .LBB0_2805
	s_and_b64 vcc, exec, s[58:59]
	s_cbranch_vccz .LBB0_2808
	s_barrier

.LBB0_2917:
	ds_read_b128 v[140:143], v149
	ds_read_b128 v[152:155], v149 offset:1024
	ds_read_b128 v[156:159], v149 offset:2048
	ds_read_b128 v[160:163], v149 offset:3072
	ds_read_b128 v[164:167], v150
	ds_read_b128 v[168:171], v150 offset:1024
	ds_read_b128 v[172:175], v150 offset:2048
	ds_read_b128 v[176:179], v150 offset:3072
	ds_read_b128 v[180:183], v151
	ds_read_b128 v[184:187], v151 offset:1024
	ds_read_b128 v[188:191], v151 offset:2048
	ds_read_b128 v[192:195], v151 offset:3072
	ds_read_b128 v[196:199], v151 offset:4096
	ds_read_b128 v[200:203], v151 offset:5120
	ds_read_b128 v[204:207], v151 offset:6144
	ds_read_b128 v[208:211], v151 offset:7168
	s_add_u32 s42, s40, 0xffe00080
	s_addc_u32 s43, s41, -1
	s_cmpk_eq_i32 s64, 0x7c
	s_cselect_b32 s45, s21, s43
	s_cselect_b32 s44, s39, s42
	s_cselect_b32 s43, s19, s63
	s_cselect_b32 s42, s61, s62
	v_lshl_add_u64 v[212:213], s[40:41], 0, v[132:133]
	s_add_i32 m0, s29, 0xc000
	s_nop 0
	global_load_lds_dwordx4 v[212:213], off
	v_lshl_add_u64 v[212:213], s[40:41], 0, v[134:135]
	s_add_i32 m0, s29, 0xe000
	s_nop 0
	global_load_lds_dwordx4 v[212:213], off
	s_waitcnt vmcnt(8)
	s_waitcnt lgkmcnt(0)
	s_barrier
	s_setprio 1
	s_waitcnt lgkmcnt(0)
	v_mfma_f32_16x16x32_bf16 v[124:127], v[140:143], v[180:183], v[124:127]
	v_mfma_f32_16x16x32_bf16 v[120:123], v[156:159], v[180:183], v[120:123]
	v_mfma_f32_16x16x32_bf16 v[108:111], v[140:143], v[188:191], v[108:111]
	v_mfma_f32_16x16x32_bf16 v[104:107], v[156:159], v[188:191], v[104:107]
	v_mfma_f32_16x16x32_bf16 v[92:95], v[140:143], v[196:199], v[92:95]
	v_mfma_f32_16x16x32_bf16 v[88:91], v[156:159], v[196:199], v[88:91]
	v_mfma_f32_16x16x32_bf16 v[76:79], v[140:143], v[204:207], v[76:79]
	v_mfma_f32_16x16x32_bf16 v[72:75], v[156:159], v[204:207], v[72:75]
	v_mfma_f32_16x16x32_bf16 v[124:127], v[152:155], v[184:187], v[124:127]
	v_mfma_f32_16x16x32_bf16 v[120:123], v[160:163], v[184:187], v[120:123]
	v_mfma_f32_16x16x32_bf16 v[108:111], v[152:155], v[192:195], v[108:111]
	v_mfma_f32_16x16x32_bf16 v[104:107], v[160:163], v[192:195], v[104:107]
	v_mfma_f32_16x16x32_bf16 v[92:95], v[152:155], v[200:203], v[92:95]
	v_mfma_f32_16x16x32_bf16 v[88:91], v[160:163], v[200:203], v[88:91]
	v_mfma_f32_16x16x32_bf16 v[76:79], v[152:155], v[208:211], v[76:79]
	v_mfma_f32_16x16x32_bf16 v[72:75], v[160:163], v[208:211], v[72:75]
	v_mfma_f32_16x16x32_bf16 v[116:119], v[164:167], v[180:183], v[116:119]
	v_mfma_f32_16x16x32_bf16 v[112:115], v[172:175], v[180:183], v[112:115]
	v_mfma_f32_16x16x32_bf16 v[100:103], v[164:167], v[188:191], v[100:103]
	v_mfma_f32_16x16x32_bf16 v[96:99], v[172:175], v[188:191], v[96:99]
	v_mfma_f32_16x16x32_bf16 v[84:87], v[164:167], v[196:199], v[84:87]
	v_mfma_f32_16x16x32_bf16 v[80:83], v[172:175], v[196:199], v[80:83]
	v_mfma_f32_16x16x32_bf16 v[68:71], v[164:167], v[204:207], v[68:71]
	v_mfma_f32_16x16x32_bf16 v[64:67], v[172:175], v[204:207], v[64:67]
	v_mfma_f32_16x16x32_bf16 v[116:119], v[168:171], v[184:187], v[116:119]
	v_mfma_f32_16x16x32_bf16 v[112:115], v[176:179], v[184:187], v[112:115]
	v_mfma_f32_16x16x32_bf16 v[100:103], v[168:171], v[192:195], v[100:103]
	v_mfma_f32_16x16x32_bf16 v[96:99], v[176:179], v[192:195], v[96:99]
	v_mfma_f32_16x16x32_bf16 v[84:87], v[168:171], v[200:203], v[84:87]
	v_mfma_f32_16x16x32_bf16 v[80:83], v[176:179], v[200:203], v[80:83]
	v_mfma_f32_16x16x32_bf16 v[68:71], v[168:171], v[208:211], v[68:71]
	v_mfma_f32_16x16x32_bf16 v[64:67], v[176:179], v[208:211], v[64:67]
	s_barrier
	s_setprio 0
	ds_read_b128 v[180:183], v151 offset:16384
	ds_read_b128 v[184:187], v151 offset:17408
	ds_read_b128 v[188:191], v151 offset:18432
	ds_read_b128 v[192:195], v151 offset:19456
	ds_read_b128 v[196:199], v151 offset:20480
	ds_read_b128 v[200:203], v151 offset:21504
	ds_read_b128 v[204:207], v151 offset:22528
	ds_read_b128 v[208:211], v151 offset:23552
	s_add_i32 s65, s56, s94
	v_lshl_add_u64 v[212:213], s[42:43], 0, v[128:129]
	s_mov_b32 m0, s65
	s_nop 0
	global_load_lds_dwordx4 v[212:213], off
	s_add_i32 m0, s65, 0x2000
	s_add_u32 s66, s42, 0x200000
	v_lshl_add_u64 v[214:215], s[42:43], 0, v[130:131]
	s_addc_u32 s67, s43, 0
	s_add_i32 s65, s57, s94
	global_load_lds_dwordx4 v[214:215], off
	v_lshl_add_u64 v[216:217], s[66:67], 0, v[128:129]
	s_mov_b32 m0, s65
	v_lshl_add_u64 v[218:219], s[44:45], 0, v[130:131]
	global_load_lds_dwordx4 v[216:217], off
	v_lshl_add_u64 v[216:217], s[66:67], 0, v[130:131]
	s_add_i32 m0, s65, 0x2000
	s_nop 0
	global_load_lds_dwordx4 v[216:217], off
	v_lshl_add_u64 v[216:217], s[44:45], 0, v[128:129]
	s_mov_b32 m0, s29
	s_nop 0
	global_load_lds_dwordx4 v[216:217], off
	s_mov_b32 m0, s30
	s_nop 0
	global_load_lds_dwordx4 v[218:219], off
	s_waitcnt vmcnt(8)
	s_waitcnt lgkmcnt(0)
	s_barrier
	s_setprio 1
	s_waitcnt lgkmcnt(0)
	v_mfma_f32_16x16x32_bf16 v[60:63], v[140:143], v[180:183], v[60:63]
	v_mfma_f32_16x16x32_bf16 v[56:59], v[156:159], v[180:183], v[56:59]
	v_mfma_f32_16x16x32_bf16 v[44:47], v[140:143], v[188:191], v[44:47]
	v_mfma_f32_16x16x32_bf16 v[40:43], v[156:159], v[188:191], v[40:43]
	v_mfma_f32_16x16x32_bf16 v[28:31], v[140:143], v[196:199], v[28:31]
	v_mfma_f32_16x16x32_bf16 v[24:27], v[156:159], v[196:199], v[24:27]
	v_mfma_f32_16x16x32_bf16 v[12:15], v[140:143], v[204:207], v[12:15]
	v_mfma_f32_16x16x32_bf16 v[8:11], v[156:159], v[204:207], v[8:11]
	v_mfma_f32_16x16x32_bf16 v[60:63], v[152:155], v[184:187], v[60:63]
	v_mfma_f32_16x16x32_bf16 v[56:59], v[160:163], v[184:187], v[56:59]
	v_mfma_f32_16x16x32_bf16 v[44:47], v[152:155], v[192:195], v[44:47]
	v_mfma_f32_16x16x32_bf16 v[40:43], v[160:163], v[192:195], v[40:43]
	v_mfma_f32_16x16x32_bf16 v[28:31], v[152:155], v[200:203], v[28:31]
	v_mfma_f32_16x16x32_bf16 v[24:27], v[160:163], v[200:203], v[24:27]
	v_mfma_f32_16x16x32_bf16 v[12:15], v[152:155], v[208:211], v[12:15]
	v_mfma_f32_16x16x32_bf16 v[8:11], v[160:163], v[208:211], v[8:11]
	v_mfma_f32_16x16x32_bf16 v[52:55], v[164:167], v[180:183], v[52:55]
	v_mfma_f32_16x16x32_bf16 v[48:51], v[172:175], v[180:183], v[48:51]
	v_mfma_f32_16x16x32_bf16 v[36:39], v[164:167], v[188:191], v[36:39]
	v_mfma_f32_16x16x32_bf16 v[32:35], v[172:175], v[188:191], v[32:35]
	v_mfma_f32_16x16x32_bf16 v[20:23], v[164:167], v[196:199], v[20:23]
	v_mfma_f32_16x16x32_bf16 v[16:19], v[172:175], v[196:199], v[16:19]
	v_mfma_f32_16x16x32_bf16 v[4:7], v[164:167], v[204:207], v[4:7]
	v_mfma_f32_16x16x32_bf16 v[0:3], v[172:175], v[204:207], v[0:3]
	v_mfma_f32_16x16x32_bf16 v[52:55], v[168:171], v[184:187], v[52:55]
	v_mfma_f32_16x16x32_bf16 v[48:51], v[176:179], v[184:187], v[48:51]
	v_mfma_f32_16x16x32_bf16 v[36:39], v[168:171], v[192:195], v[36:39]
	v_mfma_f32_16x16x32_bf16 v[32:35], v[176:179], v[192:195], v[32:35]
	v_mfma_f32_16x16x32_bf16 v[20:23], v[168:171], v[200:203], v[20:23]
	v_mfma_f32_16x16x32_bf16 v[16:19], v[176:179], v[200:203], v[16:19]
	v_mfma_f32_16x16x32_bf16 v[4:7], v[168:171], v[208:211], v[4:7]
	v_mfma_f32_16x16x32_bf16 v[0:3], v[176:179], v[208:211], v[0:3]
	s_barrier
	s_setprio 0
	s_add_i32 s65, 0, 0x18000
	s_add_i32 s66, 0, 0x1c000
	v_add_u32_e32 v160, s65, v145
	ds_read_b128 v[140:143], v160
	ds_read_b128 v[152:155], v160 offset:1024
	ds_read_b128 v[156:159], v160 offset:2048
	ds_read_b128 v[160:163], v160 offset:3072
	v_add_u32_e32 v176, s66, v145
	ds_read_b128 v[164:167], v176
	ds_read_b128 v[168:171], v176 offset:1024
	ds_read_b128 v[172:175], v176 offset:2048
	ds_read_b128 v[176:179], v176 offset:3072
	ds_read_b128 v[180:183], v151 offset:32768
	ds_read_b128 v[184:187], v151 offset:33792
	ds_read_b128 v[188:191], v151 offset:34816
	ds_read_b128 v[192:195], v151 offset:35840
	ds_read_b128 v[196:199], v151 offset:36864
	ds_read_b128 v[200:203], v151 offset:37888
	ds_read_b128 v[204:207], v151 offset:38912
	ds_read_b128 v[208:211], v151 offset:39936
	s_add_u32 s44, s44, 0x200000
	s_addc_u32 s45, s45, 0
	s_mov_b32 m0, s46
	v_lshl_add_u64 v[220:221], s[44:45], 0, v[128:129]
	global_load_lds_dwordx4 v[220:221], off
	v_lshl_add_u64 v[220:221], s[44:45], 0, v[130:131]
	s_mov_b32 m0, s47
	s_nop 0
	global_load_lds_dwordx4 v[220:221], off
	s_waitcnt vmcnt(8)
	s_waitcnt lgkmcnt(0)
	s_barrier
	s_setprio 1
	s_waitcnt lgkmcnt(0)
	v_mfma_f32_16x16x32_bf16 v[124:127], v[140:143], v[180:183], v[124:127]
	v_mfma_f32_16x16x32_bf16 v[120:123], v[156:159], v[180:183], v[120:123]
	v_mfma_f32_16x16x32_bf16 v[108:111], v[140:143], v[188:191], v[108:111]
	v_mfma_f32_16x16x32_bf16 v[104:107], v[156:159], v[188:191], v[104:107]
	v_mfma_f32_16x16x32_bf16 v[92:95], v[140:143], v[196:199], v[92:95]
	v_mfma_f32_16x16x32_bf16 v[88:91], v[156:159], v[196:199], v[88:91]
	v_mfma_f32_16x16x32_bf16 v[76:79], v[140:143], v[204:207], v[76:79]
	v_mfma_f32_16x16x32_bf16 v[72:75], v[156:159], v[204:207], v[72:75]
	v_mfma_f32_16x16x32_bf16 v[124:127], v[152:155], v[184:187], v[124:127]
	v_mfma_f32_16x16x32_bf16 v[120:123], v[160:163], v[184:187], v[120:123]
	v_mfma_f32_16x16x32_bf16 v[108:111], v[152:155], v[192:195], v[108:111]
	v_mfma_f32_16x16x32_bf16 v[104:107], v[160:163], v[192:195], v[104:107]
	v_mfma_f32_16x16x32_bf16 v[92:95], v[152:155], v[200:203], v[92:95]
	v_mfma_f32_16x16x32_bf16 v[88:91], v[160:163], v[200:203], v[88:91]
	v_mfma_f32_16x16x32_bf16 v[76:79], v[152:155], v[208:211], v[76:79]
	v_mfma_f32_16x16x32_bf16 v[72:75], v[160:163], v[208:211], v[72:75]
	v_mfma_f32_16x16x32_bf16 v[116:119], v[164:167], v[180:183], v[116:119]
	v_mfma_f32_16x16x32_bf16 v[112:115], v[172:175], v[180:183], v[112:115]
	v_mfma_f32_16x16x32_bf16 v[100:103], v[164:167], v[188:191], v[100:103]
	v_mfma_f32_16x16x32_bf16 v[96:99], v[172:175], v[188:191], v[96:99]
	v_mfma_f32_16x16x32_bf16 v[84:87], v[164:167], v[196:199], v[84:87]
	v_mfma_f32_16x16x32_bf16 v[80:83], v[172:175], v[196:199], v[80:83]
	v_mfma_f32_16x16x32_bf16 v[68:71], v[164:167], v[204:207], v[68:71]
	v_mfma_f32_16x16x32_bf16 v[64:67], v[172:175], v[204:207], v[64:67]
	v_mfma_f32_16x16x32_bf16 v[116:119], v[168:171], v[184:187], v[116:119]
	v_mfma_f32_16x16x32_bf16 v[112:115], v[176:179], v[184:187], v[112:115]
	v_mfma_f32_16x16x32_bf16 v[100:103], v[168:171], v[192:195], v[100:103]
	v_mfma_f32_16x16x32_bf16 v[96:99], v[176:179], v[192:195], v[96:99]
	v_mfma_f32_16x16x32_bf16 v[84:87], v[168:171], v[200:203], v[84:87]
	v_mfma_f32_16x16x32_bf16 v[80:83], v[176:179], v[200:203], v[80:83]
	v_mfma_f32_16x16x32_bf16 v[68:71], v[168:171], v[208:211], v[68:71]
	v_mfma_f32_16x16x32_bf16 v[64:67], v[176:179], v[208:211], v[64:67]
	s_barrier
	s_setprio 0
	ds_read_b128 v[180:183], v151 offset:49152
	ds_read_b128 v[184:187], v151 offset:50176
	ds_read_b128 v[188:191], v151 offset:51200
	ds_read_b128 v[192:195], v151 offset:52224
	ds_read_b128 v[196:199], v151 offset:53248
	ds_read_b128 v[200:203], v151 offset:54272
	ds_read_b128 v[204:207], v151 offset:55296
	ds_read_b128 v[208:211], v151 offset:56320
	s_add_i32 s44, s65, s94
	v_lshl_add_u64 v[212:213], v[212:213], 0, s[16:17]
	s_mov_b32 m0, s44
	s_nop 0
	global_load_lds_dwordx4 v[212:213], off
	s_add_i32 m0, s44, 0x2000
	s_add_u32 s42, s42, 0x200080
	v_lshl_add_u64 v[212:213], v[214:215], 0, s[16:17]
	s_addc_u32 s43, s43, 0
	s_add_i32 s44, s66, s94
	global_load_lds_dwordx4 v[212:213], off
	v_lshl_add_u64 v[212:213], s[42:43], 0, v[128:129]
	s_mov_b32 m0, s44
	s_nop 0
	global_load_lds_dwordx4 v[212:213], off
	v_lshl_add_u64 v[212:213], s[42:43], 0, v[130:131]
	s_add_i32 m0, s44, 0x2000
	s_nop 0
	global_load_lds_dwordx4 v[212:213], off
	v_lshl_add_u64 v[212:213], v[216:217], 0, s[16:17]
	s_mov_b32 m0, s48
	s_nop 0
	global_load_lds_dwordx4 v[212:213], off
	v_lshl_add_u64 v[212:213], v[218:219], 0, s[16:17]
	s_mov_b32 m0, s49
	s_nop 0
	global_load_lds_dwordx4 v[212:213], off
	s_waitcnt vmcnt(8)
	s_waitcnt lgkmcnt(0)
	s_barrier
	s_setprio 1
	s_waitcnt lgkmcnt(0)
	v_mfma_f32_16x16x32_bf16 v[60:63], v[140:143], v[180:183], v[60:63]
	v_mfma_f32_16x16x32_bf16 v[56:59], v[156:159], v[180:183], v[56:59]
	v_mfma_f32_16x16x32_bf16 v[44:47], v[140:143], v[188:191], v[44:47]
	v_mfma_f32_16x16x32_bf16 v[40:43], v[156:159], v[188:191], v[40:43]
	v_mfma_f32_16x16x32_bf16 v[28:31], v[140:143], v[196:199], v[28:31]
	v_mfma_f32_16x16x32_bf16 v[24:27], v[156:159], v[196:199], v[24:27]
	v_mfma_f32_16x16x32_bf16 v[12:15], v[140:143], v[204:207], v[12:15]
	v_mfma_f32_16x16x32_bf16 v[8:11], v[156:159], v[204:207], v[8:11]
	v_mfma_f32_16x16x32_bf16 v[60:63], v[152:155], v[184:187], v[60:63]
	v_mfma_f32_16x16x32_bf16 v[56:59], v[160:163], v[184:187], v[56:59]
	v_mfma_f32_16x16x32_bf16 v[44:47], v[152:155], v[192:195], v[44:47]
	v_mfma_f32_16x16x32_bf16 v[40:43], v[160:163], v[192:195], v[40:43]
	v_mfma_f32_16x16x32_bf16 v[28:31], v[152:155], v[200:203], v[28:31]
	v_mfma_f32_16x16x32_bf16 v[24:27], v[160:163], v[200:203], v[24:27]
	v_mfma_f32_16x16x32_bf16 v[12:15], v[152:155], v[208:211], v[12:15]
	v_mfma_f32_16x16x32_bf16 v[8:11], v[160:163], v[208:211], v[8:11]
	v_mfma_f32_16x16x32_bf16 v[52:55], v[164:167], v[180:183], v[52:55]
	v_mfma_f32_16x16x32_bf16 v[48:51], v[172:175], v[180:183], v[48:51]
	v_mfma_f32_16x16x32_bf16 v[36:39], v[164:167], v[188:191], v[36:39]
	v_mfma_f32_16x16x32_bf16 v[32:35], v[172:175], v[188:191], v[32:35]
	v_mfma_f32_16x16x32_bf16 v[20:23], v[164:167], v[196:199], v[20:23]
	v_mfma_f32_16x16x32_bf16 v[16:19], v[172:175], v[196:199], v[16:19]
	v_mfma_f32_16x16x32_bf16 v[4:7], v[164:167], v[204:207], v[4:7]
	v_mfma_f32_16x16x32_bf16 v[0:3], v[172:175], v[204:207], v[0:3]
	v_mfma_f32_16x16x32_bf16 v[52:55], v[168:171], v[184:187], v[52:55]
	v_mfma_f32_16x16x32_bf16 v[48:51], v[176:179], v[184:187], v[48:51]
	v_mfma_f32_16x16x32_bf16 v[36:39], v[168:171], v[192:195], v[36:39]
	v_mfma_f32_16x16x32_bf16 v[32:35], v[176:179], v[192:195], v[32:35]
	v_mfma_f32_16x16x32_bf16 v[20:23], v[168:171], v[200:203], v[20:23]
	v_mfma_f32_16x16x32_bf16 v[16:19], v[176:179], v[200:203], v[16:19]
	v_mfma_f32_16x16x32_bf16 v[4:7], v[168:171], v[208:211], v[4:7]
	v_mfma_f32_16x16x32_bf16 v[0:3], v[176:179], v[208:211], v[0:3]
	s_barrier
	s_setprio 0
	s_add_i32 s64, s64, 2
	s_add_u32 s40, s40, 0x100
	s_addc_u32 s41, s41, 0
	s_add_u32 s62, s62, 0x100
	s_addc_u32 s63, s63, 0
	s_cmpk_gt_u32 s64, 0x7d
	s_cbranch_scc0 .LBB0_2917
	s_and_b64 vcc, exec, s[58:59]
	s_cbranch_vccz .LBB0_2920
	s_barrier
